# GEMM K-loops: LDS-DMA issued in saddr form (scalar base + 32-bit lane offset), dropping the per-piece 64-bit VALU address adds
# speedup vs baseline: 1.0052x; 1.0052x over previous
.LBB0_218:
	s_add_u32 s4, s39, 0x4800000
	s_mov_b64 s[10:11], 0x80
	s_addc_u32 s5, s40, 0
	s_add_i32 m0, s29, 0x18000
	v_lshl_add_u64 v[4:5], v[4:5], 0, s[10:11]
	s_waitcnt vmcnt(2)
	s_barrier
	global_load_lds_dwordx4 v[4:5], off
	v_lshl_add_u64 v[2:3], v[2:3], 0, s[10:11]
	s_add_i32 m0, s29, 0x1a000
	s_add_i32 s48, s29, 0x8000
	s_add_i32 s49, s29, 0xa000
	global_load_lds_dwordx4 v[2:3], off
	v_lshl_add_u64 v[0:1], v[0:1], 0, s[10:11]
	s_mov_b32 m0, s48
	s_add_u32 s12, s30, 0x40080
	global_load_lds_dwordx4 v[0:1], off
	v_lshl_add_u64 v[0:1], v[6:7], 0, s[10:11]
	s_mov_b32 m0, s49
	s_addc_u32 s13, s31, 0
	global_load_lds_dwordx4 v[0:1], off
	s_add_i32 m0, s29, 0x1c000
	s_nop 0
	global_load_lds_dwordx4 v132, s[12:13]
	v_lshl_add_u64 v[0:1], s[12:13], 0, v[128:129]
	s_add_i32 m0, s29, 0x1e000
	s_sext_i32_i8 s57, s6
	global_load_lds_dwordx4 v[0:1], off
	v_and_b32_e32 v0, 15, v10
	v_readlane_b32 s6, v247, 6
	v_and_b32_e32 v4, 48, v10
	v_lshrrev_b32_e32 v2, 6, v10
	v_or_b32_e32 v148, s6, v0
	v_lshlrev_b32_e32 v3, 6, v148
	s_movk_i32 s6, 0x3c0
	v_and_or_b32 v3, v3, s6, v4
	v_readlane_b32 s6, v247, 8
	v_lshl_or_b32 v0, v0, 6, v4
	v_lshlrev_b32_e32 v4, 2, v10
	v_lshl_add_u32 v5, v2, 10, s6
	v_readlane_b32 s6, v247, 10
	v_and_b32_e32 v4, 32, v4
	v_lshrrev_b32_e32 v1, 1, v10
	v_add_lshl_u32 v2, v2, s6, 10
	v_bitop3_b32 v149, v0, v2, v4 bitop3:0xde
	v_lshlrev_b32_e32 v0, 14, v8
	v_and_b32_e32 v1, 56, v1
	v_readlane_b32 s6, v247, 9
	v_and_b32_e32 v0, 0xffff8000, v0
	v_lshl_add_u32 v0, v9, 11, v0
	v_add_u32_e32 v150, s6, v1
	v_and_b32_e32 v1, 1, v8
	v_lshl_or_b32 v0, v1, 6, v0
	v_lshl_add_u32 v136, v11, 1, v0
	v_lshlrev_b32_e32 v0, 14, v12
	v_lshlrev_b32_e32 v6, 2, v148
	v_and_b32_e32 v0, 0xffff8000, v0
	v_and_b32_e32 v6, 32, v6
	s_waitcnt vmcnt(6)
	s_cmpk_lt_u32 s75, 0x100
	v_lshl_add_u32 v0, v13, 11, v0
	v_and_b32_e32 v1, 1, v12
	v_bitop3_b32 v3, v3, v5, v6 bitop3:0xde
	s_cselect_b64 s[12:13], -1, 0
	v_lshl_or_b32 v0, v1, 6, v0
	s_add_i32 s54, 0, 0x10000
	s_add_i32 s55, 0, 0x14000
	s_mov_b32 s51, 0
	s_ashr_i32 s52, s76, 31
	s_mov_b32 s53, s76
	v_mov_b32_e32 v137, v133
	v_lshl_add_u32 v138, v14, 1, v0
	v_mov_b32_e32 v139, v133
	v_mov_b64_e32 v[140:141], 0x380
	v_mov_b64_e32 v[142:143], 0x37f
	v_add_u32_e32 v151, s54, v149
	v_add_u32_e32 v152, s55, v149
	v_add_u32_e32 v153, 0, v3
	s_movk_i32 s56, 0x1c00
	s_barrier
	s_branch .LBB0_221

.LBB0_224:
	ds_read_b128 v[144:147], v151
	ds_read_b128 v[154:157], v151 offset:1024
	ds_read_b128 v[158:161], v151 offset:2048
	ds_read_b128 v[162:165], v151 offset:3072
	ds_read_b128 v[166:169], v152
	ds_read_b128 v[170:173], v152 offset:1024
	ds_read_b128 v[174:177], v152 offset:2048
	ds_read_b128 v[178:181], v152 offset:3072
	s_add_u32 s34, s30, 0xfffc0080
	s_addc_u32 s35, s31, -1
	s_cmp_eq_u32 s62, 12
	s_cselect_b32 s37, s15, s35
	s_cselect_b32 s36, s17, s34
	s_cselect_b32 s35, s58, s61
	s_cselect_b32 s34, s59, s60
	s_add_i32 m0, s29, 0xc000
	ds_read_b128 v[182:185], v153
	ds_read_b128 v[186:189], v153 offset:1024
	ds_read_b128 v[190:193], v153 offset:2048
	ds_read_b128 v[194:197], v153 offset:3072
	ds_read_b128 v[198:201], v153 offset:4096
	ds_read_b128 v[202:205], v153 offset:5120
	ds_read_b128 v[206:209], v153 offset:6144
	ds_read_b128 v[210:213], v153 offset:7168
	global_load_lds_dwordx4 v138, s[30:31]
	s_add_i32 m0, s29, 0xe000
	s_nop 0
	global_load_lds_dwordx4 v136, s[30:31]
	s_waitcnt vmcnt(8)
	s_waitcnt lgkmcnt(0)
	s_barrier
	s_setprio 1
	s_waitcnt lgkmcnt(0)
	v_mfma_f32_16x16x32_bf16 v[124:127], v[144:147], v[182:185], v[124:127]
	v_mfma_f32_16x16x32_bf16 v[120:123], v[158:161], v[182:185], v[120:123]
	v_mfma_f32_16x16x32_bf16 v[116:119], v[144:147], v[190:193], v[116:119]
	v_mfma_f32_16x16x32_bf16 v[108:111], v[158:161], v[190:193], v[108:111]
	v_mfma_f32_16x16x32_bf16 v[100:103], v[144:147], v[198:201], v[100:103]
	v_mfma_f32_16x16x32_bf16 v[92:95], v[158:161], v[198:201], v[92:95]
	v_mfma_f32_16x16x32_bf16 v[84:87], v[144:147], v[206:209], v[84:87]
	v_mfma_f32_16x16x32_bf16 v[76:79], v[158:161], v[206:209], v[76:79]
	v_mfma_f32_16x16x32_bf16 v[124:127], v[154:157], v[186:189], v[124:127]
	v_mfma_f32_16x16x32_bf16 v[120:123], v[162:165], v[186:189], v[120:123]
	v_mfma_f32_16x16x32_bf16 v[116:119], v[154:157], v[194:197], v[116:119]
	v_mfma_f32_16x16x32_bf16 v[108:111], v[162:165], v[194:197], v[108:111]
	v_mfma_f32_16x16x32_bf16 v[100:103], v[154:157], v[202:205], v[100:103]
	v_mfma_f32_16x16x32_bf16 v[92:95], v[162:165], v[202:205], v[92:95]
	v_mfma_f32_16x16x32_bf16 v[84:87], v[154:157], v[210:213], v[84:87]
	v_mfma_f32_16x16x32_bf16 v[76:79], v[162:165], v[210:213], v[76:79]
	s_setprio 0
	s_setprio 1
	v_mfma_f32_16x16x32_bf16 v[112:115], v[166:169], v[182:185], v[112:115]
	v_mfma_f32_16x16x32_bf16 v[104:107], v[174:177], v[182:185], v[104:107]
	v_mfma_f32_16x16x32_bf16 v[96:99], v[166:169], v[190:193], v[96:99]
	v_mfma_f32_16x16x32_bf16 v[88:91], v[174:177], v[190:193], v[88:91]
	v_mfma_f32_16x16x32_bf16 v[80:83], v[166:169], v[198:201], v[80:83]
	v_mfma_f32_16x16x32_bf16 v[72:75], v[174:177], v[198:201], v[72:75]
	v_mfma_f32_16x16x32_bf16 v[68:71], v[166:169], v[206:209], v[68:71]
	v_mfma_f32_16x16x32_bf16 v[64:67], v[174:177], v[206:209], v[64:67]
	v_mfma_f32_16x16x32_bf16 v[112:115], v[170:173], v[186:189], v[112:115]
	v_mfma_f32_16x16x32_bf16 v[104:107], v[178:181], v[186:189], v[104:107]
	v_mfma_f32_16x16x32_bf16 v[96:99], v[170:173], v[194:197], v[96:99]
	v_mfma_f32_16x16x32_bf16 v[88:91], v[178:181], v[194:197], v[88:91]
	v_mfma_f32_16x16x32_bf16 v[80:83], v[170:173], v[202:205], v[80:83]
	v_mfma_f32_16x16x32_bf16 v[72:75], v[178:181], v[202:205], v[72:75]
	v_mfma_f32_16x16x32_bf16 v[68:71], v[170:173], v[210:213], v[68:71]
	v_mfma_f32_16x16x32_bf16 v[64:67], v[178:181], v[210:213], v[64:67]
	s_setprio 0
	s_barrier
	s_add_i32 s63, s54, s66
	v_lshl_add_u64 v[214:215], s[34:35], 0, v[132:133]
	s_mov_b32 m0, s63
	ds_read_b128 v[182:185], v153 offset:16384
	ds_read_b128 v[186:189], v153 offset:17408
	ds_read_b128 v[190:193], v153 offset:18432
	ds_read_b128 v[194:197], v153 offset:19456
	ds_read_b128 v[198:201], v153 offset:20480
	ds_read_b128 v[202:205], v153 offset:21504
	ds_read_b128 v[206:209], v153 offset:22528
	ds_read_b128 v[210:213], v153 offset:23552
	global_load_lds_dwordx4 v[214:215], off
	s_add_i32 m0, s63, 0x2000
	s_add_u32 s64, s34, 0x40000
	v_lshl_add_u64 v[216:217], s[34:35], 0, v[128:129]
	s_addc_u32 s65, s35, 0
	s_add_i32 s63, s55, s66
	global_load_lds_dwordx4 v[216:217], off
	s_mov_b32 m0, s63
	v_lshl_add_u64 v[220:221], s[36:37], 0, v[130:131]
	global_load_lds_dwordx4 v132, s[64:65]
	s_add_i32 m0, s63, 0x2000
	s_nop 0
	global_load_lds_dwordx4 v128, s[64:65]
	v_lshl_add_u64 v[218:219], s[36:37], 0, v[134:135]
	s_mov_b32 m0, s29
	s_nop 0
	global_load_lds_dwordx4 v[218:219], off
	s_mov_b32 m0, s45
	s_nop 0
	global_load_lds_dwordx4 v[220:221], off
	s_waitcnt vmcnt(8)
	s_waitcnt lgkmcnt(0)
	s_barrier
	s_setprio 1
	s_waitcnt lgkmcnt(0)
	v_mfma_f32_16x16x32_bf16 v[60:63], v[144:147], v[182:185], v[60:63]
	v_mfma_f32_16x16x32_bf16 v[56:59], v[158:161], v[182:185], v[56:59]
	v_mfma_f32_16x16x32_bf16 v[52:55], v[144:147], v[190:193], v[52:55]
	v_mfma_f32_16x16x32_bf16 v[44:47], v[158:161], v[190:193], v[44:47]
	v_mfma_f32_16x16x32_bf16 v[36:39], v[144:147], v[198:201], v[36:39]
	v_mfma_f32_16x16x32_bf16 v[28:31], v[158:161], v[198:201], v[28:31]
	v_mfma_f32_16x16x32_bf16 v[20:23], v[144:147], v[206:209], v[20:23]
	v_mfma_f32_16x16x32_bf16 v[12:15], v[158:161], v[206:209], v[12:15]
	v_mfma_f32_16x16x32_bf16 v[60:63], v[154:157], v[186:189], v[60:63]
	v_mfma_f32_16x16x32_bf16 v[56:59], v[162:165], v[186:189], v[56:59]
	v_mfma_f32_16x16x32_bf16 v[52:55], v[154:157], v[194:197], v[52:55]
	v_mfma_f32_16x16x32_bf16 v[44:47], v[162:165], v[194:197], v[44:47]
	v_mfma_f32_16x16x32_bf16 v[36:39], v[154:157], v[202:205], v[36:39]
	v_mfma_f32_16x16x32_bf16 v[28:31], v[162:165], v[202:205], v[28:31]
	v_mfma_f32_16x16x32_bf16 v[20:23], v[154:157], v[210:213], v[20:23]
	v_mfma_f32_16x16x32_bf16 v[12:15], v[162:165], v[210:213], v[12:15]
	s_setprio 0
	s_setprio 1
	v_mfma_f32_16x16x32_bf16 v[48:51], v[166:169], v[182:185], v[48:51]
	v_mfma_f32_16x16x32_bf16 v[40:43], v[174:177], v[182:185], v[40:43]
	v_mfma_f32_16x16x32_bf16 v[32:35], v[166:169], v[190:193], v[32:35]
	v_mfma_f32_16x16x32_bf16 v[24:27], v[174:177], v[190:193], v[24:27]
	v_mfma_f32_16x16x32_bf16 v[16:19], v[166:169], v[198:201], v[16:19]
	v_mfma_f32_16x16x32_bf16 v[8:11], v[174:177], v[198:201], v[8:11]
	v_mfma_f32_16x16x32_bf16 v[4:7], v[166:169], v[206:209], v[4:7]
	v_mfma_f32_16x16x32_bf16 v[0:3], v[174:177], v[206:209], v[0:3]
	v_mfma_f32_16x16x32_bf16 v[48:51], v[170:173], v[186:189], v[48:51]
	v_mfma_f32_16x16x32_bf16 v[40:43], v[178:181], v[186:189], v[40:43]
	v_mfma_f32_16x16x32_bf16 v[32:35], v[170:173], v[194:197], v[32:35]
	v_mfma_f32_16x16x32_bf16 v[24:27], v[178:181], v[194:197], v[24:27]
	v_mfma_f32_16x16x32_bf16 v[16:19], v[170:173], v[202:205], v[16:19]
	v_mfma_f32_16x16x32_bf16 v[8:11], v[178:181], v[202:205], v[8:11]
	v_mfma_f32_16x16x32_bf16 v[4:7], v[170:173], v[210:213], v[4:7]
	v_mfma_f32_16x16x32_bf16 v[0:3], v[178:181], v[210:213], v[0:3]
	s_setprio 0
	s_barrier
	s_add_i32 s63, 0, 0x18000
	s_add_i32 s64, 0, 0x1c000
	v_add_u32_e32 v162, s63, v149
	v_add_u32_e32 v178, s64, v149
	ds_read_b128 v[144:147], v162
	ds_read_b128 v[154:157], v162 offset:1024
	ds_read_b128 v[158:161], v162 offset:2048
	ds_read_b128 v[162:165], v162 offset:3072
	ds_read_b128 v[166:169], v178
	ds_read_b128 v[170:173], v178 offset:1024
	ds_read_b128 v[174:177], v178 offset:2048
	ds_read_b128 v[178:181], v178 offset:3072
	s_add_u32 s36, s36, 0x40000
	s_addc_u32 s37, s37, 0
	s_mov_b32 m0, s46
	ds_read_b128 v[182:185], v153 offset:32768
	ds_read_b128 v[186:189], v153 offset:33792
	ds_read_b128 v[190:193], v153 offset:34816
	ds_read_b128 v[194:197], v153 offset:35840
	ds_read_b128 v[198:201], v153 offset:36864
	ds_read_b128 v[202:205], v153 offset:37888
	ds_read_b128 v[206:209], v153 offset:38912
	ds_read_b128 v[210:213], v153 offset:39936
	global_load_lds_dwordx4 v134, s[36:37]
	s_mov_b32 m0, s47
	s_nop 0
	global_load_lds_dwordx4 v130, s[36:37]
	s_waitcnt vmcnt(8)
	s_waitcnt lgkmcnt(0)
	s_barrier
	s_setprio 1
	s_waitcnt lgkmcnt(0)
	v_mfma_f32_16x16x32_bf16 v[124:127], v[144:147], v[182:185], v[124:127]
	v_mfma_f32_16x16x32_bf16 v[120:123], v[158:161], v[182:185], v[120:123]
	v_mfma_f32_16x16x32_bf16 v[116:119], v[144:147], v[190:193], v[116:119]
	v_mfma_f32_16x16x32_bf16 v[108:111], v[158:161], v[190:193], v[108:111]
	v_mfma_f32_16x16x32_bf16 v[100:103], v[144:147], v[198:201], v[100:103]
	v_mfma_f32_16x16x32_bf16 v[92:95], v[158:161], v[198:201], v[92:95]
	v_mfma_f32_16x16x32_bf16 v[84:87], v[144:147], v[206:209], v[84:87]
	v_mfma_f32_16x16x32_bf16 v[76:79], v[158:161], v[206:209], v[76:79]
	v_mfma_f32_16x16x32_bf16 v[124:127], v[154:157], v[186:189], v[124:127]
	v_mfma_f32_16x16x32_bf16 v[120:123], v[162:165], v[186:189], v[120:123]
	v_mfma_f32_16x16x32_bf16 v[116:119], v[154:157], v[194:197], v[116:119]
	v_mfma_f32_16x16x32_bf16 v[108:111], v[162:165], v[194:197], v[108:111]
	v_mfma_f32_16x16x32_bf16 v[100:103], v[154:157], v[202:205], v[100:103]
	v_mfma_f32_16x16x32_bf16 v[92:95], v[162:165], v[202:205], v[92:95]
	v_mfma_f32_16x16x32_bf16 v[84:87], v[154:157], v[210:213], v[84:87]
	v_mfma_f32_16x16x32_bf16 v[76:79], v[162:165], v[210:213], v[76:79]
	s_setprio 0
	s_setprio 1
	v_mfma_f32_16x16x32_bf16 v[112:115], v[166:169], v[182:185], v[112:115]
	v_mfma_f32_16x16x32_bf16 v[104:107], v[174:177], v[182:185], v[104:107]
	v_mfma_f32_16x16x32_bf16 v[96:99], v[166:169], v[190:193], v[96:99]
	v_mfma_f32_16x16x32_bf16 v[88:91], v[174:177], v[190:193], v[88:91]
	v_mfma_f32_16x16x32_bf16 v[80:83], v[166:169], v[198:201], v[80:83]
	v_mfma_f32_16x16x32_bf16 v[72:75], v[174:177], v[198:201], v[72:75]
	v_mfma_f32_16x16x32_bf16 v[68:71], v[166:169], v[206:209], v[68:71]
	v_mfma_f32_16x16x32_bf16 v[64:67], v[174:177], v[206:209], v[64:67]
	v_mfma_f32_16x16x32_bf16 v[112:115], v[170:173], v[186:189], v[112:115]
	v_mfma_f32_16x16x32_bf16 v[104:107], v[178:181], v[186:189], v[104:107]
	v_mfma_f32_16x16x32_bf16 v[96:99], v[170:173], v[194:197], v[96:99]
	v_mfma_f32_16x16x32_bf16 v[88:91], v[178:181], v[194:197], v[88:91]
	v_mfma_f32_16x16x32_bf16 v[80:83], v[170:173], v[202:205], v[80:83]
	v_mfma_f32_16x16x32_bf16 v[72:75], v[178:181], v[202:205], v[72:75]
	v_mfma_f32_16x16x32_bf16 v[68:71], v[170:173], v[210:213], v[68:71]
	v_mfma_f32_16x16x32_bf16 v[64:67], v[178:181], v[210:213], v[64:67]
	s_setprio 0
	s_barrier
	s_add_i32 s36, s63, s66
	v_lshl_add_u64 v[214:215], v[214:215], 0, s[10:11]
	s_mov_b32 m0, s36
	ds_read_b128 v[182:185], v153 offset:49152
	ds_read_b128 v[186:189], v153 offset:50176
	ds_read_b128 v[190:193], v153 offset:51200
	ds_read_b128 v[194:197], v153 offset:52224
	ds_read_b128 v[198:201], v153 offset:53248
	ds_read_b128 v[202:205], v153 offset:54272
	ds_read_b128 v[206:209], v153 offset:55296
	ds_read_b128 v[210:213], v153 offset:56320
	global_load_lds_dwordx4 v[214:215], off
	s_add_i32 m0, s36, 0x2000
	s_add_u32 s34, s34, 0x40080
	v_lshl_add_u64 v[214:215], v[216:217], 0, s[10:11]
	s_addc_u32 s35, s35, 0
	s_add_i32 s36, s64, s66
	global_load_lds_dwordx4 v[214:215], off
	s_mov_b32 m0, s36
	s_nop 0
	global_load_lds_dwordx4 v132, s[34:35]
	s_add_i32 m0, s36, 0x2000
	s_nop 0
	global_load_lds_dwordx4 v128, s[34:35]
	v_lshl_add_u64 v[214:215], v[218:219], 0, s[10:11]
	s_mov_b32 m0, s48
	s_nop 0
	global_load_lds_dwordx4 v[214:215], off
	v_lshl_add_u64 v[214:215], v[220:221], 0, s[10:11]
	s_mov_b32 m0, s49
	s_nop 0
	global_load_lds_dwordx4 v[214:215], off
	s_waitcnt vmcnt(8)
	s_waitcnt lgkmcnt(0)
	s_barrier
	s_setprio 1
	s_waitcnt lgkmcnt(0)
	v_mfma_f32_16x16x32_bf16 v[60:63], v[144:147], v[182:185], v[60:63]
	v_mfma_f32_16x16x32_bf16 v[56:59], v[158:161], v[182:185], v[56:59]
	v_mfma_f32_16x16x32_bf16 v[52:55], v[144:147], v[190:193], v[52:55]
	v_mfma_f32_16x16x32_bf16 v[44:47], v[158:161], v[190:193], v[44:47]
	v_mfma_f32_16x16x32_bf16 v[36:39], v[144:147], v[198:201], v[36:39]
	v_mfma_f32_16x16x32_bf16 v[28:31], v[158:161], v[198:201], v[28:31]
	v_mfma_f32_16x16x32_bf16 v[20:23], v[144:147], v[206:209], v[20:23]
	v_mfma_f32_16x16x32_bf16 v[12:15], v[158:161], v[206:209], v[12:15]
	v_mfma_f32_16x16x32_bf16 v[60:63], v[154:157], v[186:189], v[60:63]
	v_mfma_f32_16x16x32_bf16 v[56:59], v[162:165], v[186:189], v[56:59]
	v_mfma_f32_16x16x32_bf16 v[52:55], v[154:157], v[194:197], v[52:55]
	v_mfma_f32_16x16x32_bf16 v[44:47], v[162:165], v[194:197], v[44:47]
	v_mfma_f32_16x16x32_bf16 v[36:39], v[154:157], v[202:205], v[36:39]
	v_mfma_f32_16x16x32_bf16 v[28:31], v[162:165], v[202:205], v[28:31]
	v_mfma_f32_16x16x32_bf16 v[20:23], v[154:157], v[210:213], v[20:23]
	v_mfma_f32_16x16x32_bf16 v[12:15], v[162:165], v[210:213], v[12:15]
	s_setprio 0
	s_setprio 1
	v_mfma_f32_16x16x32_bf16 v[48:51], v[166:169], v[182:185], v[48:51]
	v_mfma_f32_16x16x32_bf16 v[40:43], v[174:177], v[182:185], v[40:43]
	v_mfma_f32_16x16x32_bf16 v[32:35], v[166:169], v[190:193], v[32:35]
	v_mfma_f32_16x16x32_bf16 v[24:27], v[174:177], v[190:193], v[24:27]
	v_mfma_f32_16x16x32_bf16 v[16:19], v[166:169], v[198:201], v[16:19]
	v_mfma_f32_16x16x32_bf16 v[8:11], v[174:177], v[198:201], v[8:11]
	v_mfma_f32_16x16x32_bf16 v[4:7], v[166:169], v[206:209], v[4:7]
	v_mfma_f32_16x16x32_bf16 v[0:3], v[174:177], v[206:209], v[0:3]
	v_mfma_f32_16x16x32_bf16 v[48:51], v[170:173], v[186:189], v[48:51]
	v_mfma_f32_16x16x32_bf16 v[40:43], v[178:181], v[186:189], v[40:43]
	v_mfma_f32_16x16x32_bf16 v[32:35], v[170:173], v[194:197], v[32:35]
	v_mfma_f32_16x16x32_bf16 v[24:27], v[178:181], v[194:197], v[24:27]
	v_mfma_f32_16x16x32_bf16 v[16:19], v[170:173], v[202:205], v[16:19]
	v_mfma_f32_16x16x32_bf16 v[8:11], v[178:181], v[202:205], v[8:11]
	v_mfma_f32_16x16x32_bf16 v[4:7], v[170:173], v[210:213], v[4:7]
	v_mfma_f32_16x16x32_bf16 v[0:3], v[178:181], v[210:213], v[0:3]
	s_setprio 0
	s_barrier
	s_add_i32 s62, s62, 2
	s_add_u32 s60, s60, 0x100
	s_addc_u32 s61, s61, 0
	s_add_u32 s30, s30, 0x100
	s_addc_u32 s31, s31, 0
	s_cmp_gt_u32 s62, 13
	s_cbranch_scc0 .LBB0_224
	s_and_b64 vcc, exec, s[12:13]
	s_cbranch_vccz .LBB0_227
	s_barrier

.LBB0_275:
	s_or_b64 exec, exec, s[2:3]
	s_add_i32 s3, 0, 0x23fa8
	s_mov_b32 s2, -1
	v_mov_b32_e32 v0, s3
	s_barrier
	ds_read_b64 v[0:1], v0
	v_mbcnt_lo_u32_b32 v4, s2, 0
	v_mbcnt_hi_u32_b32 v4, s2, v4
	s_waitcnt lgkmcnt(0)
	v_readfirstlane_b32 s11, v0
	v_readfirstlane_b32 s20, v1
	s_add_u32 s21, s11, 0x4800000
	s_addc_u32 s24, s20, 0
	s_add_i32 s3, 0, 0x23f10
	v_mov_b32_e32 v0, s3
	s_add_i32 s3, 0, 0x23f48
	ds_read_b64 v[6:7], v0
	v_mov_b32_e32 v0, s3
	ds_read2_b64 v[0:3], v0 offset1:1
	s_andn2_b64 vcc, exec, s[0:1]
	s_waitcnt lgkmcnt(1)
	v_readfirstlane_b32 s25, v6
	v_readfirstlane_b32 s26, v7
	s_waitcnt lgkmcnt(0)
	v_readfirstlane_b32 s2, v0
	v_cndmask_b32_e64 v0, 0, 1, s[0:1]
	v_cmp_ne_u32_e64 s[6:7], 1, v0
	v_readfirstlane_b32 s3, v1
	v_mov_b32_e32 v1, 0
	v_readfirstlane_b32 s4, v2
	v_readfirstlane_b32 s5, v3
	v_writelane_b32 v247, s6, 12
	v_lshlrev_b32_e32 v0, 1, v4
	s_nop 0
	v_writelane_b32 v247, s7, 13
	s_cbranch_vccnz .LBB0_278
	s_cmpk_lg_i32 s76, 0x100
	s_cbranch_scc1 .Lnsp_generic
	s_mul_i32 s16, s84, 0x1c00
	s_add_u32 s0, s11, s16
	s_addc_u32 s1, s20, 0
	s_add_u32 s0, s0, 0x4801000
	s_addc_u32 s1, s1, 0
	s_lshl_b32 s16, s84, 7
	s_add_u32 s12, s11, s16
	s_addc_u32 s13, s20, 0
	s_add_u32 s6, s12, 0xb800000
	s_addc_u32 s7, s13, 0
	s_lshl_b32 s16, s84, 2
	s_add_u32 s14, s25, s16
	s_addc_u32 s15, s26, 0
	s_mov_b32 s10, 0x3c800000
	v_and_b32_e32 v9, 7, v4
	v_lshlrev_b32_e32 v5, 4, v4
	v_lshrrev_b32_e32 v13, 3, v4
	v_lshlrev_b32_e32 v7, 18, v13
	v_lshl_add_u32 v7, v9, 4, v7
	v_lshlrev_b32_e32 v14, 13, v13
	global_load_dword v11, v14, s[14:15]
	v_lshlrev_b32_e32 v14, 5, v9
	global_load_dwordx4 v[16:19], v14, s[2:3]
	global_load_dwordx4 v[20:23], v14, s[2:3] offset:16
	v_lshrrev_b32_e32 v8, 4, v4
	v_add_u32_e32 v10, -1, v8
	v_max_i32_e32 v10, 0, v10
	v_lshl_add_u32 v10, v10, 8, v14
	global_load_dwordx4 v[24:27], v10, s[4:5]
	global_load_dwordx4 v[28:31], v10, s[4:5] offset:16
	v_cmp_lt_u32_e64 s[16:17], 47, v4
	v_add_u32_e32 v6, 0x400, v5
	v_add_u32_e32 v14, 0x500, v5
	s_nop 0
	v_cndmask_b32_e64 v6, v6, v14, s[16:17]
	global_load_dwordx4 v[48:51], v5, s[0:1]
	global_load_dwordx4 v[52:55], v6, s[0:1]
	s_add_u32 s0, s0, 0xe00000
	s_addc_u32 s1, s1, 0
	global_load_dwordx4 v[56:59], v5, s[0:1]
	global_load_dwordx4 v[60:63], v6, s[0:1]
	s_add_u32 s0, s0, 0xe00000
	s_addc_u32 s1, s1, 0
	global_load_dwordx4 v[64:67], v5, s[0:1]
	global_load_dwordx4 v[68:71], v6, s[0:1]
	s_add_u32 s0, s0, 0xe00000
	s_addc_u32 s1, s1, 0
	global_load_dwordx4 v[72:75], v5, s[0:1]
	global_load_dwordx4 v[76:79], v6, s[0:1]
	s_add_u32 s0, s0, 0xe00000
	s_addc_u32 s1, s1, 0
	global_load_dwordx4 v[80:83], v5, s[0:1]
	global_load_dwordx4 v[84:87], v6, s[0:1]
	s_add_u32 s0, s0, 0xe00000
	s_addc_u32 s1, s1, 0
	global_load_dwordx4 v[88:91], v5, s[0:1]
	global_load_dwordx4 v[92:95], v6, s[0:1]
	s_add_u32 s0, s0, 0xe00000
	s_addc_u32 s1, s1, 0
	global_load_dwordx4 v[96:99], v5, s[0:1]
	global_load_dwordx4 v[100:103], v6, s[0:1]
	s_add_u32 s0, s0, 0xe00000
	s_addc_u32 s1, s1, 0
	global_load_dwordx4 v[104:107], v5, s[0:1]
	global_load_dwordx4 v[108:111], v6, s[0:1]
	s_add_u32 s0, s0, 0xe00000
	s_addc_u32 s1, s1, 0
	v_cmp_eq_u32_e64 s[16:17], 3, v8
	v_mul_u32_u24_e32 v14, 5, v8
	v_add_u32_e32 v14, 0xc8, v14
	v_cndmask_b32_e64 v10, 0, 5, s[16:17]
	v_add_u32_e32 v14, v14, v10
	v_lshlrev_b32_e32 v14, 20, v14
	v_and_b32_e32 v13, 1, v13
	v_lshl_add_u32 v14, v13, 18, v14
	v_cmp_eq_u32_e64 s[18:19], 1, v8
	v_lshl_add_u32 v8, v9, 4, v14
	v_cmp_eq_u32_e64 s[16:17], 0, v9
	v_mov_b32_e32 v10, 0
	v_mov_b32_e32 v15, 0x358637bd
	v_cndmask_b32_e64 v10, v10, -1.0, s[16:17]
	v_cmp_eq_u32_e64 s[16:17], 1, v9
	s_nop 1
	v_cndmask_b32_e64 v10, v10, 1.0, s[16:17]
	v_mov_b32_e32 v13, 1.0
	v_cmp_eq_u32_e32 vcc, 1, v9
	v_mov_b32_e32 v14, 0x3e4693af
	s_nop 0
	v_cndmask_b32_e32 v13, v13, v14, vcc
	v_cmp_eq_u32_e32 vcc, 2, v9
	v_mov_b32_e32 v14, 0x3d1a08c8
	s_nop 0
	v_cndmask_b32_e32 v13, v13, v14, vcc
	v_cmp_eq_u32_e32 vcc, 3, v9
	v_mov_b32_e32 v14, 0x3beef74e
	s_nop 0
	v_cndmask_b32_e32 v13, v13, v14, vcc
	v_cmp_eq_u32_e32 vcc, 4, v9
	v_mov_b32_e32 v14, 0x3ab95d22
	s_nop 0
	v_cndmask_b32_e32 v13, v13, v14, vcc
	v_cmp_eq_u32_e32 vcc, 5, v9
	v_mov_b32_e32 v14, 0x398fc8f8
	s_nop 0
	v_cndmask_b32_e32 v13, v13, v14, vcc
	v_cmp_eq_u32_e32 vcc, 6, v9
	v_mov_b32_e32 v14, 0x385f10c4
	s_nop 0
	v_cndmask_b32_e32 v13, v13, v14, vcc
	v_cmp_eq_u32_e32 vcc, 7, v9
	v_mov_b32_e32 v14, 0x372d07a7
	s_nop 0
	v_cndmask_b32_e32 v13, v13, v14, vcc
	s_waitcnt vmcnt(20)
	v_cvt_f32_i32_e32 v11, v11
	v_mul_f32_e32 v11, v13, v11
	v_mul_f32_e32 v14, 0.15915494, v11
	v_floor_f32_e32 v14, v14
	v_fma_f32 v14, v11, 0.15915494, -v14
	v_cos_f32_e32 v11, v14
	v_sin_f32_e32 v12, v14
	v_cmp_gt_u32_e32 vcc, 2, v9
	s_waitcnt vmcnt(16)
	s_waitcnt vmcnt(14)
	v_readlane_b32 s28, v11, 0
	v_readlane_b32 s38, v12, 0
	v_readlane_b32 s29, v11, 1
	v_readlane_b32 s39, v12, 1
	v_readlane_b32 s30, v11, 2
	v_readlane_b32 s40, v12, 2
	v_readlane_b32 s31, v11, 3
	v_readlane_b32 s41, v12, 3
	v_readlane_b32 s34, v11, 4
	v_readlane_b32 s42, v12, 4
	v_readlane_b32 s35, v11, 5
	v_readlane_b32 s43, v12, 5
	v_readlane_b32 s36, v11, 6
	v_readlane_b32 s44, v12, 6
	v_readlane_b32 s37, v11, 7
	v_readlane_b32 s45, v12, 7
	v_mul_f32_e32 v32, s38, v10
	v_mul_f32_e32 v33, s39, v10
	v_mul_f32_e32 v34, s40, v10
	v_mul_f32_e32 v35, s41, v10
	v_mul_f32_e32 v36, s42, v10
	v_mul_f32_e32 v37, s43, v10
	v_mul_f32_e32 v38, s44, v10
	v_mul_f32_e32 v39, s45, v10
	v_lshlrev_b32_e32 v112, 16, v48
	v_and_b32_e32 v113, 0xffff0000, v48
	v_lshlrev_b32_e32 v114, 16, v49
	v_and_b32_e32 v115, 0xffff0000, v49
	v_lshlrev_b32_e32 v116, 16, v50
	v_and_b32_e32 v117, 0xffff0000, v50
	v_lshlrev_b32_e32 v118, 16, v51
	v_and_b32_e32 v119, 0xffff0000, v51
	v_mul_f32_e32 v140, v112, v112
	v_mul_f32_e32 v141, v113, v113
	v_fmac_f32_e32 v140, v114, v114
	v_fmac_f32_e32 v141, v115, v115
	v_fmac_f32_e32 v140, v116, v116
	v_fmac_f32_e32 v141, v117, v117
	v_fmac_f32_e32 v140, v118, v118
	v_fmac_f32_e32 v141, v119, v119
	v_add_f32_e32 v140, v140, v141
	s_nop 1
	v_add_f32_dpp v140, v140, v140 quad_perm:[1,0,3,2] row_mask:0xf bank_mask:0xf bound_ctrl:1
	s_nop 1
	v_add_f32_dpp v140, v140, v140 quad_perm:[2,3,0,1] row_mask:0xf bank_mask:0xf bound_ctrl:1
	s_nop 1
	v_add_f32_dpp v140, v140, v140 row_half_mirror row_mask:0xf bank_mask:0xf bound_ctrl:1
	v_fma_f32 v141, v140, s10, v15
	v_rsq_f32_e32 v141, v141
	s_nop 0
	v_mul_f32_e32 v112, v112, v141
	v_mul_f32_e32 v113, v113, v141
	v_mul_f32_e32 v114, v114, v141
	v_mul_f32_e32 v115, v115, v141
	v_mul_f32_e32 v116, v116, v141
	v_mul_f32_e32 v117, v117, v141
	v_mul_f32_e32 v118, v118, v141
	v_mul_f32_e32 v119, v119, v141
	v_mul_f32_e32 v112, v112, v16
	v_mul_f32_e32 v113, v113, v17
	v_mul_f32_e32 v114, v114, v18
	v_mul_f32_e32 v115, v115, v19
	v_mul_f32_e32 v116, v116, v20
	v_mul_f32_e32 v117, v117, v21
	v_mul_f32_e32 v118, v118, v22
	v_mul_f32_e32 v119, v119, v23
	v_mov_b32_dpp v120, v112 quad_perm:[1,0,3,2] row_mask:0xf bank_mask:0xf
	v_mov_b32_dpp v121, v113 quad_perm:[1,0,3,2] row_mask:0xf bank_mask:0xf
	v_mov_b32_dpp v122, v114 quad_perm:[1,0,3,2] row_mask:0xf bank_mask:0xf
	v_mov_b32_dpp v123, v115 quad_perm:[1,0,3,2] row_mask:0xf bank_mask:0xf
	v_mov_b32_dpp v124, v116 quad_perm:[1,0,3,2] row_mask:0xf bank_mask:0xf
	v_mov_b32_dpp v125, v117 quad_perm:[1,0,3,2] row_mask:0xf bank_mask:0xf
	v_mov_b32_dpp v126, v118 quad_perm:[1,0,3,2] row_mask:0xf bank_mask:0xf
	v_mov_b32_dpp v127, v119 quad_perm:[1,0,3,2] row_mask:0xf bank_mask:0xf
	v_mul_f32_e32 v128, s28, v112
	v_mul_f32_e32 v129, s29, v113
	v_mul_f32_e32 v130, s30, v114
	v_mul_f32_e32 v131, s31, v115
	v_mul_f32_e32 v132, s34, v116
	v_mul_f32_e32 v133, s35, v117
	v_mul_f32_e32 v134, s36, v118
	v_mul_f32_e32 v135, s37, v119
	v_fmac_f32_e32 v128, v32, v120
	v_fmac_f32_e32 v129, v33, v121
	v_fmac_f32_e32 v130, v34, v122
	v_fmac_f32_e32 v131, v35, v123
	v_fmac_f32_e32 v132, v36, v124
	v_fmac_f32_e32 v133, v37, v125
	v_fmac_f32_e32 v134, v38, v126
	v_fmac_f32_e32 v135, v39, v127
	v_cndmask_b32_e32 v112, v112, v128, vcc
	v_cndmask_b32_e32 v113, v113, v129, vcc
	v_cndmask_b32_e32 v114, v114, v130, vcc
	v_cndmask_b32_e32 v115, v115, v131, vcc
	v_cndmask_b32_e32 v116, v116, v132, vcc
	v_cndmask_b32_e32 v117, v117, v133, vcc
	v_cndmask_b32_e32 v118, v118, v134, vcc
	v_cndmask_b32_e32 v119, v119, v135, vcc
	v_mul_f32_e32 v112, 0x3e38aa3b, v112
	v_mul_f32_e32 v113, 0x3e38aa3b, v113
	v_mul_f32_e32 v114, 0x3e38aa3b, v114
	v_mul_f32_e32 v115, 0x3e38aa3b, v115
	v_mul_f32_e32 v116, 0x3e38aa3b, v116
	v_mul_f32_e32 v117, 0x3e38aa3b, v117
	v_mul_f32_e32 v118, 0x3e38aa3b, v118
	v_mul_f32_e32 v119, 0x3e38aa3b, v119
	v_cvt_pk_bf16_f32 v136, v112, v113
	v_cvt_pk_bf16_f32 v137, v114, v115
	v_cvt_pk_bf16_f32 v138, v116, v117
	v_cvt_pk_bf16_f32 v139, v118, v119
	global_store_dwordx4 v7, v[136:139], s[6:7]
	s_nop 1
	v_lshlrev_b32_e32 v112, 16, v52
	v_and_b32_e32 v113, 0xffff0000, v52
	v_lshlrev_b32_e32 v114, 16, v53
	v_and_b32_e32 v115, 0xffff0000, v53
	v_lshlrev_b32_e32 v116, 16, v54
	v_and_b32_e32 v117, 0xffff0000, v54
	v_lshlrev_b32_e32 v118, 16, v55
	v_and_b32_e32 v119, 0xffff0000, v55
	v_mul_f32_e32 v140, v112, v112
	v_mul_f32_e32 v141, v113, v113
	v_fmac_f32_e32 v140, v114, v114
	v_fmac_f32_e32 v141, v115, v115
	v_fmac_f32_e32 v140, v116, v116
	v_fmac_f32_e32 v141, v117, v117
	v_fmac_f32_e32 v140, v118, v118
	v_fmac_f32_e32 v141, v119, v119
	v_add_f32_e32 v140, v140, v141
	s_nop 1
	v_add_f32_dpp v140, v140, v140 quad_perm:[1,0,3,2] row_mask:0xf bank_mask:0xf bound_ctrl:1
	s_nop 1
	v_add_f32_dpp v140, v140, v140 quad_perm:[2,3,0,1] row_mask:0xf bank_mask:0xf bound_ctrl:1
	s_nop 1
	v_add_f32_dpp v140, v140, v140 row_half_mirror row_mask:0xf bank_mask:0xf bound_ctrl:1
	v_fma_f32 v141, v140, s10, v15
	v_rsq_f32_e32 v141, v141
	s_nop 0
	v_mul_f32_e32 v112, v112, v141
	v_mul_f32_e32 v113, v113, v141
	v_mul_f32_e32 v114, v114, v141
	v_mul_f32_e32 v115, v115, v141
	v_mul_f32_e32 v116, v116, v141
	v_mul_f32_e32 v117, v117, v141
	v_mul_f32_e32 v118, v118, v141
	v_mul_f32_e32 v119, v119, v141
	v_mul_f32_e32 v112, v112, v24
	v_mul_f32_e32 v113, v113, v25
	v_mul_f32_e32 v114, v114, v26
	v_mul_f32_e32 v115, v115, v27
	v_mul_f32_e32 v116, v116, v28
	v_mul_f32_e32 v117, v117, v29
	v_mul_f32_e32 v118, v118, v30
	v_mul_f32_e32 v119, v119, v31
	v_mov_b32_dpp v120, v112 quad_perm:[1,0,3,2] row_mask:0xf bank_mask:0xf
	v_mov_b32_dpp v121, v113 quad_perm:[1,0,3,2] row_mask:0xf bank_mask:0xf
	v_mov_b32_dpp v122, v114 quad_perm:[1,0,3,2] row_mask:0xf bank_mask:0xf
	v_mov_b32_dpp v123, v115 quad_perm:[1,0,3,2] row_mask:0xf bank_mask:0xf
	v_mov_b32_dpp v124, v116 quad_perm:[1,0,3,2] row_mask:0xf bank_mask:0xf
	v_mov_b32_dpp v125, v117 quad_perm:[1,0,3,2] row_mask:0xf bank_mask:0xf
	v_mov_b32_dpp v126, v118 quad_perm:[1,0,3,2] row_mask:0xf bank_mask:0xf
	v_mov_b32_dpp v127, v119 quad_perm:[1,0,3,2] row_mask:0xf bank_mask:0xf
	v_mul_f32_e32 v128, s28, v112
	v_mul_f32_e32 v129, s29, v113
	v_mul_f32_e32 v130, s30, v114
	v_mul_f32_e32 v131, s31, v115
	v_mul_f32_e32 v132, s34, v116
	v_mul_f32_e32 v133, s35, v117
	v_mul_f32_e32 v134, s36, v118
	v_mul_f32_e32 v135, s37, v119
	v_fmac_f32_e32 v128, v32, v120
	v_fmac_f32_e32 v129, v33, v121
	v_fmac_f32_e32 v130, v34, v122
	v_fmac_f32_e32 v131, v35, v123
	v_fmac_f32_e32 v132, v36, v124
	v_fmac_f32_e32 v133, v37, v125
	v_fmac_f32_e32 v134, v38, v126
	v_fmac_f32_e32 v135, v39, v127
	v_cndmask_b32_e32 v112, v112, v128, vcc
	v_cndmask_b32_e32 v113, v113, v129, vcc
	v_cndmask_b32_e32 v114, v114, v130, vcc
	v_cndmask_b32_e32 v115, v115, v131, vcc
	v_cndmask_b32_e32 v116, v116, v132, vcc
	v_cndmask_b32_e32 v117, v117, v133, vcc
	v_cndmask_b32_e32 v118, v118, v134, vcc
	v_cndmask_b32_e32 v119, v119, v135, vcc
	v_cvt_pk_bf16_f32 v136, v112, v113
	v_cvt_pk_bf16_f32 v137, v114, v115
	v_cvt_pk_bf16_f32 v138, v116, v117
	v_cvt_pk_bf16_f32 v139, v118, v119
	v_cndmask_b32_e64 v136, v136, v52, s[18:19]
	v_cndmask_b32_e64 v137, v137, v53, s[18:19]
	v_cndmask_b32_e64 v138, v138, v54, s[18:19]
	v_cndmask_b32_e64 v139, v139, v55, s[18:19]
	global_store_dwordx4 v8, v[136:139], s[12:13]
	s_add_u32 s6, s6, 0x200000
	s_addc_u32 s7, s7, 0
	s_add_u32 s12, s12, 0x80000
	s_addc_u32 s13, s13, 0
	s_waitcnt vmcnt(14)
	v_readlane_b32 s28, v11, 8
	v_readlane_b32 s38, v12, 8
	v_readlane_b32 s29, v11, 9
	v_readlane_b32 s39, v12, 9
	v_readlane_b32 s30, v11, 10
	v_readlane_b32 s40, v12, 10
	v_readlane_b32 s31, v11, 11
	v_readlane_b32 s41, v12, 11
	v_readlane_b32 s34, v11, 12
	v_readlane_b32 s42, v12, 12
	v_readlane_b32 s35, v11, 13
	v_readlane_b32 s43, v12, 13
	v_readlane_b32 s36, v11, 14
	v_readlane_b32 s44, v12, 14
	v_readlane_b32 s37, v11, 15
	v_readlane_b32 s45, v12, 15
	v_mul_f32_e32 v32, s38, v10
	v_mul_f32_e32 v33, s39, v10
	v_mul_f32_e32 v34, s40, v10
	v_mul_f32_e32 v35, s41, v10
	v_mul_f32_e32 v36, s42, v10
	v_mul_f32_e32 v37, s43, v10
	v_mul_f32_e32 v38, s44, v10
	v_mul_f32_e32 v39, s45, v10
	v_lshlrev_b32_e32 v112, 16, v56
	v_and_b32_e32 v113, 0xffff0000, v56
	v_lshlrev_b32_e32 v114, 16, v57
	v_and_b32_e32 v115, 0xffff0000, v57
	v_lshlrev_b32_e32 v116, 16, v58
	v_and_b32_e32 v117, 0xffff0000, v58
	v_lshlrev_b32_e32 v118, 16, v59
	v_and_b32_e32 v119, 0xffff0000, v59
	v_mul_f32_e32 v140, v112, v112
	v_mul_f32_e32 v141, v113, v113
	v_fmac_f32_e32 v140, v114, v114
	v_fmac_f32_e32 v141, v115, v115
	v_fmac_f32_e32 v140, v116, v116
	v_fmac_f32_e32 v141, v117, v117
	v_fmac_f32_e32 v140, v118, v118
	v_fmac_f32_e32 v141, v119, v119
	v_add_f32_e32 v140, v140, v141
	s_nop 1
	v_add_f32_dpp v140, v140, v140 quad_perm:[1,0,3,2] row_mask:0xf bank_mask:0xf bound_ctrl:1
	s_nop 1
	v_add_f32_dpp v140, v140, v140 quad_perm:[2,3,0,1] row_mask:0xf bank_mask:0xf bound_ctrl:1
	s_nop 1
	v_add_f32_dpp v140, v140, v140 row_half_mirror row_mask:0xf bank_mask:0xf bound_ctrl:1
	v_fma_f32 v141, v140, s10, v15
	v_rsq_f32_e32 v141, v141
	s_nop 0
	v_mul_f32_e32 v112, v112, v141
	v_mul_f32_e32 v113, v113, v141
	v_mul_f32_e32 v114, v114, v141
	v_mul_f32_e32 v115, v115, v141
	v_mul_f32_e32 v116, v116, v141
	v_mul_f32_e32 v117, v117, v141
	v_mul_f32_e32 v118, v118, v141
	v_mul_f32_e32 v119, v119, v141
	v_mul_f32_e32 v112, v112, v16
	v_mul_f32_e32 v113, v113, v17
	v_mul_f32_e32 v114, v114, v18
	v_mul_f32_e32 v115, v115, v19
	v_mul_f32_e32 v116, v116, v20
	v_mul_f32_e32 v117, v117, v21
	v_mul_f32_e32 v118, v118, v22
	v_mul_f32_e32 v119, v119, v23
	v_mov_b32_dpp v120, v112 quad_perm:[1,0,3,2] row_mask:0xf bank_mask:0xf
	v_mov_b32_dpp v121, v113 quad_perm:[1,0,3,2] row_mask:0xf bank_mask:0xf
	v_mov_b32_dpp v122, v114 quad_perm:[1,0,3,2] row_mask:0xf bank_mask:0xf
	v_mov_b32_dpp v123, v115 quad_perm:[1,0,3,2] row_mask:0xf bank_mask:0xf
	v_mov_b32_dpp v124, v116 quad_perm:[1,0,3,2] row_mask:0xf bank_mask:0xf
	v_mov_b32_dpp v125, v117 quad_perm:[1,0,3,2] row_mask:0xf bank_mask:0xf
	v_mov_b32_dpp v126, v118 quad_perm:[1,0,3,2] row_mask:0xf bank_mask:0xf
	v_mov_b32_dpp v127, v119 quad_perm:[1,0,3,2] row_mask:0xf bank_mask:0xf
	v_mul_f32_e32 v128, s28, v112
	v_mul_f32_e32 v129, s29, v113
	v_mul_f32_e32 v130, s30, v114
	v_mul_f32_e32 v131, s31, v115
	v_mul_f32_e32 v132, s34, v116
	v_mul_f32_e32 v133, s35, v117
	v_mul_f32_e32 v134, s36, v118
	v_mul_f32_e32 v135, s37, v119
	v_fmac_f32_e32 v128, v32, v120
	v_fmac_f32_e32 v129, v33, v121
	v_fmac_f32_e32 v130, v34, v122
	v_fmac_f32_e32 v131, v35, v123
	v_fmac_f32_e32 v132, v36, v124
	v_fmac_f32_e32 v133, v37, v125
	v_fmac_f32_e32 v134, v38, v126
	v_fmac_f32_e32 v135, v39, v127
	v_cndmask_b32_e32 v112, v112, v128, vcc
	v_cndmask_b32_e32 v113, v113, v129, vcc
	v_cndmask_b32_e32 v114, v114, v130, vcc
	v_cndmask_b32_e32 v115, v115, v131, vcc
	v_cndmask_b32_e32 v116, v116, v132, vcc
	v_cndmask_b32_e32 v117, v117, v133, vcc
	v_cndmask_b32_e32 v118, v118, v134, vcc
	v_cndmask_b32_e32 v119, v119, v135, vcc
	v_mul_f32_e32 v112, 0x3e38aa3b, v112
	v_mul_f32_e32 v113, 0x3e38aa3b, v113
	v_mul_f32_e32 v114, 0x3e38aa3b, v114
	v_mul_f32_e32 v115, 0x3e38aa3b, v115
	v_mul_f32_e32 v116, 0x3e38aa3b, v116
	v_mul_f32_e32 v117, 0x3e38aa3b, v117
	v_mul_f32_e32 v118, 0x3e38aa3b, v118
	v_mul_f32_e32 v119, 0x3e38aa3b, v119
	v_cvt_pk_bf16_f32 v136, v112, v113
	v_cvt_pk_bf16_f32 v137, v114, v115
	v_cvt_pk_bf16_f32 v138, v116, v117
	v_cvt_pk_bf16_f32 v139, v118, v119
	global_store_dwordx4 v7, v[136:139], s[6:7]
	s_nop 1
	v_lshlrev_b32_e32 v112, 16, v60
	v_and_b32_e32 v113, 0xffff0000, v60
	v_lshlrev_b32_e32 v114, 16, v61
	v_and_b32_e32 v115, 0xffff0000, v61
	v_lshlrev_b32_e32 v116, 16, v62
	v_and_b32_e32 v117, 0xffff0000, v62
	v_lshlrev_b32_e32 v118, 16, v63
	v_and_b32_e32 v119, 0xffff0000, v63
	v_mul_f32_e32 v140, v112, v112
	v_mul_f32_e32 v141, v113, v113
	v_fmac_f32_e32 v140, v114, v114
	v_fmac_f32_e32 v141, v115, v115
	v_fmac_f32_e32 v140, v116, v116
	v_fmac_f32_e32 v141, v117, v117
	v_fmac_f32_e32 v140, v118, v118
	v_fmac_f32_e32 v141, v119, v119
	v_add_f32_e32 v140, v140, v141
	s_nop 1
	v_add_f32_dpp v140, v140, v140 quad_perm:[1,0,3,2] row_mask:0xf bank_mask:0xf bound_ctrl:1
	s_nop 1
	v_add_f32_dpp v140, v140, v140 quad_perm:[2,3,0,1] row_mask:0xf bank_mask:0xf bound_ctrl:1
	s_nop 1
	v_add_f32_dpp v140, v140, v140 row_half_mirror row_mask:0xf bank_mask:0xf bound_ctrl:1
	v_fma_f32 v141, v140, s10, v15
	v_rsq_f32_e32 v141, v141
	s_nop 0
	v_mul_f32_e32 v112, v112, v141
	v_mul_f32_e32 v113, v113, v141
	v_mul_f32_e32 v114, v114, v141
	v_mul_f32_e32 v115, v115, v141
	v_mul_f32_e32 v116, v116, v141
	v_mul_f32_e32 v117, v117, v141
	v_mul_f32_e32 v118, v118, v141
	v_mul_f32_e32 v119, v119, v141
	v_mul_f32_e32 v112, v112, v24
	v_mul_f32_e32 v113, v113, v25
	v_mul_f32_e32 v114, v114, v26
	v_mul_f32_e32 v115, v115, v27
	v_mul_f32_e32 v116, v116, v28
	v_mul_f32_e32 v117, v117, v29
	v_mul_f32_e32 v118, v118, v30
	v_mul_f32_e32 v119, v119, v31
	v_mov_b32_dpp v120, v112 quad_perm:[1,0,3,2] row_mask:0xf bank_mask:0xf
	v_mov_b32_dpp v121, v113 quad_perm:[1,0,3,2] row_mask:0xf bank_mask:0xf
	v_mov_b32_dpp v122, v114 quad_perm:[1,0,3,2] row_mask:0xf bank_mask:0xf
	v_mov_b32_dpp v123, v115 quad_perm:[1,0,3,2] row_mask:0xf bank_mask:0xf
	v_mov_b32_dpp v124, v116 quad_perm:[1,0,3,2] row_mask:0xf bank_mask:0xf
	v_mov_b32_dpp v125, v117 quad_perm:[1,0,3,2] row_mask:0xf bank_mask:0xf
	v_mov_b32_dpp v126, v118 quad_perm:[1,0,3,2] row_mask:0xf bank_mask:0xf
	v_mov_b32_dpp v127, v119 quad_perm:[1,0,3,2] row_mask:0xf bank_mask:0xf
	v_mul_f32_e32 v128, s28, v112
	v_mul_f32_e32 v129, s29, v113
	v_mul_f32_e32 v130, s30, v114
	v_mul_f32_e32 v131, s31, v115
	v_mul_f32_e32 v132, s34, v116
	v_mul_f32_e32 v133, s35, v117
	v_mul_f32_e32 v134, s36, v118
	v_mul_f32_e32 v135, s37, v119
	v_fmac_f32_e32 v128, v32, v120
	v_fmac_f32_e32 v129, v33, v121
	v_fmac_f32_e32 v130, v34, v122
	v_fmac_f32_e32 v131, v35, v123
	v_fmac_f32_e32 v132, v36, v124
	v_fmac_f32_e32 v133, v37, v125
	v_fmac_f32_e32 v134, v38, v126
	v_fmac_f32_e32 v135, v39, v127
	v_cndmask_b32_e32 v112, v112, v128, vcc
	v_cndmask_b32_e32 v113, v113, v129, vcc
	v_cndmask_b32_e32 v114, v114, v130, vcc
	v_cndmask_b32_e32 v115, v115, v131, vcc
	v_cndmask_b32_e32 v116, v116, v132, vcc
	v_cndmask_b32_e32 v117, v117, v133, vcc
	v_cndmask_b32_e32 v118, v118, v134, vcc
	v_cndmask_b32_e32 v119, v119, v135, vcc
	v_cvt_pk_bf16_f32 v136, v112, v113
	v_cvt_pk_bf16_f32 v137, v114, v115
	v_cvt_pk_bf16_f32 v138, v116, v117
	v_cvt_pk_bf16_f32 v139, v118, v119
	v_cndmask_b32_e64 v136, v136, v60, s[18:19]
	v_cndmask_b32_e64 v137, v137, v61, s[18:19]
	v_cndmask_b32_e64 v138, v138, v62, s[18:19]
	v_cndmask_b32_e64 v139, v139, v63, s[18:19]
	global_store_dwordx4 v8, v[136:139], s[12:13]
	s_add_u32 s6, s6, 0x200000
	s_addc_u32 s7, s7, 0
	s_add_u32 s12, s12, 0x80000
	s_addc_u32 s13, s13, 0
	s_waitcnt vmcnt(14)
	v_readlane_b32 s28, v11, 16
	v_readlane_b32 s38, v12, 16
	v_readlane_b32 s29, v11, 17
	v_readlane_b32 s39, v12, 17
	v_readlane_b32 s30, v11, 18
	v_readlane_b32 s40, v12, 18
	v_readlane_b32 s31, v11, 19
	v_readlane_b32 s41, v12, 19
	v_readlane_b32 s34, v11, 20
	v_readlane_b32 s42, v12, 20
	v_readlane_b32 s35, v11, 21
	v_readlane_b32 s43, v12, 21
	v_readlane_b32 s36, v11, 22
	v_readlane_b32 s44, v12, 22
	v_readlane_b32 s37, v11, 23
	v_readlane_b32 s45, v12, 23
	v_mul_f32_e32 v32, s38, v10
	v_mul_f32_e32 v33, s39, v10
	v_mul_f32_e32 v34, s40, v10
	v_mul_f32_e32 v35, s41, v10
	v_mul_f32_e32 v36, s42, v10
	v_mul_f32_e32 v37, s43, v10
	v_mul_f32_e32 v38, s44, v10
	v_mul_f32_e32 v39, s45, v10
	v_lshlrev_b32_e32 v112, 16, v64
	v_and_b32_e32 v113, 0xffff0000, v64
	v_lshlrev_b32_e32 v114, 16, v65
	v_and_b32_e32 v115, 0xffff0000, v65
	v_lshlrev_b32_e32 v116, 16, v66
	v_and_b32_e32 v117, 0xffff0000, v66
	v_lshlrev_b32_e32 v118, 16, v67
	v_and_b32_e32 v119, 0xffff0000, v67
	v_mul_f32_e32 v140, v112, v112
	v_mul_f32_e32 v141, v113, v113
	v_fmac_f32_e32 v140, v114, v114
	v_fmac_f32_e32 v141, v115, v115
	v_fmac_f32_e32 v140, v116, v116
	v_fmac_f32_e32 v141, v117, v117
	v_fmac_f32_e32 v140, v118, v118
	v_fmac_f32_e32 v141, v119, v119
	v_add_f32_e32 v140, v140, v141
	s_nop 1
	v_add_f32_dpp v140, v140, v140 quad_perm:[1,0,3,2] row_mask:0xf bank_mask:0xf bound_ctrl:1
	s_nop 1
	v_add_f32_dpp v140, v140, v140 quad_perm:[2,3,0,1] row_mask:0xf bank_mask:0xf bound_ctrl:1
	s_nop 1
	v_add_f32_dpp v140, v140, v140 row_half_mirror row_mask:0xf bank_mask:0xf bound_ctrl:1
	v_fma_f32 v141, v140, s10, v15
	v_rsq_f32_e32 v141, v141
	s_nop 0
	v_mul_f32_e32 v112, v112, v141
	v_mul_f32_e32 v113, v113, v141
	v_mul_f32_e32 v114, v114, v141
	v_mul_f32_e32 v115, v115, v141
	v_mul_f32_e32 v116, v116, v141
	v_mul_f32_e32 v117, v117, v141
	v_mul_f32_e32 v118, v118, v141
	v_mul_f32_e32 v119, v119, v141
	v_mul_f32_e32 v112, v112, v16
	v_mul_f32_e32 v113, v113, v17
	v_mul_f32_e32 v114, v114, v18
	v_mul_f32_e32 v115, v115, v19
	v_mul_f32_e32 v116, v116, v20
	v_mul_f32_e32 v117, v117, v21
	v_mul_f32_e32 v118, v118, v22
	v_mul_f32_e32 v119, v119, v23
	v_mov_b32_dpp v120, v112 quad_perm:[1,0,3,2] row_mask:0xf bank_mask:0xf
	v_mov_b32_dpp v121, v113 quad_perm:[1,0,3,2] row_mask:0xf bank_mask:0xf
	v_mov_b32_dpp v122, v114 quad_perm:[1,0,3,2] row_mask:0xf bank_mask:0xf
	v_mov_b32_dpp v123, v115 quad_perm:[1,0,3,2] row_mask:0xf bank_mask:0xf
	v_mov_b32_dpp v124, v116 quad_perm:[1,0,3,2] row_mask:0xf bank_mask:0xf
	v_mov_b32_dpp v125, v117 quad_perm:[1,0,3,2] row_mask:0xf bank_mask:0xf
	v_mov_b32_dpp v126, v118 quad_perm:[1,0,3,2] row_mask:0xf bank_mask:0xf
	v_mov_b32_dpp v127, v119 quad_perm:[1,0,3,2] row_mask:0xf bank_mask:0xf
	v_mul_f32_e32 v128, s28, v112
	v_mul_f32_e32 v129, s29, v113
	v_mul_f32_e32 v130, s30, v114
	v_mul_f32_e32 v131, s31, v115
	v_mul_f32_e32 v132, s34, v116
	v_mul_f32_e32 v133, s35, v117
	v_mul_f32_e32 v134, s36, v118
	v_mul_f32_e32 v135, s37, v119
	v_fmac_f32_e32 v128, v32, v120
	v_fmac_f32_e32 v129, v33, v121
	v_fmac_f32_e32 v130, v34, v122
	v_fmac_f32_e32 v131, v35, v123
	v_fmac_f32_e32 v132, v36, v124
	v_fmac_f32_e32 v133, v37, v125
	v_fmac_f32_e32 v134, v38, v126
	v_fmac_f32_e32 v135, v39, v127
	v_cndmask_b32_e32 v112, v112, v128, vcc
	v_cndmask_b32_e32 v113, v113, v129, vcc
	v_cndmask_b32_e32 v114, v114, v130, vcc
	v_cndmask_b32_e32 v115, v115, v131, vcc
	v_cndmask_b32_e32 v116, v116, v132, vcc
	v_cndmask_b32_e32 v117, v117, v133, vcc
	v_cndmask_b32_e32 v118, v118, v134, vcc
	v_cndmask_b32_e32 v119, v119, v135, vcc
	v_mul_f32_e32 v112, 0x3e38aa3b, v112
	v_mul_f32_e32 v113, 0x3e38aa3b, v113
	v_mul_f32_e32 v114, 0x3e38aa3b, v114
	v_mul_f32_e32 v115, 0x3e38aa3b, v115
	v_mul_f32_e32 v116, 0x3e38aa3b, v116
	v_mul_f32_e32 v117, 0x3e38aa3b, v117
	v_mul_f32_e32 v118, 0x3e38aa3b, v118
	v_mul_f32_e32 v119, 0x3e38aa3b, v119
	v_cvt_pk_bf16_f32 v136, v112, v113
	v_cvt_pk_bf16_f32 v137, v114, v115
	v_cvt_pk_bf16_f32 v138, v116, v117
	v_cvt_pk_bf16_f32 v139, v118, v119
	global_store_dwordx4 v7, v[136:139], s[6:7]
	s_nop 1
	v_lshlrev_b32_e32 v112, 16, v68
	v_and_b32_e32 v113, 0xffff0000, v68
	v_lshlrev_b32_e32 v114, 16, v69
	v_and_b32_e32 v115, 0xffff0000, v69
	v_lshlrev_b32_e32 v116, 16, v70
	v_and_b32_e32 v117, 0xffff0000, v70
	v_lshlrev_b32_e32 v118, 16, v71
	v_and_b32_e32 v119, 0xffff0000, v71
	v_mul_f32_e32 v140, v112, v112
	v_mul_f32_e32 v141, v113, v113
	v_fmac_f32_e32 v140, v114, v114
	v_fmac_f32_e32 v141, v115, v115
	v_fmac_f32_e32 v140, v116, v116
	v_fmac_f32_e32 v141, v117, v117
	v_fmac_f32_e32 v140, v118, v118
	v_fmac_f32_e32 v141, v119, v119
	v_add_f32_e32 v140, v140, v141
	s_nop 1
	v_add_f32_dpp v140, v140, v140 quad_perm:[1,0,3,2] row_mask:0xf bank_mask:0xf bound_ctrl:1
	s_nop 1
	v_add_f32_dpp v140, v140, v140 quad_perm:[2,3,0,1] row_mask:0xf bank_mask:0xf bound_ctrl:1
	s_nop 1
	v_add_f32_dpp v140, v140, v140 row_half_mirror row_mask:0xf bank_mask:0xf bound_ctrl:1
	v_fma_f32 v141, v140, s10, v15
	v_rsq_f32_e32 v141, v141
	s_nop 0
	v_mul_f32_e32 v112, v112, v141
	v_mul_f32_e32 v113, v113, v141
	v_mul_f32_e32 v114, v114, v141
	v_mul_f32_e32 v115, v115, v141
	v_mul_f32_e32 v116, v116, v141
	v_mul_f32_e32 v117, v117, v141
	v_mul_f32_e32 v118, v118, v141
	v_mul_f32_e32 v119, v119, v141
	v_mul_f32_e32 v112, v112, v24
	v_mul_f32_e32 v113, v113, v25
	v_mul_f32_e32 v114, v114, v26
	v_mul_f32_e32 v115, v115, v27
	v_mul_f32_e32 v116, v116, v28
	v_mul_f32_e32 v117, v117, v29
	v_mul_f32_e32 v118, v118, v30
	v_mul_f32_e32 v119, v119, v31
	v_mov_b32_dpp v120, v112 quad_perm:[1,0,3,2] row_mask:0xf bank_mask:0xf
	v_mov_b32_dpp v121, v113 quad_perm:[1,0,3,2] row_mask:0xf bank_mask:0xf
	v_mov_b32_dpp v122, v114 quad_perm:[1,0,3,2] row_mask:0xf bank_mask:0xf
	v_mov_b32_dpp v123, v115 quad_perm:[1,0,3,2] row_mask:0xf bank_mask:0xf
	v_mov_b32_dpp v124, v116 quad_perm:[1,0,3,2] row_mask:0xf bank_mask:0xf
	v_mov_b32_dpp v125, v117 quad_perm:[1,0,3,2] row_mask:0xf bank_mask:0xf
	v_mov_b32_dpp v126, v118 quad_perm:[1,0,3,2] row_mask:0xf bank_mask:0xf
	v_mov_b32_dpp v127, v119 quad_perm:[1,0,3,2] row_mask:0xf bank_mask:0xf
	v_mul_f32_e32 v128, s28, v112
	v_mul_f32_e32 v129, s29, v113
	v_mul_f32_e32 v130, s30, v114
	v_mul_f32_e32 v131, s31, v115
	v_mul_f32_e32 v132, s34, v116
	v_mul_f32_e32 v133, s35, v117
	v_mul_f32_e32 v134, s36, v118
	v_mul_f32_e32 v135, s37, v119
	v_fmac_f32_e32 v128, v32, v120
	v_fmac_f32_e32 v129, v33, v121
	v_fmac_f32_e32 v130, v34, v122
	v_fmac_f32_e32 v131, v35, v123
	v_fmac_f32_e32 v132, v36, v124
	v_fmac_f32_e32 v133, v37, v125
	v_fmac_f32_e32 v134, v38, v126
	v_fmac_f32_e32 v135, v39, v127
	v_cndmask_b32_e32 v112, v112, v128, vcc
	v_cndmask_b32_e32 v113, v113, v129, vcc
	v_cndmask_b32_e32 v114, v114, v130, vcc
	v_cndmask_b32_e32 v115, v115, v131, vcc
	v_cndmask_b32_e32 v116, v116, v132, vcc
	v_cndmask_b32_e32 v117, v117, v133, vcc
	v_cndmask_b32_e32 v118, v118, v134, vcc
	v_cndmask_b32_e32 v119, v119, v135, vcc
	v_cvt_pk_bf16_f32 v136, v112, v113
	v_cvt_pk_bf16_f32 v137, v114, v115
	v_cvt_pk_bf16_f32 v138, v116, v117
	v_cvt_pk_bf16_f32 v139, v118, v119
	v_cndmask_b32_e64 v136, v136, v68, s[18:19]
	v_cndmask_b32_e64 v137, v137, v69, s[18:19]
	v_cndmask_b32_e64 v138, v138, v70, s[18:19]
	v_cndmask_b32_e64 v139, v139, v71, s[18:19]
	global_store_dwordx4 v8, v[136:139], s[12:13]
	s_add_u32 s6, s6, 0x200000
	s_addc_u32 s7, s7, 0
	s_add_u32 s12, s12, 0x80000
	s_addc_u32 s13, s13, 0
	s_waitcnt vmcnt(14)
	v_readlane_b32 s28, v11, 24
	v_readlane_b32 s38, v12, 24
	v_readlane_b32 s29, v11, 25
	v_readlane_b32 s39, v12, 25
	v_readlane_b32 s30, v11, 26
	v_readlane_b32 s40, v12, 26
	v_readlane_b32 s31, v11, 27
	v_readlane_b32 s41, v12, 27
	v_readlane_b32 s34, v11, 28
	v_readlane_b32 s42, v12, 28
	v_readlane_b32 s35, v11, 29
	v_readlane_b32 s43, v12, 29
	v_readlane_b32 s36, v11, 30
	v_readlane_b32 s44, v12, 30
	v_readlane_b32 s37, v11, 31
	v_readlane_b32 s45, v12, 31
	v_mul_f32_e32 v32, s38, v10
	v_mul_f32_e32 v33, s39, v10
	v_mul_f32_e32 v34, s40, v10
	v_mul_f32_e32 v35, s41, v10
	v_mul_f32_e32 v36, s42, v10
	v_mul_f32_e32 v37, s43, v10
	v_mul_f32_e32 v38, s44, v10
	v_mul_f32_e32 v39, s45, v10
	v_lshlrev_b32_e32 v112, 16, v72
	v_and_b32_e32 v113, 0xffff0000, v72
	v_lshlrev_b32_e32 v114, 16, v73
	v_and_b32_e32 v115, 0xffff0000, v73
	v_lshlrev_b32_e32 v116, 16, v74
	v_and_b32_e32 v117, 0xffff0000, v74
	v_lshlrev_b32_e32 v118, 16, v75
	v_and_b32_e32 v119, 0xffff0000, v75
	v_mul_f32_e32 v140, v112, v112
	v_mul_f32_e32 v141, v113, v113
	v_fmac_f32_e32 v140, v114, v114
	v_fmac_f32_e32 v141, v115, v115
	v_fmac_f32_e32 v140, v116, v116
	v_fmac_f32_e32 v141, v117, v117
	v_fmac_f32_e32 v140, v118, v118
	v_fmac_f32_e32 v141, v119, v119
	v_add_f32_e32 v140, v140, v141
	s_nop 1
	v_add_f32_dpp v140, v140, v140 quad_perm:[1,0,3,2] row_mask:0xf bank_mask:0xf bound_ctrl:1
	s_nop 1
	v_add_f32_dpp v140, v140, v140 quad_perm:[2,3,0,1] row_mask:0xf bank_mask:0xf bound_ctrl:1
	s_nop 1
	v_add_f32_dpp v140, v140, v140 row_half_mirror row_mask:0xf bank_mask:0xf bound_ctrl:1
	v_fma_f32 v141, v140, s10, v15
	v_rsq_f32_e32 v141, v141
	s_nop 0
	v_mul_f32_e32 v112, v112, v141
	v_mul_f32_e32 v113, v113, v141
	v_mul_f32_e32 v114, v114, v141
	v_mul_f32_e32 v115, v115, v141
	v_mul_f32_e32 v116, v116, v141
	v_mul_f32_e32 v117, v117, v141
	v_mul_f32_e32 v118, v118, v141
	v_mul_f32_e32 v119, v119, v141
	v_mul_f32_e32 v112, v112, v16
	v_mul_f32_e32 v113, v113, v17
	v_mul_f32_e32 v114, v114, v18
	v_mul_f32_e32 v115, v115, v19
	v_mul_f32_e32 v116, v116, v20
	v_mul_f32_e32 v117, v117, v21
	v_mul_f32_e32 v118, v118, v22
	v_mul_f32_e32 v119, v119, v23
	v_mov_b32_dpp v120, v112 quad_perm:[1,0,3,2] row_mask:0xf bank_mask:0xf
	v_mov_b32_dpp v121, v113 quad_perm:[1,0,3,2] row_mask:0xf bank_mask:0xf
	v_mov_b32_dpp v122, v114 quad_perm:[1,0,3,2] row_mask:0xf bank_mask:0xf
	v_mov_b32_dpp v123, v115 quad_perm:[1,0,3,2] row_mask:0xf bank_mask:0xf
	v_mov_b32_dpp v124, v116 quad_perm:[1,0,3,2] row_mask:0xf bank_mask:0xf
	v_mov_b32_dpp v125, v117 quad_perm:[1,0,3,2] row_mask:0xf bank_mask:0xf
	v_mov_b32_dpp v126, v118 quad_perm:[1,0,3,2] row_mask:0xf bank_mask:0xf
	v_mov_b32_dpp v127, v119 quad_perm:[1,0,3,2] row_mask:0xf bank_mask:0xf
	v_mul_f32_e32 v128, s28, v112
	v_mul_f32_e32 v129, s29, v113
	v_mul_f32_e32 v130, s30, v114
	v_mul_f32_e32 v131, s31, v115
	v_mul_f32_e32 v132, s34, v116
	v_mul_f32_e32 v133, s35, v117
	v_mul_f32_e32 v134, s36, v118
	v_mul_f32_e32 v135, s37, v119
	v_fmac_f32_e32 v128, v32, v120
	v_fmac_f32_e32 v129, v33, v121
	v_fmac_f32_e32 v130, v34, v122
	v_fmac_f32_e32 v131, v35, v123
	v_fmac_f32_e32 v132, v36, v124
	v_fmac_f32_e32 v133, v37, v125
	v_fmac_f32_e32 v134, v38, v126
	v_fmac_f32_e32 v135, v39, v127
	v_cndmask_b32_e32 v112, v112, v128, vcc
	v_cndmask_b32_e32 v113, v113, v129, vcc
	v_cndmask_b32_e32 v114, v114, v130, vcc
	v_cndmask_b32_e32 v115, v115, v131, vcc
	v_cndmask_b32_e32 v116, v116, v132, vcc
	v_cndmask_b32_e32 v117, v117, v133, vcc
	v_cndmask_b32_e32 v118, v118, v134, vcc
	v_cndmask_b32_e32 v119, v119, v135, vcc
	v_mul_f32_e32 v112, 0x3e38aa3b, v112
	v_mul_f32_e32 v113, 0x3e38aa3b, v113
	v_mul_f32_e32 v114, 0x3e38aa3b, v114
	v_mul_f32_e32 v115, 0x3e38aa3b, v115
	v_mul_f32_e32 v116, 0x3e38aa3b, v116
	v_mul_f32_e32 v117, 0x3e38aa3b, v117
	v_mul_f32_e32 v118, 0x3e38aa3b, v118
	v_mul_f32_e32 v119, 0x3e38aa3b, v119
	v_cvt_pk_bf16_f32 v136, v112, v113
	v_cvt_pk_bf16_f32 v137, v114, v115
	v_cvt_pk_bf16_f32 v138, v116, v117
	v_cvt_pk_bf16_f32 v139, v118, v119
	global_store_dwordx4 v7, v[136:139], s[6:7]
	s_nop 1
	v_lshlrev_b32_e32 v112, 16, v76
	v_and_b32_e32 v113, 0xffff0000, v76
	v_lshlrev_b32_e32 v114, 16, v77
	v_and_b32_e32 v115, 0xffff0000, v77
	v_lshlrev_b32_e32 v116, 16, v78
	v_and_b32_e32 v117, 0xffff0000, v78
	v_lshlrev_b32_e32 v118, 16, v79
	v_and_b32_e32 v119, 0xffff0000, v79
	v_mul_f32_e32 v140, v112, v112
	v_mul_f32_e32 v141, v113, v113
	v_fmac_f32_e32 v140, v114, v114
	v_fmac_f32_e32 v141, v115, v115
	v_fmac_f32_e32 v140, v116, v116
	v_fmac_f32_e32 v141, v117, v117
	v_fmac_f32_e32 v140, v118, v118
	v_fmac_f32_e32 v141, v119, v119
	v_add_f32_e32 v140, v140, v141
	s_nop 1
	v_add_f32_dpp v140, v140, v140 quad_perm:[1,0,3,2] row_mask:0xf bank_mask:0xf bound_ctrl:1
	s_nop 1
	v_add_f32_dpp v140, v140, v140 quad_perm:[2,3,0,1] row_mask:0xf bank_mask:0xf bound_ctrl:1
	s_nop 1
	v_add_f32_dpp v140, v140, v140 row_half_mirror row_mask:0xf bank_mask:0xf bound_ctrl:1
	v_fma_f32 v141, v140, s10, v15
	v_rsq_f32_e32 v141, v141
	s_nop 0
	v_mul_f32_e32 v112, v112, v141
	v_mul_f32_e32 v113, v113, v141
	v_mul_f32_e32 v114, v114, v141
	v_mul_f32_e32 v115, v115, v141
	v_mul_f32_e32 v116, v116, v141
	v_mul_f32_e32 v117, v117, v141
	v_mul_f32_e32 v118, v118, v141
	v_mul_f32_e32 v119, v119, v141
	v_mul_f32_e32 v112, v112, v24
	v_mul_f32_e32 v113, v113, v25
	v_mul_f32_e32 v114, v114, v26
	v_mul_f32_e32 v115, v115, v27
	v_mul_f32_e32 v116, v116, v28
	v_mul_f32_e32 v117, v117, v29
	v_mul_f32_e32 v118, v118, v30
	v_mul_f32_e32 v119, v119, v31
	v_mov_b32_dpp v120, v112 quad_perm:[1,0,3,2] row_mask:0xf bank_mask:0xf
	v_mov_b32_dpp v121, v113 quad_perm:[1,0,3,2] row_mask:0xf bank_mask:0xf
	v_mov_b32_dpp v122, v114 quad_perm:[1,0,3,2] row_mask:0xf bank_mask:0xf
	v_mov_b32_dpp v123, v115 quad_perm:[1,0,3,2] row_mask:0xf bank_mask:0xf
	v_mov_b32_dpp v124, v116 quad_perm:[1,0,3,2] row_mask:0xf bank_mask:0xf
	v_mov_b32_dpp v125, v117 quad_perm:[1,0,3,2] row_mask:0xf bank_mask:0xf
	v_mov_b32_dpp v126, v118 quad_perm:[1,0,3,2] row_mask:0xf bank_mask:0xf
	v_mov_b32_dpp v127, v119 quad_perm:[1,0,3,2] row_mask:0xf bank_mask:0xf
	v_mul_f32_e32 v128, s28, v112
	v_mul_f32_e32 v129, s29, v113
	v_mul_f32_e32 v130, s30, v114
	v_mul_f32_e32 v131, s31, v115
	v_mul_f32_e32 v132, s34, v116
	v_mul_f32_e32 v133, s35, v117
	v_mul_f32_e32 v134, s36, v118
	v_mul_f32_e32 v135, s37, v119
	v_fmac_f32_e32 v128, v32, v120
	v_fmac_f32_e32 v129, v33, v121
	v_fmac_f32_e32 v130, v34, v122
	v_fmac_f32_e32 v131, v35, v123
	v_fmac_f32_e32 v132, v36, v124
	v_fmac_f32_e32 v133, v37, v125
	v_fmac_f32_e32 v134, v38, v126
	v_fmac_f32_e32 v135, v39, v127
	v_cndmask_b32_e32 v112, v112, v128, vcc
	v_cndmask_b32_e32 v113, v113, v129, vcc
	v_cndmask_b32_e32 v114, v114, v130, vcc
	v_cndmask_b32_e32 v115, v115, v131, vcc
	v_cndmask_b32_e32 v116, v116, v132, vcc
	v_cndmask_b32_e32 v117, v117, v133, vcc
	v_cndmask_b32_e32 v118, v118, v134, vcc
	v_cndmask_b32_e32 v119, v119, v135, vcc
	v_cvt_pk_bf16_f32 v136, v112, v113
	v_cvt_pk_bf16_f32 v137, v114, v115
	v_cvt_pk_bf16_f32 v138, v116, v117
	v_cvt_pk_bf16_f32 v139, v118, v119
	v_cndmask_b32_e64 v136, v136, v76, s[18:19]
	v_cndmask_b32_e64 v137, v137, v77, s[18:19]
	v_cndmask_b32_e64 v138, v138, v78, s[18:19]
	v_cndmask_b32_e64 v139, v139, v79, s[18:19]
	global_store_dwordx4 v8, v[136:139], s[12:13]
	s_add_u32 s6, s6, 0x200000
	s_addc_u32 s7, s7, 0
	s_add_u32 s12, s12, 0x80000
	s_addc_u32 s13, s13, 0
	s_waitcnt vmcnt(14)
	v_readlane_b32 s28, v11, 32
	v_readlane_b32 s38, v12, 32
	v_readlane_b32 s29, v11, 33
	v_readlane_b32 s39, v12, 33
	v_readlane_b32 s30, v11, 34
	v_readlane_b32 s40, v12, 34
	v_readlane_b32 s31, v11, 35
	v_readlane_b32 s41, v12, 35
	v_readlane_b32 s34, v11, 36
	v_readlane_b32 s42, v12, 36
	v_readlane_b32 s35, v11, 37
	v_readlane_b32 s43, v12, 37
	v_readlane_b32 s36, v11, 38
	v_readlane_b32 s44, v12, 38
	v_readlane_b32 s37, v11, 39
	v_readlane_b32 s45, v12, 39
	v_mul_f32_e32 v32, s38, v10
	v_mul_f32_e32 v33, s39, v10
	v_mul_f32_e32 v34, s40, v10
	v_mul_f32_e32 v35, s41, v10
	v_mul_f32_e32 v36, s42, v10
	v_mul_f32_e32 v37, s43, v10
	v_mul_f32_e32 v38, s44, v10
	v_mul_f32_e32 v39, s45, v10
	v_lshlrev_b32_e32 v112, 16, v80
	v_and_b32_e32 v113, 0xffff0000, v80
	v_lshlrev_b32_e32 v114, 16, v81
	v_and_b32_e32 v115, 0xffff0000, v81
	v_lshlrev_b32_e32 v116, 16, v82
	v_and_b32_e32 v117, 0xffff0000, v82
	v_lshlrev_b32_e32 v118, 16, v83
	v_and_b32_e32 v119, 0xffff0000, v83
	v_mul_f32_e32 v140, v112, v112
	v_mul_f32_e32 v141, v113, v113
	v_fmac_f32_e32 v140, v114, v114
	v_fmac_f32_e32 v141, v115, v115
	v_fmac_f32_e32 v140, v116, v116
	v_fmac_f32_e32 v141, v117, v117
	v_fmac_f32_e32 v140, v118, v118
	v_fmac_f32_e32 v141, v119, v119
	v_add_f32_e32 v140, v140, v141
	s_nop 1
	v_add_f32_dpp v140, v140, v140 quad_perm:[1,0,3,2] row_mask:0xf bank_mask:0xf bound_ctrl:1
	s_nop 1
	v_add_f32_dpp v140, v140, v140 quad_perm:[2,3,0,1] row_mask:0xf bank_mask:0xf bound_ctrl:1
	s_nop 1
	v_add_f32_dpp v140, v140, v140 row_half_mirror row_mask:0xf bank_mask:0xf bound_ctrl:1
	v_fma_f32 v141, v140, s10, v15
	v_rsq_f32_e32 v141, v141
	s_nop 0
	v_mul_f32_e32 v112, v112, v141
	v_mul_f32_e32 v113, v113, v141
	v_mul_f32_e32 v114, v114, v141
	v_mul_f32_e32 v115, v115, v141
	v_mul_f32_e32 v116, v116, v141
	v_mul_f32_e32 v117, v117, v141
	v_mul_f32_e32 v118, v118, v141
	v_mul_f32_e32 v119, v119, v141
	v_mul_f32_e32 v112, v112, v16
	v_mul_f32_e32 v113, v113, v17
	v_mul_f32_e32 v114, v114, v18
	v_mul_f32_e32 v115, v115, v19
	v_mul_f32_e32 v116, v116, v20
	v_mul_f32_e32 v117, v117, v21
	v_mul_f32_e32 v118, v118, v22
	v_mul_f32_e32 v119, v119, v23
	v_mov_b32_dpp v120, v112 quad_perm:[1,0,3,2] row_mask:0xf bank_mask:0xf
	v_mov_b32_dpp v121, v113 quad_perm:[1,0,3,2] row_mask:0xf bank_mask:0xf
	v_mov_b32_dpp v122, v114 quad_perm:[1,0,3,2] row_mask:0xf bank_mask:0xf
	v_mov_b32_dpp v123, v115 quad_perm:[1,0,3,2] row_mask:0xf bank_mask:0xf
	v_mov_b32_dpp v124, v116 quad_perm:[1,0,3,2] row_mask:0xf bank_mask:0xf
	v_mov_b32_dpp v125, v117 quad_perm:[1,0,3,2] row_mask:0xf bank_mask:0xf
	v_mov_b32_dpp v126, v118 quad_perm:[1,0,3,2] row_mask:0xf bank_mask:0xf
	v_mov_b32_dpp v127, v119 quad_perm:[1,0,3,2] row_mask:0xf bank_mask:0xf
	v_mul_f32_e32 v128, s28, v112
	v_mul_f32_e32 v129, s29, v113
	v_mul_f32_e32 v130, s30, v114
	v_mul_f32_e32 v131, s31, v115
	v_mul_f32_e32 v132, s34, v116
	v_mul_f32_e32 v133, s35, v117
	v_mul_f32_e32 v134, s36, v118
	v_mul_f32_e32 v135, s37, v119
	v_fmac_f32_e32 v128, v32, v120
	v_fmac_f32_e32 v129, v33, v121
	v_fmac_f32_e32 v130, v34, v122
	v_fmac_f32_e32 v131, v35, v123
	v_fmac_f32_e32 v132, v36, v124
	v_fmac_f32_e32 v133, v37, v125
	v_fmac_f32_e32 v134, v38, v126
	v_fmac_f32_e32 v135, v39, v127
	v_cndmask_b32_e32 v112, v112, v128, vcc
	v_cndmask_b32_e32 v113, v113, v129, vcc
	v_cndmask_b32_e32 v114, v114, v130, vcc
	v_cndmask_b32_e32 v115, v115, v131, vcc
	v_cndmask_b32_e32 v116, v116, v132, vcc
	v_cndmask_b32_e32 v117, v117, v133, vcc
	v_cndmask_b32_e32 v118, v118, v134, vcc
	v_cndmask_b32_e32 v119, v119, v135, vcc
	v_mul_f32_e32 v112, 0x3e38aa3b, v112
	v_mul_f32_e32 v113, 0x3e38aa3b, v113
	v_mul_f32_e32 v114, 0x3e38aa3b, v114
	v_mul_f32_e32 v115, 0x3e38aa3b, v115
	v_mul_f32_e32 v116, 0x3e38aa3b, v116
	v_mul_f32_e32 v117, 0x3e38aa3b, v117
	v_mul_f32_e32 v118, 0x3e38aa3b, v118
	v_mul_f32_e32 v119, 0x3e38aa3b, v119
	v_cvt_pk_bf16_f32 v136, v112, v113
	v_cvt_pk_bf16_f32 v137, v114, v115
	v_cvt_pk_bf16_f32 v138, v116, v117
	v_cvt_pk_bf16_f32 v139, v118, v119
	global_store_dwordx4 v7, v[136:139], s[6:7]
	s_nop 1
	v_lshlrev_b32_e32 v112, 16, v84
	v_and_b32_e32 v113, 0xffff0000, v84
	v_lshlrev_b32_e32 v114, 16, v85
	v_and_b32_e32 v115, 0xffff0000, v85
	v_lshlrev_b32_e32 v116, 16, v86
	v_and_b32_e32 v117, 0xffff0000, v86
	v_lshlrev_b32_e32 v118, 16, v87
	v_and_b32_e32 v119, 0xffff0000, v87
	v_mul_f32_e32 v140, v112, v112
	v_mul_f32_e32 v141, v113, v113
	v_fmac_f32_e32 v140, v114, v114
	v_fmac_f32_e32 v141, v115, v115
	v_fmac_f32_e32 v140, v116, v116
	v_fmac_f32_e32 v141, v117, v117
	v_fmac_f32_e32 v140, v118, v118
	v_fmac_f32_e32 v141, v119, v119
	v_add_f32_e32 v140, v140, v141
	s_nop 1
	v_add_f32_dpp v140, v140, v140 quad_perm:[1,0,3,2] row_mask:0xf bank_mask:0xf bound_ctrl:1
	s_nop 1
	v_add_f32_dpp v140, v140, v140 quad_perm:[2,3,0,1] row_mask:0xf bank_mask:0xf bound_ctrl:1
	s_nop 1
	v_add_f32_dpp v140, v140, v140 row_half_mirror row_mask:0xf bank_mask:0xf bound_ctrl:1
	v_fma_f32 v141, v140, s10, v15
	v_rsq_f32_e32 v141, v141
	s_nop 0
	v_mul_f32_e32 v112, v112, v141
	v_mul_f32_e32 v113, v113, v141
	v_mul_f32_e32 v114, v114, v141
	v_mul_f32_e32 v115, v115, v141
	v_mul_f32_e32 v116, v116, v141
	v_mul_f32_e32 v117, v117, v141
	v_mul_f32_e32 v118, v118, v141
	v_mul_f32_e32 v119, v119, v141
	v_mul_f32_e32 v112, v112, v24
	v_mul_f32_e32 v113, v113, v25
	v_mul_f32_e32 v114, v114, v26
	v_mul_f32_e32 v115, v115, v27
	v_mul_f32_e32 v116, v116, v28
	v_mul_f32_e32 v117, v117, v29
	v_mul_f32_e32 v118, v118, v30
	v_mul_f32_e32 v119, v119, v31
	v_mov_b32_dpp v120, v112 quad_perm:[1,0,3,2] row_mask:0xf bank_mask:0xf
	v_mov_b32_dpp v121, v113 quad_perm:[1,0,3,2] row_mask:0xf bank_mask:0xf
	v_mov_b32_dpp v122, v114 quad_perm:[1,0,3,2] row_mask:0xf bank_mask:0xf
	v_mov_b32_dpp v123, v115 quad_perm:[1,0,3,2] row_mask:0xf bank_mask:0xf
	v_mov_b32_dpp v124, v116 quad_perm:[1,0,3,2] row_mask:0xf bank_mask:0xf
	v_mov_b32_dpp v125, v117 quad_perm:[1,0,3,2] row_mask:0xf bank_mask:0xf
	v_mov_b32_dpp v126, v118 quad_perm:[1,0,3,2] row_mask:0xf bank_mask:0xf
	v_mov_b32_dpp v127, v119 quad_perm:[1,0,3,2] row_mask:0xf bank_mask:0xf
	v_mul_f32_e32 v128, s28, v112
	v_mul_f32_e32 v129, s29, v113
	v_mul_f32_e32 v130, s30, v114
	v_mul_f32_e32 v131, s31, v115
	v_mul_f32_e32 v132, s34, v116
	v_mul_f32_e32 v133, s35, v117
	v_mul_f32_e32 v134, s36, v118
	v_mul_f32_e32 v135, s37, v119
	v_fmac_f32_e32 v128, v32, v120
	v_fmac_f32_e32 v129, v33, v121
	v_fmac_f32_e32 v130, v34, v122
	v_fmac_f32_e32 v131, v35, v123
	v_fmac_f32_e32 v132, v36, v124
	v_fmac_f32_e32 v133, v37, v125
	v_fmac_f32_e32 v134, v38, v126
	v_fmac_f32_e32 v135, v39, v127
	v_cndmask_b32_e32 v112, v112, v128, vcc
	v_cndmask_b32_e32 v113, v113, v129, vcc
	v_cndmask_b32_e32 v114, v114, v130, vcc
	v_cndmask_b32_e32 v115, v115, v131, vcc
	v_cndmask_b32_e32 v116, v116, v132, vcc
	v_cndmask_b32_e32 v117, v117, v133, vcc
	v_cndmask_b32_e32 v118, v118, v134, vcc
	v_cndmask_b32_e32 v119, v119, v135, vcc
	v_cvt_pk_bf16_f32 v136, v112, v113
	v_cvt_pk_bf16_f32 v137, v114, v115
	v_cvt_pk_bf16_f32 v138, v116, v117
	v_cvt_pk_bf16_f32 v139, v118, v119
	v_cndmask_b32_e64 v136, v136, v84, s[18:19]
	v_cndmask_b32_e64 v137, v137, v85, s[18:19]
	v_cndmask_b32_e64 v138, v138, v86, s[18:19]
	v_cndmask_b32_e64 v139, v139, v87, s[18:19]
	global_store_dwordx4 v8, v[136:139], s[12:13]
	s_add_u32 s6, s6, 0x200000
	s_addc_u32 s7, s7, 0
	s_add_u32 s12, s12, 0x80000
	s_addc_u32 s13, s13, 0
	s_waitcnt vmcnt(14)
	v_readlane_b32 s28, v11, 40
	v_readlane_b32 s38, v12, 40
	v_readlane_b32 s29, v11, 41
	v_readlane_b32 s39, v12, 41
	v_readlane_b32 s30, v11, 42
	v_readlane_b32 s40, v12, 42
	v_readlane_b32 s31, v11, 43
	v_readlane_b32 s41, v12, 43
	v_readlane_b32 s34, v11, 44
	v_readlane_b32 s42, v12, 44
	v_readlane_b32 s35, v11, 45
	v_readlane_b32 s43, v12, 45
	v_readlane_b32 s36, v11, 46
	v_readlane_b32 s44, v12, 46
	v_readlane_b32 s37, v11, 47
	v_readlane_b32 s45, v12, 47
	v_mul_f32_e32 v32, s38, v10
	v_mul_f32_e32 v33, s39, v10
	v_mul_f32_e32 v34, s40, v10
	v_mul_f32_e32 v35, s41, v10
	v_mul_f32_e32 v36, s42, v10
	v_mul_f32_e32 v37, s43, v10
	v_mul_f32_e32 v38, s44, v10
	v_mul_f32_e32 v39, s45, v10
	v_lshlrev_b32_e32 v112, 16, v88
	v_and_b32_e32 v113, 0xffff0000, v88
	v_lshlrev_b32_e32 v114, 16, v89
	v_and_b32_e32 v115, 0xffff0000, v89
	v_lshlrev_b32_e32 v116, 16, v90
	v_and_b32_e32 v117, 0xffff0000, v90
	v_lshlrev_b32_e32 v118, 16, v91
	v_and_b32_e32 v119, 0xffff0000, v91
	v_mul_f32_e32 v140, v112, v112
	v_mul_f32_e32 v141, v113, v113
	v_fmac_f32_e32 v140, v114, v114
	v_fmac_f32_e32 v141, v115, v115
	v_fmac_f32_e32 v140, v116, v116
	v_fmac_f32_e32 v141, v117, v117
	v_fmac_f32_e32 v140, v118, v118
	v_fmac_f32_e32 v141, v119, v119
	v_add_f32_e32 v140, v140, v141
	s_nop 1
	v_add_f32_dpp v140, v140, v140 quad_perm:[1,0,3,2] row_mask:0xf bank_mask:0xf bound_ctrl:1
	s_nop 1
	v_add_f32_dpp v140, v140, v140 quad_perm:[2,3,0,1] row_mask:0xf bank_mask:0xf bound_ctrl:1
	s_nop 1
	v_add_f32_dpp v140, v140, v140 row_half_mirror row_mask:0xf bank_mask:0xf bound_ctrl:1
	v_fma_f32 v141, v140, s10, v15
	v_rsq_f32_e32 v141, v141
	s_nop 0
	v_mul_f32_e32 v112, v112, v141
	v_mul_f32_e32 v113, v113, v141
	v_mul_f32_e32 v114, v114, v141
	v_mul_f32_e32 v115, v115, v141
	v_mul_f32_e32 v116, v116, v141
	v_mul_f32_e32 v117, v117, v141
	v_mul_f32_e32 v118, v118, v141
	v_mul_f32_e32 v119, v119, v141
	v_mul_f32_e32 v112, v112, v16
	v_mul_f32_e32 v113, v113, v17
	v_mul_f32_e32 v114, v114, v18
	v_mul_f32_e32 v115, v115, v19
	v_mul_f32_e32 v116, v116, v20
	v_mul_f32_e32 v117, v117, v21
	v_mul_f32_e32 v118, v118, v22
	v_mul_f32_e32 v119, v119, v23
	v_mov_b32_dpp v120, v112 quad_perm:[1,0,3,2] row_mask:0xf bank_mask:0xf
	v_mov_b32_dpp v121, v113 quad_perm:[1,0,3,2] row_mask:0xf bank_mask:0xf
	v_mov_b32_dpp v122, v114 quad_perm:[1,0,3,2] row_mask:0xf bank_mask:0xf
	v_mov_b32_dpp v123, v115 quad_perm:[1,0,3,2] row_mask:0xf bank_mask:0xf
	v_mov_b32_dpp v124, v116 quad_perm:[1,0,3,2] row_mask:0xf bank_mask:0xf
	v_mov_b32_dpp v125, v117 quad_perm:[1,0,3,2] row_mask:0xf bank_mask:0xf
	v_mov_b32_dpp v126, v118 quad_perm:[1,0,3,2] row_mask:0xf bank_mask:0xf
	v_mov_b32_dpp v127, v119 quad_perm:[1,0,3,2] row_mask:0xf bank_mask:0xf
	v_mul_f32_e32 v128, s28, v112
	v_mul_f32_e32 v129, s29, v113
	v_mul_f32_e32 v130, s30, v114
	v_mul_f32_e32 v131, s31, v115
	v_mul_f32_e32 v132, s34, v116
	v_mul_f32_e32 v133, s35, v117
	v_mul_f32_e32 v134, s36, v118
	v_mul_f32_e32 v135, s37, v119
	v_fmac_f32_e32 v128, v32, v120
	v_fmac_f32_e32 v129, v33, v121
	v_fmac_f32_e32 v130, v34, v122
	v_fmac_f32_e32 v131, v35, v123
	v_fmac_f32_e32 v132, v36, v124
	v_fmac_f32_e32 v133, v37, v125
	v_fmac_f32_e32 v134, v38, v126
	v_fmac_f32_e32 v135, v39, v127
	v_cndmask_b32_e32 v112, v112, v128, vcc
	v_cndmask_b32_e32 v113, v113, v129, vcc
	v_cndmask_b32_e32 v114, v114, v130, vcc
	v_cndmask_b32_e32 v115, v115, v131, vcc
	v_cndmask_b32_e32 v116, v116, v132, vcc
	v_cndmask_b32_e32 v117, v117, v133, vcc
	v_cndmask_b32_e32 v118, v118, v134, vcc
	v_cndmask_b32_e32 v119, v119, v135, vcc
	v_mul_f32_e32 v112, 0x3e38aa3b, v112
	v_mul_f32_e32 v113, 0x3e38aa3b, v113
	v_mul_f32_e32 v114, 0x3e38aa3b, v114
	v_mul_f32_e32 v115, 0x3e38aa3b, v115
	v_mul_f32_e32 v116, 0x3e38aa3b, v116
	v_mul_f32_e32 v117, 0x3e38aa3b, v117
	v_mul_f32_e32 v118, 0x3e38aa3b, v118
	v_mul_f32_e32 v119, 0x3e38aa3b, v119
	v_cvt_pk_bf16_f32 v136, v112, v113
	v_cvt_pk_bf16_f32 v137, v114, v115
	v_cvt_pk_bf16_f32 v138, v116, v117
	v_cvt_pk_bf16_f32 v139, v118, v119
	global_store_dwordx4 v7, v[136:139], s[6:7]
	s_nop 1
	v_lshlrev_b32_e32 v112, 16, v92
	v_and_b32_e32 v113, 0xffff0000, v92
	v_lshlrev_b32_e32 v114, 16, v93
	v_and_b32_e32 v115, 0xffff0000, v93
	v_lshlrev_b32_e32 v116, 16, v94
	v_and_b32_e32 v117, 0xffff0000, v94
	v_lshlrev_b32_e32 v118, 16, v95
	v_and_b32_e32 v119, 0xffff0000, v95
	v_mul_f32_e32 v140, v112, v112
	v_mul_f32_e32 v141, v113, v113
	v_fmac_f32_e32 v140, v114, v114
	v_fmac_f32_e32 v141, v115, v115
	v_fmac_f32_e32 v140, v116, v116
	v_fmac_f32_e32 v141, v117, v117
	v_fmac_f32_e32 v140, v118, v118
	v_fmac_f32_e32 v141, v119, v119
	v_add_f32_e32 v140, v140, v141
	s_nop 1
	v_add_f32_dpp v140, v140, v140 quad_perm:[1,0,3,2] row_mask:0xf bank_mask:0xf bound_ctrl:1
	s_nop 1
	v_add_f32_dpp v140, v140, v140 quad_perm:[2,3,0,1] row_mask:0xf bank_mask:0xf bound_ctrl:1
	s_nop 1
	v_add_f32_dpp v140, v140, v140 row_half_mirror row_mask:0xf bank_mask:0xf bound_ctrl:1
	v_fma_f32 v141, v140, s10, v15
	v_rsq_f32_e32 v141, v141
	s_nop 0
	v_mul_f32_e32 v112, v112, v141
	v_mul_f32_e32 v113, v113, v141
	v_mul_f32_e32 v114, v114, v141
	v_mul_f32_e32 v115, v115, v141
	v_mul_f32_e32 v116, v116, v141
	v_mul_f32_e32 v117, v117, v141
	v_mul_f32_e32 v118, v118, v141
	v_mul_f32_e32 v119, v119, v141
	v_mul_f32_e32 v112, v112, v24
	v_mul_f32_e32 v113, v113, v25
	v_mul_f32_e32 v114, v114, v26
	v_mul_f32_e32 v115, v115, v27
	v_mul_f32_e32 v116, v116, v28
	v_mul_f32_e32 v117, v117, v29
	v_mul_f32_e32 v118, v118, v30
	v_mul_f32_e32 v119, v119, v31
	v_mov_b32_dpp v120, v112 quad_perm:[1,0,3,2] row_mask:0xf bank_mask:0xf
	v_mov_b32_dpp v121, v113 quad_perm:[1,0,3,2] row_mask:0xf bank_mask:0xf
	v_mov_b32_dpp v122, v114 quad_perm:[1,0,3,2] row_mask:0xf bank_mask:0xf
	v_mov_b32_dpp v123, v115 quad_perm:[1,0,3,2] row_mask:0xf bank_mask:0xf
	v_mov_b32_dpp v124, v116 quad_perm:[1,0,3,2] row_mask:0xf bank_mask:0xf
	v_mov_b32_dpp v125, v117 quad_perm:[1,0,3,2] row_mask:0xf bank_mask:0xf
	v_mov_b32_dpp v126, v118 quad_perm:[1,0,3,2] row_mask:0xf bank_mask:0xf
	v_mov_b32_dpp v127, v119 quad_perm:[1,0,3,2] row_mask:0xf bank_mask:0xf
	v_mul_f32_e32 v128, s28, v112
	v_mul_f32_e32 v129, s29, v113
	v_mul_f32_e32 v130, s30, v114
	v_mul_f32_e32 v131, s31, v115
	v_mul_f32_e32 v132, s34, v116
	v_mul_f32_e32 v133, s35, v117
	v_mul_f32_e32 v134, s36, v118
	v_mul_f32_e32 v135, s37, v119
	v_fmac_f32_e32 v128, v32, v120
	v_fmac_f32_e32 v129, v33, v121
	v_fmac_f32_e32 v130, v34, v122
	v_fmac_f32_e32 v131, v35, v123
	v_fmac_f32_e32 v132, v36, v124
	v_fmac_f32_e32 v133, v37, v125
	v_fmac_f32_e32 v134, v38, v126
	v_fmac_f32_e32 v135, v39, v127
	v_cndmask_b32_e32 v112, v112, v128, vcc
	v_cndmask_b32_e32 v113, v113, v129, vcc
	v_cndmask_b32_e32 v114, v114, v130, vcc
	v_cndmask_b32_e32 v115, v115, v131, vcc
	v_cndmask_b32_e32 v116, v116, v132, vcc
	v_cndmask_b32_e32 v117, v117, v133, vcc
	v_cndmask_b32_e32 v118, v118, v134, vcc
	v_cndmask_b32_e32 v119, v119, v135, vcc
	v_cvt_pk_bf16_f32 v136, v112, v113
	v_cvt_pk_bf16_f32 v137, v114, v115
	v_cvt_pk_bf16_f32 v138, v116, v117
	v_cvt_pk_bf16_f32 v139, v118, v119
	v_cndmask_b32_e64 v136, v136, v92, s[18:19]
	v_cndmask_b32_e64 v137, v137, v93, s[18:19]
	v_cndmask_b32_e64 v138, v138, v94, s[18:19]
	v_cndmask_b32_e64 v139, v139, v95, s[18:19]
	global_store_dwordx4 v8, v[136:139], s[12:13]
	s_add_u32 s6, s6, 0x200000
	s_addc_u32 s7, s7, 0
	s_add_u32 s12, s12, 0x80000
	s_addc_u32 s13, s13, 0
	s_waitcnt vmcnt(14)
	v_readlane_b32 s28, v11, 48
	v_readlane_b32 s38, v12, 48
	v_readlane_b32 s29, v11, 49
	v_readlane_b32 s39, v12, 49
	v_readlane_b32 s30, v11, 50
	v_readlane_b32 s40, v12, 50
	v_readlane_b32 s31, v11, 51
	v_readlane_b32 s41, v12, 51
	v_readlane_b32 s34, v11, 52
	v_readlane_b32 s42, v12, 52
	v_readlane_b32 s35, v11, 53
	v_readlane_b32 s43, v12, 53
	v_readlane_b32 s36, v11, 54
	v_readlane_b32 s44, v12, 54
	v_readlane_b32 s37, v11, 55
	v_readlane_b32 s45, v12, 55
	v_mul_f32_e32 v32, s38, v10
	v_mul_f32_e32 v33, s39, v10
	v_mul_f32_e32 v34, s40, v10
	v_mul_f32_e32 v35, s41, v10
	v_mul_f32_e32 v36, s42, v10
	v_mul_f32_e32 v37, s43, v10
	v_mul_f32_e32 v38, s44, v10
	v_mul_f32_e32 v39, s45, v10
	v_lshlrev_b32_e32 v112, 16, v96
	v_and_b32_e32 v113, 0xffff0000, v96
	v_lshlrev_b32_e32 v114, 16, v97
	v_and_b32_e32 v115, 0xffff0000, v97
	v_lshlrev_b32_e32 v116, 16, v98
	v_and_b32_e32 v117, 0xffff0000, v98
	v_lshlrev_b32_e32 v118, 16, v99
	v_and_b32_e32 v119, 0xffff0000, v99
	v_mul_f32_e32 v140, v112, v112
	v_mul_f32_e32 v141, v113, v113
	v_fmac_f32_e32 v140, v114, v114
	v_fmac_f32_e32 v141, v115, v115
	v_fmac_f32_e32 v140, v116, v116
	v_fmac_f32_e32 v141, v117, v117
	v_fmac_f32_e32 v140, v118, v118
	v_fmac_f32_e32 v141, v119, v119
	v_add_f32_e32 v140, v140, v141
	s_nop 1
	v_add_f32_dpp v140, v140, v140 quad_perm:[1,0,3,2] row_mask:0xf bank_mask:0xf bound_ctrl:1
	s_nop 1
	v_add_f32_dpp v140, v140, v140 quad_perm:[2,3,0,1] row_mask:0xf bank_mask:0xf bound_ctrl:1
	s_nop 1
	v_add_f32_dpp v140, v140, v140 row_half_mirror row_mask:0xf bank_mask:0xf bound_ctrl:1
	v_fma_f32 v141, v140, s10, v15
	v_rsq_f32_e32 v141, v141
	s_nop 0
	v_mul_f32_e32 v112, v112, v141
	v_mul_f32_e32 v113, v113, v141
	v_mul_f32_e32 v114, v114, v141
	v_mul_f32_e32 v115, v115, v141
	v_mul_f32_e32 v116, v116, v141
	v_mul_f32_e32 v117, v117, v141
	v_mul_f32_e32 v118, v118, v141
	v_mul_f32_e32 v119, v119, v141
	v_mul_f32_e32 v112, v112, v16
	v_mul_f32_e32 v113, v113, v17
	v_mul_f32_e32 v114, v114, v18
	v_mul_f32_e32 v115, v115, v19
	v_mul_f32_e32 v116, v116, v20
	v_mul_f32_e32 v117, v117, v21
	v_mul_f32_e32 v118, v118, v22
	v_mul_f32_e32 v119, v119, v23
	v_mov_b32_dpp v120, v112 quad_perm:[1,0,3,2] row_mask:0xf bank_mask:0xf
	v_mov_b32_dpp v121, v113 quad_perm:[1,0,3,2] row_mask:0xf bank_mask:0xf
	v_mov_b32_dpp v122, v114 quad_perm:[1,0,3,2] row_mask:0xf bank_mask:0xf
	v_mov_b32_dpp v123, v115 quad_perm:[1,0,3,2] row_mask:0xf bank_mask:0xf
	v_mov_b32_dpp v124, v116 quad_perm:[1,0,3,2] row_mask:0xf bank_mask:0xf
	v_mov_b32_dpp v125, v117 quad_perm:[1,0,3,2] row_mask:0xf bank_mask:0xf
	v_mov_b32_dpp v126, v118 quad_perm:[1,0,3,2] row_mask:0xf bank_mask:0xf
	v_mov_b32_dpp v127, v119 quad_perm:[1,0,3,2] row_mask:0xf bank_mask:0xf
	v_mul_f32_e32 v128, s28, v112
	v_mul_f32_e32 v129, s29, v113
	v_mul_f32_e32 v130, s30, v114
	v_mul_f32_e32 v131, s31, v115
	v_mul_f32_e32 v132, s34, v116
	v_mul_f32_e32 v133, s35, v117
	v_mul_f32_e32 v134, s36, v118
	v_mul_f32_e32 v135, s37, v119
	v_fmac_f32_e32 v128, v32, v120
	v_fmac_f32_e32 v129, v33, v121
	v_fmac_f32_e32 v130, v34, v122
	v_fmac_f32_e32 v131, v35, v123
	v_fmac_f32_e32 v132, v36, v124
	v_fmac_f32_e32 v133, v37, v125
	v_fmac_f32_e32 v134, v38, v126
	v_fmac_f32_e32 v135, v39, v127
	v_cndmask_b32_e32 v112, v112, v128, vcc
	v_cndmask_b32_e32 v113, v113, v129, vcc
	v_cndmask_b32_e32 v114, v114, v130, vcc
	v_cndmask_b32_e32 v115, v115, v131, vcc
	v_cndmask_b32_e32 v116, v116, v132, vcc
	v_cndmask_b32_e32 v117, v117, v133, vcc
	v_cndmask_b32_e32 v118, v118, v134, vcc
	v_cndmask_b32_e32 v119, v119, v135, vcc
	v_mul_f32_e32 v112, 0x3e38aa3b, v112
	v_mul_f32_e32 v113, 0x3e38aa3b, v113
	v_mul_f32_e32 v114, 0x3e38aa3b, v114
	v_mul_f32_e32 v115, 0x3e38aa3b, v115
	v_mul_f32_e32 v116, 0x3e38aa3b, v116
	v_mul_f32_e32 v117, 0x3e38aa3b, v117
	v_mul_f32_e32 v118, 0x3e38aa3b, v118
	v_mul_f32_e32 v119, 0x3e38aa3b, v119
	v_cvt_pk_bf16_f32 v136, v112, v113
	v_cvt_pk_bf16_f32 v137, v114, v115
	v_cvt_pk_bf16_f32 v138, v116, v117
	v_cvt_pk_bf16_f32 v139, v118, v119
	global_store_dwordx4 v7, v[136:139], s[6:7]
	s_nop 1
	v_lshlrev_b32_e32 v112, 16, v100
	v_and_b32_e32 v113, 0xffff0000, v100
	v_lshlrev_b32_e32 v114, 16, v101
	v_and_b32_e32 v115, 0xffff0000, v101
	v_lshlrev_b32_e32 v116, 16, v102
	v_and_b32_e32 v117, 0xffff0000, v102
	v_lshlrev_b32_e32 v118, 16, v103
	v_and_b32_e32 v119, 0xffff0000, v103
	v_mul_f32_e32 v140, v112, v112
	v_mul_f32_e32 v141, v113, v113
	v_fmac_f32_e32 v140, v114, v114
	v_fmac_f32_e32 v141, v115, v115
	v_fmac_f32_e32 v140, v116, v116
	v_fmac_f32_e32 v141, v117, v117
	v_fmac_f32_e32 v140, v118, v118
	v_fmac_f32_e32 v141, v119, v119
	v_add_f32_e32 v140, v140, v141
	s_nop 1
	v_add_f32_dpp v140, v140, v140 quad_perm:[1,0,3,2] row_mask:0xf bank_mask:0xf bound_ctrl:1
	s_nop 1
	v_add_f32_dpp v140, v140, v140 quad_perm:[2,3,0,1] row_mask:0xf bank_mask:0xf bound_ctrl:1
	s_nop 1
	v_add_f32_dpp v140, v140, v140 row_half_mirror row_mask:0xf bank_mask:0xf bound_ctrl:1
	v_fma_f32 v141, v140, s10, v15
	v_rsq_f32_e32 v141, v141
	s_nop 0
	v_mul_f32_e32 v112, v112, v141
	v_mul_f32_e32 v113, v113, v141
	v_mul_f32_e32 v114, v114, v141
	v_mul_f32_e32 v115, v115, v141
	v_mul_f32_e32 v116, v116, v141
	v_mul_f32_e32 v117, v117, v141
	v_mul_f32_e32 v118, v118, v141
	v_mul_f32_e32 v119, v119, v141
	v_mul_f32_e32 v112, v112, v24
	v_mul_f32_e32 v113, v113, v25
	v_mul_f32_e32 v114, v114, v26
	v_mul_f32_e32 v115, v115, v27
	v_mul_f32_e32 v116, v116, v28
	v_mul_f32_e32 v117, v117, v29
	v_mul_f32_e32 v118, v118, v30
	v_mul_f32_e32 v119, v119, v31
	v_mov_b32_dpp v120, v112 quad_perm:[1,0,3,2] row_mask:0xf bank_mask:0xf
	v_mov_b32_dpp v121, v113 quad_perm:[1,0,3,2] row_mask:0xf bank_mask:0xf
	v_mov_b32_dpp v122, v114 quad_perm:[1,0,3,2] row_mask:0xf bank_mask:0xf
	v_mov_b32_dpp v123, v115 quad_perm:[1,0,3,2] row_mask:0xf bank_mask:0xf
	v_mov_b32_dpp v124, v116 quad_perm:[1,0,3,2] row_mask:0xf bank_mask:0xf
	v_mov_b32_dpp v125, v117 quad_perm:[1,0,3,2] row_mask:0xf bank_mask:0xf
	v_mov_b32_dpp v126, v118 quad_perm:[1,0,3,2] row_mask:0xf bank_mask:0xf
	v_mov_b32_dpp v127, v119 quad_perm:[1,0,3,2] row_mask:0xf bank_mask:0xf
	v_mul_f32_e32 v128, s28, v112
	v_mul_f32_e32 v129, s29, v113
	v_mul_f32_e32 v130, s30, v114
	v_mul_f32_e32 v131, s31, v115
	v_mul_f32_e32 v132, s34, v116
	v_mul_f32_e32 v133, s35, v117
	v_mul_f32_e32 v134, s36, v118
	v_mul_f32_e32 v135, s37, v119
	v_fmac_f32_e32 v128, v32, v120
	v_fmac_f32_e32 v129, v33, v121
	v_fmac_f32_e32 v130, v34, v122
	v_fmac_f32_e32 v131, v35, v123
	v_fmac_f32_e32 v132, v36, v124
	v_fmac_f32_e32 v133, v37, v125
	v_fmac_f32_e32 v134, v38, v126
	v_fmac_f32_e32 v135, v39, v127
	v_cndmask_b32_e32 v112, v112, v128, vcc
	v_cndmask_b32_e32 v113, v113, v129, vcc
	v_cndmask_b32_e32 v114, v114, v130, vcc
	v_cndmask_b32_e32 v115, v115, v131, vcc
	v_cndmask_b32_e32 v116, v116, v132, vcc
	v_cndmask_b32_e32 v117, v117, v133, vcc
	v_cndmask_b32_e32 v118, v118, v134, vcc
	v_cndmask_b32_e32 v119, v119, v135, vcc
	v_cvt_pk_bf16_f32 v136, v112, v113
	v_cvt_pk_bf16_f32 v137, v114, v115
	v_cvt_pk_bf16_f32 v138, v116, v117
	v_cvt_pk_bf16_f32 v139, v118, v119
	v_cndmask_b32_e64 v136, v136, v100, s[18:19]
	v_cndmask_b32_e64 v137, v137, v101, s[18:19]
	v_cndmask_b32_e64 v138, v138, v102, s[18:19]
	v_cndmask_b32_e64 v139, v139, v103, s[18:19]
	global_store_dwordx4 v8, v[136:139], s[12:13]
	s_add_u32 s6, s6, 0x200000
	s_addc_u32 s7, s7, 0
	s_add_u32 s12, s12, 0x80000
	s_addc_u32 s13, s13, 0
	s_waitcnt vmcnt(14)
	v_readlane_b32 s28, v11, 56
	v_readlane_b32 s38, v12, 56
	v_readlane_b32 s29, v11, 57
	v_readlane_b32 s39, v12, 57
	v_readlane_b32 s30, v11, 58
	v_readlane_b32 s40, v12, 58
	v_readlane_b32 s31, v11, 59
	v_readlane_b32 s41, v12, 59
	v_readlane_b32 s34, v11, 60
	v_readlane_b32 s42, v12, 60
	v_readlane_b32 s35, v11, 61
	v_readlane_b32 s43, v12, 61
	v_readlane_b32 s36, v11, 62
	v_readlane_b32 s44, v12, 62
	v_readlane_b32 s37, v11, 63
	v_readlane_b32 s45, v12, 63
	v_mul_f32_e32 v32, s38, v10
	v_mul_f32_e32 v33, s39, v10
	v_mul_f32_e32 v34, s40, v10
	v_mul_f32_e32 v35, s41, v10
	v_mul_f32_e32 v36, s42, v10
	v_mul_f32_e32 v37, s43, v10
	v_mul_f32_e32 v38, s44, v10
	v_mul_f32_e32 v39, s45, v10
	v_lshlrev_b32_e32 v112, 16, v104
	v_and_b32_e32 v113, 0xffff0000, v104
	v_lshlrev_b32_e32 v114, 16, v105
	v_and_b32_e32 v115, 0xffff0000, v105
	v_lshlrev_b32_e32 v116, 16, v106
	v_and_b32_e32 v117, 0xffff0000, v106
	v_lshlrev_b32_e32 v118, 16, v107
	v_and_b32_e32 v119, 0xffff0000, v107
	v_mul_f32_e32 v140, v112, v112
	v_mul_f32_e32 v141, v113, v113
	v_fmac_f32_e32 v140, v114, v114
	v_fmac_f32_e32 v141, v115, v115
	v_fmac_f32_e32 v140, v116, v116
	v_fmac_f32_e32 v141, v117, v117
	v_fmac_f32_e32 v140, v118, v118
	v_fmac_f32_e32 v141, v119, v119
	v_add_f32_e32 v140, v140, v141
	s_nop 1
	v_add_f32_dpp v140, v140, v140 quad_perm:[1,0,3,2] row_mask:0xf bank_mask:0xf bound_ctrl:1
	s_nop 1
	v_add_f32_dpp v140, v140, v140 quad_perm:[2,3,0,1] row_mask:0xf bank_mask:0xf bound_ctrl:1
	s_nop 1
	v_add_f32_dpp v140, v140, v140 row_half_mirror row_mask:0xf bank_mask:0xf bound_ctrl:1
	v_fma_f32 v141, v140, s10, v15
	v_rsq_f32_e32 v141, v141
	s_nop 0
	v_mul_f32_e32 v112, v112, v141
	v_mul_f32_e32 v113, v113, v141
	v_mul_f32_e32 v114, v114, v141
	v_mul_f32_e32 v115, v115, v141
	v_mul_f32_e32 v116, v116, v141
	v_mul_f32_e32 v117, v117, v141
	v_mul_f32_e32 v118, v118, v141
	v_mul_f32_e32 v119, v119, v141
	v_mul_f32_e32 v112, v112, v16
	v_mul_f32_e32 v113, v113, v17
	v_mul_f32_e32 v114, v114, v18
	v_mul_f32_e32 v115, v115, v19
	v_mul_f32_e32 v116, v116, v20
	v_mul_f32_e32 v117, v117, v21
	v_mul_f32_e32 v118, v118, v22
	v_mul_f32_e32 v119, v119, v23
	v_mov_b32_dpp v120, v112 quad_perm:[1,0,3,2] row_mask:0xf bank_mask:0xf
	v_mov_b32_dpp v121, v113 quad_perm:[1,0,3,2] row_mask:0xf bank_mask:0xf
	v_mov_b32_dpp v122, v114 quad_perm:[1,0,3,2] row_mask:0xf bank_mask:0xf
	v_mov_b32_dpp v123, v115 quad_perm:[1,0,3,2] row_mask:0xf bank_mask:0xf
	v_mov_b32_dpp v124, v116 quad_perm:[1,0,3,2] row_mask:0xf bank_mask:0xf
	v_mov_b32_dpp v125, v117 quad_perm:[1,0,3,2] row_mask:0xf bank_mask:0xf
	v_mov_b32_dpp v126, v118 quad_perm:[1,0,3,2] row_mask:0xf bank_mask:0xf
	v_mov_b32_dpp v127, v119 quad_perm:[1,0,3,2] row_mask:0xf bank_mask:0xf
	v_mul_f32_e32 v128, s28, v112
	v_mul_f32_e32 v129, s29, v113
	v_mul_f32_e32 v130, s30, v114
	v_mul_f32_e32 v131, s31, v115
	v_mul_f32_e32 v132, s34, v116
	v_mul_f32_e32 v133, s35, v117
	v_mul_f32_e32 v134, s36, v118
	v_mul_f32_e32 v135, s37, v119
	v_fmac_f32_e32 v128, v32, v120
	v_fmac_f32_e32 v129, v33, v121
	v_fmac_f32_e32 v130, v34, v122
	v_fmac_f32_e32 v131, v35, v123
	v_fmac_f32_e32 v132, v36, v124
	v_fmac_f32_e32 v133, v37, v125
	v_fmac_f32_e32 v134, v38, v126
	v_fmac_f32_e32 v135, v39, v127
	v_cndmask_b32_e32 v112, v112, v128, vcc
	v_cndmask_b32_e32 v113, v113, v129, vcc
	v_cndmask_b32_e32 v114, v114, v130, vcc
	v_cndmask_b32_e32 v115, v115, v131, vcc
	v_cndmask_b32_e32 v116, v116, v132, vcc
	v_cndmask_b32_e32 v117, v117, v133, vcc
	v_cndmask_b32_e32 v118, v118, v134, vcc
	v_cndmask_b32_e32 v119, v119, v135, vcc
	v_mul_f32_e32 v112, 0x3e38aa3b, v112
	v_mul_f32_e32 v113, 0x3e38aa3b, v113
	v_mul_f32_e32 v114, 0x3e38aa3b, v114
	v_mul_f32_e32 v115, 0x3e38aa3b, v115
	v_mul_f32_e32 v116, 0x3e38aa3b, v116
	v_mul_f32_e32 v117, 0x3e38aa3b, v117
	v_mul_f32_e32 v118, 0x3e38aa3b, v118
	v_mul_f32_e32 v119, 0x3e38aa3b, v119
	v_cvt_pk_bf16_f32 v136, v112, v113
	v_cvt_pk_bf16_f32 v137, v114, v115
	v_cvt_pk_bf16_f32 v138, v116, v117
	v_cvt_pk_bf16_f32 v139, v118, v119
	global_store_dwordx4 v7, v[136:139], s[6:7]
	s_nop 1
	v_lshlrev_b32_e32 v112, 16, v108
	v_and_b32_e32 v113, 0xffff0000, v108
	v_lshlrev_b32_e32 v114, 16, v109
	v_and_b32_e32 v115, 0xffff0000, v109
	v_lshlrev_b32_e32 v116, 16, v110
	v_and_b32_e32 v117, 0xffff0000, v110
	v_lshlrev_b32_e32 v118, 16, v111
	v_and_b32_e32 v119, 0xffff0000, v111
	v_mul_f32_e32 v140, v112, v112
	v_mul_f32_e32 v141, v113, v113
	v_fmac_f32_e32 v140, v114, v114
	v_fmac_f32_e32 v141, v115, v115
	v_fmac_f32_e32 v140, v116, v116
	v_fmac_f32_e32 v141, v117, v117
	v_fmac_f32_e32 v140, v118, v118
	v_fmac_f32_e32 v141, v119, v119
	v_add_f32_e32 v140, v140, v141
	s_nop 1
	v_add_f32_dpp v140, v140, v140 quad_perm:[1,0,3,2] row_mask:0xf bank_mask:0xf bound_ctrl:1
	s_nop 1
	v_add_f32_dpp v140, v140, v140 quad_perm:[2,3,0,1] row_mask:0xf bank_mask:0xf bound_ctrl:1
	s_nop 1
	v_add_f32_dpp v140, v140, v140 row_half_mirror row_mask:0xf bank_mask:0xf bound_ctrl:1
	v_fma_f32 v141, v140, s10, v15
	v_rsq_f32_e32 v141, v141
	s_nop 0
	v_mul_f32_e32 v112, v112, v141
	v_mul_f32_e32 v113, v113, v141
	v_mul_f32_e32 v114, v114, v141
	v_mul_f32_e32 v115, v115, v141
	v_mul_f32_e32 v116, v116, v141
	v_mul_f32_e32 v117, v117, v141
	v_mul_f32_e32 v118, v118, v141
	v_mul_f32_e32 v119, v119, v141
	v_mul_f32_e32 v112, v112, v24
	v_mul_f32_e32 v113, v113, v25
	v_mul_f32_e32 v114, v114, v26
	v_mul_f32_e32 v115, v115, v27
	v_mul_f32_e32 v116, v116, v28
	v_mul_f32_e32 v117, v117, v29
	v_mul_f32_e32 v118, v118, v30
	v_mul_f32_e32 v119, v119, v31
	v_mov_b32_dpp v120, v112 quad_perm:[1,0,3,2] row_mask:0xf bank_mask:0xf
	v_mov_b32_dpp v121, v113 quad_perm:[1,0,3,2] row_mask:0xf bank_mask:0xf
	v_mov_b32_dpp v122, v114 quad_perm:[1,0,3,2] row_mask:0xf bank_mask:0xf
	v_mov_b32_dpp v123, v115 quad_perm:[1,0,3,2] row_mask:0xf bank_mask:0xf
	v_mov_b32_dpp v124, v116 quad_perm:[1,0,3,2] row_mask:0xf bank_mask:0xf
	v_mov_b32_dpp v125, v117 quad_perm:[1,0,3,2] row_mask:0xf bank_mask:0xf
	v_mov_b32_dpp v126, v118 quad_perm:[1,0,3,2] row_mask:0xf bank_mask:0xf
	v_mov_b32_dpp v127, v119 quad_perm:[1,0,3,2] row_mask:0xf bank_mask:0xf
	v_mul_f32_e32 v128, s28, v112
	v_mul_f32_e32 v129, s29, v113
	v_mul_f32_e32 v130, s30, v114
	v_mul_f32_e32 v131, s31, v115
	v_mul_f32_e32 v132, s34, v116
	v_mul_f32_e32 v133, s35, v117
	v_mul_f32_e32 v134, s36, v118
	v_mul_f32_e32 v135, s37, v119
	v_fmac_f32_e32 v128, v32, v120
	v_fmac_f32_e32 v129, v33, v121
	v_fmac_f32_e32 v130, v34, v122
	v_fmac_f32_e32 v131, v35, v123
	v_fmac_f32_e32 v132, v36, v124
	v_fmac_f32_e32 v133, v37, v125
	v_fmac_f32_e32 v134, v38, v126
	v_fmac_f32_e32 v135, v39, v127
	v_cndmask_b32_e32 v112, v112, v128, vcc
	v_cndmask_b32_e32 v113, v113, v129, vcc
	v_cndmask_b32_e32 v114, v114, v130, vcc
	v_cndmask_b32_e32 v115, v115, v131, vcc
	v_cndmask_b32_e32 v116, v116, v132, vcc
	v_cndmask_b32_e32 v117, v117, v133, vcc
	v_cndmask_b32_e32 v118, v118, v134, vcc
	v_cndmask_b32_e32 v119, v119, v135, vcc
	v_cvt_pk_bf16_f32 v136, v112, v113
	v_cvt_pk_bf16_f32 v137, v114, v115
	v_cvt_pk_bf16_f32 v138, v116, v117
	v_cvt_pk_bf16_f32 v139, v118, v119
	v_cndmask_b32_e64 v136, v136, v108, s[18:19]
	v_cndmask_b32_e64 v137, v137, v109, s[18:19]
	v_cndmask_b32_e64 v138, v138, v110, s[18:19]
	v_cndmask_b32_e64 v139, v139, v111, s[18:19]
	global_store_dwordx4 v8, v[136:139], s[12:13]
	s_add_u32 s6, s6, 0x200000
	s_addc_u32 s7, s7, 0
	s_add_u32 s12, s12, 0x80000
	s_addc_u32 s13, s13, 0
	s_branch .LBB0_278
	s_nop 0
	s_nop 0
	s_nop 0
	s_nop 0
	s_nop 0
	s_nop 0
	s_nop 0
	s_nop 0
	s_nop 0
	s_nop 0
	s_nop 0
	s_nop 0
	s_nop 0
	s_nop 0
	s_nop 0
	s_nop 0
	s_nop 0
	s_nop 0
	s_nop 0
	s_nop 0
	s_nop 0
	s_nop 0
	s_nop 0
	s_nop 0
	s_nop 0
	s_nop 0
	s_nop 0
	s_nop 0
	s_nop 0
	s_nop 0
	s_nop 0
	s_nop 0
	s_nop 0
	s_nop 0
	s_nop 0
	s_nop 0
	s_nop 0
	s_nop 0
	s_nop 0
	s_nop 0
	s_nop 0
	s_nop 0
	s_nop 0
	s_nop 0
	s_nop 0
	s_nop 0
	s_nop 0
	s_nop 0
	s_nop 0
	s_nop 0
	s_nop 0
	s_nop 0
	s_nop 0
	s_nop 0
	s_nop 0
	s_nop 0
	s_nop 0
	s_nop 0
	s_nop 0
	s_nop 0
	s_nop 0
	s_nop 0
	s_nop 0
	s_nop 0
	s_nop 0
	s_nop 0
	s_nop 0
	s_nop 0
	s_nop 0
	s_nop 0
	s_nop 0
	s_nop 0
	s_nop 0
	s_nop 0
	s_nop 0
	s_nop 0
	s_nop 0
	s_nop 0
	s_nop 0
	s_nop 0
	s_nop 0
	s_nop 0
	s_nop 0
	s_nop 0
	s_nop 0
	s_nop 0
	s_nop 0
	s_nop 0
	s_nop 0
	s_nop 0
	s_nop 0
	s_nop 0
	s_nop 0
	s_nop 0
	s_nop 0
	s_nop 0
	s_nop 0
	s_nop 0
	s_nop 0
	s_nop 0
	s_nop 0
	s_nop 0
	s_nop 0
	s_nop 0
	s_nop 0
	s_nop 0
	s_nop 0
	s_nop 0
	s_nop 0
	s_nop 0
	s_nop 0
	s_nop 0
	s_nop 0
	s_nop 0
	s_nop 0
	s_nop 0
	s_nop 0
	s_nop 0
	s_nop 0
	s_nop 0
	s_nop 0
	s_nop 0
	s_nop 0
	s_nop 0
	s_nop 0
	s_nop 0
	s_nop 0
	s_nop 0
	s_nop 0
	s_nop 0
	s_nop 0
	s_nop 0
	s_nop 0
	s_nop 0
	s_nop 0
	s_nop 0
	s_nop 0
	s_nop 0
	s_nop 0
	s_nop 0
	s_nop 0
	s_nop 0
	s_nop 0
	s_nop 0
	s_nop 0
	s_nop 0
	s_nop 0
	s_nop 0
	s_nop 0
	s_nop 0
	s_nop 0
	s_nop 0
	s_nop 0
	s_nop 0
	s_nop 0
	s_nop 0
	s_nop 0
	s_nop 0
	s_nop 0
	s_nop 0
	s_nop 0
	s_nop 0
	s_nop 0
	s_nop 0
	s_nop 0
	s_nop 0
	s_nop 0
	s_nop 0
	s_nop 0
	s_nop 0
	s_nop 0
	s_nop 0
	s_nop 0
	s_nop 0
	s_nop 0
	s_nop 0
	s_nop 0
	s_nop 0
	s_nop 0
	s_nop 0
	s_nop 0
	s_nop 0
	s_nop 0
	s_nop 0
	s_nop 0
	s_nop 0
	s_nop 0
	s_nop 0
	s_nop 0
	s_nop 0
	s_nop 0
	s_nop 0
	s_nop 0
	s_nop 0
	s_nop 0
	s_nop 0
	s_nop 0
	s_nop 0
	s_nop 0
	s_nop 0
	s_nop 0
	s_nop 0
	s_nop 0
	s_nop 0
	s_nop 0
	s_nop 0
	s_nop 0
	s_nop 0
	s_nop 0
	s_nop 0
	s_nop 0
	s_nop 0
	s_nop 0
	s_nop 0
	s_nop 0
	s_nop 0
	s_nop 0
	s_nop 0
	s_nop 0
	s_nop 0
	s_nop 0
	s_nop 0
	s_nop 0
	s_nop 0
	s_nop 0
	s_nop 0
	s_nop 0
	s_nop 0
	s_nop 0
	s_nop 0
	s_nop 0
	s_nop 0
	s_nop 0
	s_nop 0
	s_nop 0
	s_nop 0
	s_nop 0
	s_nop 0
	s_nop 0
	s_nop 0
	s_nop 0
	s_nop 0
	s_nop 0
	s_nop 0
	s_nop 0
	s_nop 0
	s_nop 0
	s_nop 0
	s_nop 0
	s_nop 0
	s_nop 0
	s_nop 0
	s_nop 0
	s_nop 0
	s_nop 0
	s_nop 0
	s_nop 0
	s_nop 0
	s_nop 0
	s_nop 0
	s_nop 0
	s_nop 0
	s_nop 0
	s_nop 0
	s_nop 0
	s_nop 0
	s_nop 0

.LBB0_364:
	s_sext_i32_i8 s3, s4
	s_lshl_b32 s2, s2, 3
	s_add_i32 s6, s2, s3
	s_add_u32 s49, s1, 0x2000000
	s_addc_u32 s51, s5, 0
	s_mov_b64 s[4:5], 0x80
	s_add_i32 m0, s45, 0x18000
	v_lshl_add_u64 v[14:15], v[14:15], 0, s[4:5]
	s_waitcnt vmcnt(2)
	s_barrier
	global_load_lds_dwordx4 v[14:15], off
	v_lshl_add_u64 v[12:13], v[12:13], 0, s[4:5]
	s_add_i32 m0, s45, 0x1a000
	s_add_i32 s52, s45, 0x8000
	s_add_i32 s53, s45, 0xa000
	global_load_lds_dwordx4 v[12:13], off
	v_lshl_add_u64 v[8:9], v[8:9], 0, s[4:5]
	s_mov_b32 m0, s52
	s_add_u32 s2, s38, 0x80080
	global_load_lds_dwordx4 v[8:9], off
	v_lshl_add_u64 v[8:9], v[10:11], 0, s[4:5]
	s_mov_b32 m0, s53
	s_addc_u32 s3, s39, 0
	global_load_lds_dwordx4 v[8:9], off
	s_add_i32 m0, s45, 0x1c000
	s_nop 0
	global_load_lds_dwordx4 v4, s[2:3]
	v_lshl_add_u64 v[8:9], s[2:3], 0, v[0:1]
	s_add_i32 m0, s45, 0x1e000
	s_sext_i32_i8 s7, s0
	global_load_lds_dwordx4 v[8:9], off
	v_and_b32_e32 v8, 15, v16
	v_readlane_b32 s0, v247, 6
	v_and_b32_e32 v11, 48, v16
	v_lshrrev_b32_e32 v9, 6, v16
	v_or_b32_e32 v14, s0, v8
	v_lshlrev_b32_e32 v10, 6, v14
	s_movk_i32 s0, 0x3c0
	v_and_or_b32 v10, v10, s0, v11
	v_readlane_b32 s0, v247, 8
	v_lshlrev_b32_e32 v13, 2, v14
	v_and_b32_e32 v13, 32, v13
	v_lshl_add_u32 v12, v9, 10, s0
	v_bitop3_b32 v13, v10, v12, v13 bitop3:0xde
	v_readlane_b32 s0, v247, 10
	v_lshlrev_b32_e32 v10, 2, v16
	v_lshl_or_b32 v8, v8, 6, v11
	v_add_lshl_u32 v9, v9, s0, 10
	v_and_b32_e32 v10, 32, v10
	v_bitop3_b32 v15, v8, v9, v10 bitop3:0xde
	v_lshrrev_b32_e32 v8, 2, v16
	s_waitcnt vmcnt(6)
	v_and_b32_e32 v8, 28, v8
	v_readlane_b32 s0, v247, 9
	s_add_i32 s57, 0, 0x10000
	s_add_i32 s58, 0, 0x14000
	v_add_u32_e32 v12, s0, v8
	s_ashr_i32 s54, s76, 31
	s_mov_b32 s55, s76
	s_add_i32 s56, s80, s76
	v_mov_b64_e32 v[8:9], 0x80
	v_mov_b64_e32 v[10:11], 0x7f
	v_add_u32_e32 v16, s57, v15
	v_add_u32_e32 v17, s58, v15
	v_add_u32_e32 v18, 0, v13
	s_mov_b64 s[8:9], 0x100
	s_mov_b64 s[10:11], 0x180
	v_lshlrev_b32_e32 v12, 2, v12
	v_mov_b32_e32 v13, v5
	s_mov_b64 s[12:13], 0xc000
	s_mov_b64 s[14:15], 0x20000
	s_mov_b32 s59, 0x20000
	s_mov_b64 s[16:17], 0x24000
	s_mov_b32 s60, 0x24000
	s_mov_b64 s[18:19], 0x28000
	s_mov_b32 s61, 0x28000
	s_mov_b64 s[20:21], 0x2c000
	s_mov_b64 s[24:25], s[80:81]
	s_barrier
	s_branch .LBB0_366
.LBB0_365:
	ds_read_b128 v[20:23], v16
	ds_read_b128 v[24:27], v16 offset:1024
	ds_read_b128 v[28:31], v16 offset:2048
	ds_read_b128 v[32:35], v16 offset:3072
	ds_read_b128 v[36:39], v17
	ds_read_b128 v[40:43], v17 offset:1024
	ds_read_b128 v[44:47], v17 offset:2048
	ds_read_b128 v[48:51], v17 offset:3072
	s_add_u32 s30, s33, s26
	s_addc_u32 s31, s42, s27
	s_and_b64 s[34:35], s[2:3], exec
	s_cselect_b32 s41, s31, s37
	s_cselect_b32 s40, s30, s36
	s_add_u32 s34, s43, s28
	s_addc_u32 s35, s44, s29
	s_and_b64 s[2:3], s[2:3], exec
	s_cselect_b32 s3, s35, s39
	s_cselect_b32 s2, s34, s38
	s_add_u32 s64, s36, 0x40080
	s_addc_u32 s65, s37, 0
	s_add_i32 s70, s45, 0xc000
	s_mov_b32 m0, s70
	ds_read_b128 v[52:55], v18
	ds_read_b128 v[56:59], v18 offset:1024
	ds_read_b128 v[60:63], v18 offset:2048
	ds_read_b128 v[64:67], v18 offset:3072
	ds_read_b128 v[68:71], v18 offset:4096
	ds_read_b128 v[72:75], v18 offset:5120
	ds_read_b128 v[76:79], v18 offset:6144
	ds_read_b128 v[80:83], v18 offset:7168
	global_load_lds_dwordx4 v6, s[64:65]
	v_lshl_add_u64 v[84:85], s[64:65], 0, v[2:3]
	s_add_i32 s64, s45, 0xe000
	s_mov_b32 m0, s64
	s_nop 0
	global_load_lds_dwordx4 v[84:85], off
	s_waitcnt vmcnt(8)
	s_waitcnt lgkmcnt(0)
	s_barrier
	s_setprio 1
	s_waitcnt lgkmcnt(0)
	v_mfma_f32_16x16x32_bf16 v[84:87], v[20:23], v[52:55], 0
	v_mfma_f32_16x16x32_bf16 v[88:91], v[28:31], v[52:55], 0
	v_mfma_f32_16x16x32_bf16 v[92:95], v[20:23], v[60:63], 0
	v_mfma_f32_16x16x32_bf16 v[96:99], v[28:31], v[60:63], 0
	v_mfma_f32_16x16x32_bf16 v[100:103], v[20:23], v[68:71], 0
	v_mfma_f32_16x16x32_bf16 v[104:107], v[28:31], v[68:71], 0
	v_mfma_f32_16x16x32_bf16 v[108:111], v[20:23], v[76:79], 0
	v_mfma_f32_16x16x32_bf16 v[112:115], v[28:31], v[76:79], 0
	v_mfma_f32_16x16x32_bf16 v[84:87], v[24:27], v[56:59], v[84:87]
	v_mfma_f32_16x16x32_bf16 v[88:91], v[32:35], v[56:59], v[88:91]
	v_mfma_f32_16x16x32_bf16 v[92:95], v[24:27], v[64:67], v[92:95]
	v_mfma_f32_16x16x32_bf16 v[96:99], v[32:35], v[64:67], v[96:99]
	v_mfma_f32_16x16x32_bf16 v[100:103], v[24:27], v[72:75], v[100:103]
	v_mfma_f32_16x16x32_bf16 v[104:107], v[32:35], v[72:75], v[104:107]
	v_mfma_f32_16x16x32_bf16 v[108:111], v[24:27], v[80:83], v[108:111]
	v_mfma_f32_16x16x32_bf16 v[112:115], v[32:35], v[80:83], v[112:115]
	s_setprio 0
	s_setprio 1
	v_mfma_f32_16x16x32_bf16 v[116:119], v[36:39], v[52:55], 0
	v_mfma_f32_16x16x32_bf16 v[52:55], v[44:47], v[52:55], 0
	v_mfma_f32_16x16x32_bf16 v[116:119], v[40:43], v[56:59], v[116:119]
	v_mfma_f32_16x16x32_bf16 v[52:55], v[48:51], v[56:59], v[52:55]
	v_mfma_f32_16x16x32_bf16 v[56:59], v[36:39], v[60:63], 0
	v_mfma_f32_16x16x32_bf16 v[60:63], v[44:47], v[60:63], 0
	v_mfma_f32_16x16x32_bf16 v[56:59], v[40:43], v[64:67], v[56:59]
	v_mfma_f32_16x16x32_bf16 v[60:63], v[48:51], v[64:67], v[60:63]
	v_mfma_f32_16x16x32_bf16 v[64:67], v[36:39], v[68:71], 0
	v_mfma_f32_16x16x32_bf16 v[68:71], v[44:47], v[68:71], 0
	v_mfma_f32_16x16x32_bf16 v[64:67], v[40:43], v[72:75], v[64:67]
	v_mfma_f32_16x16x32_bf16 v[68:71], v[48:51], v[72:75], v[68:71]
	v_mfma_f32_16x16x32_bf16 v[72:75], v[36:39], v[76:79], 0
	v_mfma_f32_16x16x32_bf16 v[76:79], v[44:47], v[76:79], 0
	v_mfma_f32_16x16x32_bf16 v[72:75], v[40:43], v[80:83], v[72:75]
	v_mfma_f32_16x16x32_bf16 v[76:79], v[48:51], v[80:83], v[76:79]
	s_setprio 0
	s_barrier
	v_readlane_b32 s78, v247, 11
	s_add_i32 s68, s57, s78
	v_lshl_add_u64 v[212:213], s[38:39], 0, v[4:5]
	s_add_i32 s65, s68, 0x2000
	v_lshl_add_u64 v[148:149], v[212:213], 0, s[8:9]
	s_mov_b32 m0, s68
	v_lshl_add_u64 v[214:215], s[38:39], 0, v[0:1]
	s_add_u32 s72, s38, 0x80100
	ds_read_b128 v[80:83], v18 offset:16384
	ds_read_b128 v[120:123], v18 offset:17408
	ds_read_b128 v[124:127], v18 offset:18432
	ds_read_b128 v[128:131], v18 offset:19456
	ds_read_b128 v[132:135], v18 offset:20480
	ds_read_b128 v[136:139], v18 offset:21504
	ds_read_b128 v[140:143], v18 offset:22528
	ds_read_b128 v[144:147], v18 offset:23552
	global_load_lds_dwordx4 v[148:149], off
	v_lshl_add_u64 v[148:149], v[214:215], 0, s[8:9]
	s_mov_b32 m0, s65
	s_addc_u32 s73, s39, 0
	s_add_i32 s66, s58, s78
	global_load_lds_dwordx4 v[148:149], off
	s_mov_b32 m0, s66
	s_add_i32 s67, s66, 0x2000
	global_load_lds_dwordx4 v4, s[72:73]
	s_mov_b32 m0, s67
	v_lshl_add_u64 v[216:217], s[36:37], 0, v[6:7]
	global_load_lds_dwordx4 v0, s[72:73]
	v_lshl_add_u64 v[148:149], v[216:217], 0, s[8:9]
	s_mov_b32 m0, s45
	v_lshl_add_u64 v[218:219], s[36:37], 0, v[2:3]
	global_load_lds_dwordx4 v[148:149], off
	v_lshl_add_u64 v[148:149], v[218:219], 0, s[8:9]
	s_mov_b32 m0, s46
	s_nop 0
	global_load_lds_dwordx4 v[148:149], off
	s_waitcnt vmcnt(8)
	s_waitcnt lgkmcnt(0)
	s_barrier
	s_setprio 1
	s_waitcnt lgkmcnt(0)
	v_mfma_f32_16x16x32_bf16 v[148:151], v[20:23], v[80:83], 0
	v_mfma_f32_16x16x32_bf16 v[156:159], v[20:23], v[124:127], 0
	v_mfma_f32_16x16x32_bf16 v[164:167], v[20:23], v[132:135], 0
	v_mfma_f32_16x16x32_bf16 v[20:23], v[20:23], v[140:143], 0
	v_mfma_f32_16x16x32_bf16 v[148:151], v[24:27], v[120:123], v[148:151]
	v_mfma_f32_16x16x32_bf16 v[152:155], v[28:31], v[80:83], 0
	v_mfma_f32_16x16x32_bf16 v[156:159], v[24:27], v[128:131], v[156:159]
	v_mfma_f32_16x16x32_bf16 v[160:163], v[28:31], v[124:127], 0
	v_mfma_f32_16x16x32_bf16 v[164:167], v[24:27], v[136:139], v[164:167]
	v_mfma_f32_16x16x32_bf16 v[168:171], v[28:31], v[132:135], 0
	v_mfma_f32_16x16x32_bf16 v[20:23], v[24:27], v[144:147], v[20:23]
	v_mfma_f32_16x16x32_bf16 v[24:27], v[28:31], v[140:143], 0
	v_mfma_f32_16x16x32_bf16 v[152:155], v[32:35], v[120:123], v[152:155]
	v_mfma_f32_16x16x32_bf16 v[160:163], v[32:35], v[128:131], v[160:163]
	v_mfma_f32_16x16x32_bf16 v[168:171], v[32:35], v[136:139], v[168:171]
	v_mfma_f32_16x16x32_bf16 v[24:27], v[32:35], v[144:147], v[24:27]
	s_setprio 0
	s_setprio 1
	v_mfma_f32_16x16x32_bf16 v[28:31], v[36:39], v[80:83], 0
	v_mfma_f32_16x16x32_bf16 v[32:35], v[44:47], v[80:83], 0
	v_mfma_f32_16x16x32_bf16 v[28:31], v[40:43], v[120:123], v[28:31]
	v_mfma_f32_16x16x32_bf16 v[32:35], v[48:51], v[120:123], v[32:35]
	v_mfma_f32_16x16x32_bf16 v[80:83], v[36:39], v[124:127], 0
	v_mfma_f32_16x16x32_bf16 v[120:123], v[44:47], v[124:127], 0
	v_mfma_f32_16x16x32_bf16 v[124:127], v[36:39], v[132:135], 0
	v_mfma_f32_16x16x32_bf16 v[36:39], v[36:39], v[140:143], 0
	v_mfma_f32_16x16x32_bf16 v[80:83], v[40:43], v[128:131], v[80:83]
	v_mfma_f32_16x16x32_bf16 v[120:123], v[48:51], v[128:131], v[120:123]
	v_mfma_f32_16x16x32_bf16 v[124:127], v[40:43], v[136:139], v[124:127]
	v_mfma_f32_16x16x32_bf16 v[128:131], v[44:47], v[132:135], 0
	v_mfma_f32_16x16x32_bf16 v[36:39], v[40:43], v[144:147], v[36:39]
	v_mfma_f32_16x16x32_bf16 v[40:43], v[44:47], v[140:143], 0
	v_mfma_f32_16x16x32_bf16 v[128:131], v[48:51], v[136:139], v[128:131]
	v_mfma_f32_16x16x32_bf16 v[40:43], v[48:51], v[144:147], v[40:43]
	s_setprio 0
	s_barrier
	s_add_i32 s71, 0, 0x18000
	s_add_i32 s74, 0, 0x1c000
	v_add_u32_e32 v19, s71, v15
	v_add_u32_e32 v222, s74, v15
	ds_read_b128 v[44:47], v19
	ds_read_b128 v[48:51], v19 offset:1024
	ds_read_b128 v[132:135], v19 offset:2048
	ds_read_b128 v[136:139], v19 offset:3072
	ds_read_b128 v[140:143], v222
	ds_read_b128 v[144:147], v222 offset:1024
	ds_read_b128 v[172:175], v222 offset:2048
	ds_read_b128 v[176:179], v222 offset:3072
	s_add_u32 s72, s36, 0x40100
	s_addc_u32 s73, s37, 0
	s_mov_b32 m0, s47
	ds_read_b128 v[180:183], v18 offset:32768
	ds_read_b128 v[184:187], v18 offset:33792
	ds_read_b128 v[188:191], v18 offset:34816
	ds_read_b128 v[192:195], v18 offset:35840
	ds_read_b128 v[196:199], v18 offset:36864
	ds_read_b128 v[200:203], v18 offset:37888
	ds_read_b128 v[204:207], v18 offset:38912
	ds_read_b128 v[208:211], v18 offset:39936
	global_load_lds_dwordx4 v6, s[72:73]
	s_mov_b32 m0, s48
	s_nop 0
	global_load_lds_dwordx4 v2, s[72:73]
	s_waitcnt vmcnt(8)
	s_waitcnt lgkmcnt(0)
	s_barrier
	s_setprio 1
	s_waitcnt lgkmcnt(0)
	v_mfma_f32_16x16x32_bf16 v[84:87], v[44:47], v[180:183], v[84:87]
	v_mfma_f32_16x16x32_bf16 v[88:91], v[132:135], v[180:183], v[88:91]
	v_mfma_f32_16x16x32_bf16 v[92:95], v[44:47], v[188:191], v[92:95]
	v_mfma_f32_16x16x32_bf16 v[96:99], v[132:135], v[188:191], v[96:99]
	v_mfma_f32_16x16x32_bf16 v[100:103], v[44:47], v[196:199], v[100:103]
	v_mfma_f32_16x16x32_bf16 v[104:107], v[132:135], v[196:199], v[104:107]
	v_mfma_f32_16x16x32_bf16 v[108:111], v[44:47], v[204:207], v[108:111]
	v_mfma_f32_16x16x32_bf16 v[112:115], v[132:135], v[204:207], v[112:115]
	v_mfma_f32_16x16x32_bf16 v[84:87], v[48:51], v[184:187], v[84:87]
	v_mfma_f32_16x16x32_bf16 v[88:91], v[136:139], v[184:187], v[88:91]
	v_mfma_f32_16x16x32_bf16 v[92:95], v[48:51], v[192:195], v[92:95]
	v_mfma_f32_16x16x32_bf16 v[96:99], v[136:139], v[192:195], v[96:99]
	v_mfma_f32_16x16x32_bf16 v[100:103], v[48:51], v[200:203], v[100:103]
	v_mfma_f32_16x16x32_bf16 v[104:107], v[136:139], v[200:203], v[104:107]
	v_mfma_f32_16x16x32_bf16 v[108:111], v[48:51], v[208:211], v[108:111]
	v_mfma_f32_16x16x32_bf16 v[112:115], v[136:139], v[208:211], v[112:115]
	s_setprio 0
	s_setprio 1
	v_mfma_f32_16x16x32_bf16 v[116:119], v[140:143], v[180:183], v[116:119]
	v_mfma_f32_16x16x32_bf16 v[52:55], v[172:175], v[180:183], v[52:55]
	v_mfma_f32_16x16x32_bf16 v[56:59], v[140:143], v[188:191], v[56:59]
	v_mfma_f32_16x16x32_bf16 v[60:63], v[172:175], v[188:191], v[60:63]
	v_mfma_f32_16x16x32_bf16 v[64:67], v[140:143], v[196:199], v[64:67]
	v_mfma_f32_16x16x32_bf16 v[68:71], v[172:175], v[196:199], v[68:71]
	v_mfma_f32_16x16x32_bf16 v[72:75], v[140:143], v[204:207], v[72:75]
	v_mfma_f32_16x16x32_bf16 v[76:79], v[172:175], v[204:207], v[76:79]
	v_mfma_f32_16x16x32_bf16 v[116:119], v[144:147], v[184:187], v[116:119]
	v_mfma_f32_16x16x32_bf16 v[52:55], v[176:179], v[184:187], v[52:55]
	v_mfma_f32_16x16x32_bf16 v[56:59], v[144:147], v[192:195], v[56:59]
	v_mfma_f32_16x16x32_bf16 v[60:63], v[176:179], v[192:195], v[60:63]
	v_mfma_f32_16x16x32_bf16 v[64:67], v[144:147], v[200:203], v[64:67]
	v_mfma_f32_16x16x32_bf16 v[68:71], v[176:179], v[200:203], v[68:71]
	v_mfma_f32_16x16x32_bf16 v[72:75], v[144:147], v[208:211], v[72:75]
	v_mfma_f32_16x16x32_bf16 v[76:79], v[176:179], v[208:211], v[76:79]
	s_setprio 0
	s_barrier
	s_add_i32 s71, s71, s78
	s_add_i32 s69, s71, 0x2000
	v_lshl_add_u64 v[212:213], v[212:213], 0, s[10:11]
	s_mov_b32 m0, s71
	s_add_u32 s72, s38, 0x80180
	ds_read_b128 v[180:183], v18 offset:49152
	ds_read_b128 v[184:187], v18 offset:50176
	ds_read_b128 v[188:191], v18 offset:51200
	ds_read_b128 v[192:195], v18 offset:52224
	ds_read_b128 v[196:199], v18 offset:53248
	ds_read_b128 v[200:203], v18 offset:54272
	ds_read_b128 v[204:207], v18 offset:55296
	ds_read_b128 v[208:211], v18 offset:56320
	global_load_lds_dwordx4 v[212:213], off
	v_lshl_add_u64 v[212:213], v[214:215], 0, s[10:11]
	s_mov_b32 m0, s69
	s_addc_u32 s73, s39, 0
	s_add_i32 s38, s74, s78
	global_load_lds_dwordx4 v[212:213], off
	s_mov_b32 m0, s38
	s_add_i32 s39, s38, 0x2000
	global_load_lds_dwordx4 v4, s[72:73]
	s_mov_b32 m0, s39
	s_nop 0
	global_load_lds_dwordx4 v0, s[72:73]
	v_lshl_add_u64 v[212:213], v[216:217], 0, s[10:11]
	s_mov_b32 m0, s52
	s_nop 0
	global_load_lds_dwordx4 v[212:213], off
	v_lshl_add_u64 v[212:213], v[218:219], 0, s[10:11]
	s_mov_b32 m0, s53
	s_nop 0
	global_load_lds_dwordx4 v[212:213], off
	s_waitcnt vmcnt(8)
	s_waitcnt lgkmcnt(0)
	s_barrier
	s_setprio 1
	s_waitcnt lgkmcnt(0)
	v_mfma_f32_16x16x32_bf16 v[148:151], v[44:47], v[180:183], v[148:151]
	v_mfma_f32_16x16x32_bf16 v[152:155], v[132:135], v[180:183], v[152:155]
	v_mfma_f32_16x16x32_bf16 v[156:159], v[44:47], v[188:191], v[156:159]
	v_mfma_f32_16x16x32_bf16 v[160:163], v[132:135], v[188:191], v[160:163]
	v_mfma_f32_16x16x32_bf16 v[164:167], v[44:47], v[196:199], v[164:167]
	v_mfma_f32_16x16x32_bf16 v[168:171], v[132:135], v[196:199], v[168:171]
	v_mfma_f32_16x16x32_bf16 v[20:23], v[44:47], v[204:207], v[20:23]
	v_mfma_f32_16x16x32_bf16 v[24:27], v[132:135], v[204:207], v[24:27]
	v_mfma_f32_16x16x32_bf16 v[148:151], v[48:51], v[184:187], v[148:151]
	v_mfma_f32_16x16x32_bf16 v[152:155], v[136:139], v[184:187], v[152:155]
	v_mfma_f32_16x16x32_bf16 v[156:159], v[48:51], v[192:195], v[156:159]
	v_mfma_f32_16x16x32_bf16 v[160:163], v[136:139], v[192:195], v[160:163]
	v_mfma_f32_16x16x32_bf16 v[164:167], v[48:51], v[200:203], v[164:167]
	v_mfma_f32_16x16x32_bf16 v[168:171], v[136:139], v[200:203], v[168:171]
	v_mfma_f32_16x16x32_bf16 v[20:23], v[48:51], v[208:211], v[20:23]
	v_mfma_f32_16x16x32_bf16 v[24:27], v[136:139], v[208:211], v[24:27]
	s_setprio 0
	s_setprio 1
	v_mfma_f32_16x16x32_bf16 v[28:31], v[140:143], v[180:183], v[28:31]
	v_mfma_f32_16x16x32_bf16 v[32:35], v[172:175], v[180:183], v[32:35]
	v_mfma_f32_16x16x32_bf16 v[44:47], v[140:143], v[188:191], v[80:83]
	v_mfma_f32_16x16x32_bf16 v[48:51], v[172:175], v[188:191], v[120:123]
	v_mfma_f32_16x16x32_bf16 v[80:83], v[140:143], v[196:199], v[124:127]
	v_mfma_f32_16x16x32_bf16 v[120:123], v[172:175], v[196:199], v[128:131]
	v_mfma_f32_16x16x32_bf16 v[36:39], v[140:143], v[204:207], v[36:39]
	v_mfma_f32_16x16x32_bf16 v[40:43], v[172:175], v[204:207], v[40:43]
	v_mfma_f32_16x16x32_bf16 v[28:31], v[144:147], v[184:187], v[28:31]
	v_mfma_f32_16x16x32_bf16 v[32:35], v[176:179], v[184:187], v[32:35]
	v_mfma_f32_16x16x32_bf16 v[44:47], v[144:147], v[192:195], v[44:47]
	v_mfma_f32_16x16x32_bf16 v[48:51], v[176:179], v[192:195], v[48:51]
	v_mfma_f32_16x16x32_bf16 v[80:83], v[144:147], v[200:203], v[80:83]
	v_mfma_f32_16x16x32_bf16 v[120:123], v[176:179], v[200:203], v[120:123]
	v_mfma_f32_16x16x32_bf16 v[36:39], v[144:147], v[208:211], v[36:39]
	v_mfma_f32_16x16x32_bf16 v[40:43], v[176:179], v[208:211], v[40:43]
	s_setprio 0
	s_barrier
	ds_read_b128 v[124:127], v16
	ds_read_b128 v[128:131], v16 offset:1024
	ds_read_b128 v[132:135], v16 offset:2048
	ds_read_b128 v[136:139], v16 offset:3072
	ds_read_b128 v[140:143], v17
	ds_read_b128 v[144:147], v17 offset:1024
	ds_read_b128 v[172:175], v17 offset:2048
	ds_read_b128 v[176:179], v17 offset:3072
	s_add_u32 s36, s36, 0x40180
	s_addc_u32 s37, s37, 0
	s_mov_b32 m0, s70
	ds_read_b128 v[180:183], v18
	ds_read_b128 v[184:187], v18 offset:1024
	ds_read_b128 v[188:191], v18 offset:2048
	ds_read_b128 v[192:195], v18 offset:3072
	ds_read_b128 v[196:199], v18 offset:4096
	ds_read_b128 v[200:203], v18 offset:5120
	ds_read_b128 v[204:207], v18 offset:6144
	ds_read_b128 v[208:211], v18 offset:7168
	global_load_lds_dwordx4 v6, s[36:37]
	s_mov_b32 m0, s64
	s_nop 0
	global_load_lds_dwordx4 v2, s[36:37]
	s_waitcnt vmcnt(8)
	s_waitcnt lgkmcnt(0)
	s_barrier
	s_setprio 1
	s_waitcnt lgkmcnt(0)
	v_mfma_f32_16x16x32_bf16 v[84:87], v[124:127], v[180:183], v[84:87]
	v_mfma_f32_16x16x32_bf16 v[88:91], v[132:135], v[180:183], v[88:91]
	v_mfma_f32_16x16x32_bf16 v[92:95], v[124:127], v[188:191], v[92:95]
	v_mfma_f32_16x16x32_bf16 v[96:99], v[132:135], v[188:191], v[96:99]
	v_mfma_f32_16x16x32_bf16 v[100:103], v[124:127], v[196:199], v[100:103]
	v_mfma_f32_16x16x32_bf16 v[104:107], v[132:135], v[196:199], v[104:107]
	v_mfma_f32_16x16x32_bf16 v[108:111], v[124:127], v[204:207], v[108:111]
	v_mfma_f32_16x16x32_bf16 v[112:115], v[132:135], v[204:207], v[112:115]
	v_mfma_f32_16x16x32_bf16 v[84:87], v[128:131], v[184:187], v[84:87]
	v_mfma_f32_16x16x32_bf16 v[88:91], v[136:139], v[184:187], v[88:91]
	v_mfma_f32_16x16x32_bf16 v[92:95], v[128:131], v[192:195], v[92:95]
	v_mfma_f32_16x16x32_bf16 v[96:99], v[136:139], v[192:195], v[96:99]
	v_mfma_f32_16x16x32_bf16 v[100:103], v[128:131], v[200:203], v[100:103]
	v_mfma_f32_16x16x32_bf16 v[104:107], v[136:139], v[200:203], v[104:107]
	v_mfma_f32_16x16x32_bf16 v[108:111], v[128:131], v[208:211], v[108:111]
	v_mfma_f32_16x16x32_bf16 v[112:115], v[136:139], v[208:211], v[112:115]
	s_setprio 0
	s_setprio 1
	v_mfma_f32_16x16x32_bf16 v[116:119], v[140:143], v[180:183], v[116:119]
	v_mfma_f32_16x16x32_bf16 v[52:55], v[172:175], v[180:183], v[52:55]
	v_mfma_f32_16x16x32_bf16 v[56:59], v[140:143], v[188:191], v[56:59]
	v_mfma_f32_16x16x32_bf16 v[60:63], v[172:175], v[188:191], v[60:63]
	v_mfma_f32_16x16x32_bf16 v[64:67], v[140:143], v[196:199], v[64:67]
	v_mfma_f32_16x16x32_bf16 v[68:71], v[172:175], v[196:199], v[68:71]
	v_mfma_f32_16x16x32_bf16 v[72:75], v[140:143], v[204:207], v[72:75]
	v_mfma_f32_16x16x32_bf16 v[76:79], v[172:175], v[204:207], v[76:79]
	v_mfma_f32_16x16x32_bf16 v[116:119], v[144:147], v[184:187], v[116:119]
	v_mfma_f32_16x16x32_bf16 v[52:55], v[176:179], v[184:187], v[52:55]
	v_mfma_f32_16x16x32_bf16 v[56:59], v[144:147], v[192:195], v[56:59]
	v_mfma_f32_16x16x32_bf16 v[60:63], v[176:179], v[192:195], v[60:63]
	v_mfma_f32_16x16x32_bf16 v[64:67], v[144:147], v[200:203], v[64:67]
	v_mfma_f32_16x16x32_bf16 v[68:71], v[176:179], v[200:203], v[68:71]
	v_mfma_f32_16x16x32_bf16 v[72:75], v[144:147], v[208:211], v[72:75]
	v_mfma_f32_16x16x32_bf16 v[76:79], v[176:179], v[208:211], v[76:79]
	s_setprio 0
	s_barrier
	s_mov_b32 m0, s68
	v_lshl_add_u64 v[212:213], s[2:3], 0, v[4:5]
	s_add_u32 s36, s2, 0x80000
	ds_read_b128 v[180:183], v18 offset:16384
	ds_read_b128 v[184:187], v18 offset:17408
	ds_read_b128 v[188:191], v18 offset:18432
	ds_read_b128 v[192:195], v18 offset:19456
	ds_read_b128 v[196:199], v18 offset:20480
	ds_read_b128 v[200:203], v18 offset:21504
	ds_read_b128 v[204:207], v18 offset:22528
	ds_read_b128 v[208:211], v18 offset:23552
	global_load_lds_dwordx4 v[212:213], off
	v_lshl_add_u64 v[214:215], s[2:3], 0, v[0:1]
	s_mov_b32 m0, s65
	s_addc_u32 s37, s3, 0
	global_load_lds_dwordx4 v[214:215], off
	s_mov_b32 m0, s66
	v_lshl_add_u64 v[218:219], s[40:41], 0, v[2:3]
	global_load_lds_dwordx4 v4, s[36:37]
	s_mov_b32 m0, s67
	s_nop 0
	global_load_lds_dwordx4 v0, s[36:37]
	v_lshl_add_u64 v[216:217], s[40:41], 0, v[6:7]
	s_mov_b32 m0, s45
	s_nop 0
	global_load_lds_dwordx4 v[216:217], off
	s_mov_b32 m0, s46
	s_nop 0
	global_load_lds_dwordx4 v[218:219], off
	s_waitcnt vmcnt(8)
	s_waitcnt lgkmcnt(0)
	s_barrier
	s_setprio 1
	s_waitcnt lgkmcnt(0)
	v_mfma_f32_16x16x32_bf16 v[148:151], v[124:127], v[180:183], v[148:151]
	v_mfma_f32_16x16x32_bf16 v[152:155], v[132:135], v[180:183], v[152:155]
	v_mfma_f32_16x16x32_bf16 v[156:159], v[124:127], v[188:191], v[156:159]
	v_mfma_f32_16x16x32_bf16 v[160:163], v[132:135], v[188:191], v[160:163]
	v_mfma_f32_16x16x32_bf16 v[164:167], v[124:127], v[196:199], v[164:167]
	v_mfma_f32_16x16x32_bf16 v[168:171], v[132:135], v[196:199], v[168:171]
	v_mfma_f32_16x16x32_bf16 v[20:23], v[124:127], v[204:207], v[20:23]
	v_mfma_f32_16x16x32_bf16 v[24:27], v[132:135], v[204:207], v[24:27]
	v_mfma_f32_16x16x32_bf16 v[148:151], v[128:131], v[184:187], v[148:151]
	v_mfma_f32_16x16x32_bf16 v[152:155], v[136:139], v[184:187], v[152:155]
	v_mfma_f32_16x16x32_bf16 v[156:159], v[128:131], v[192:195], v[156:159]
	v_mfma_f32_16x16x32_bf16 v[160:163], v[136:139], v[192:195], v[160:163]
	v_mfma_f32_16x16x32_bf16 v[164:167], v[128:131], v[200:203], v[164:167]
	v_mfma_f32_16x16x32_bf16 v[168:171], v[136:139], v[200:203], v[168:171]
	v_mfma_f32_16x16x32_bf16 v[20:23], v[128:131], v[208:211], v[20:23]
	v_mfma_f32_16x16x32_bf16 v[24:27], v[136:139], v[208:211], v[24:27]
	s_setprio 0
	s_setprio 1
	v_mfma_f32_16x16x32_bf16 v[28:31], v[140:143], v[180:183], v[28:31]
	v_mfma_f32_16x16x32_bf16 v[32:35], v[172:175], v[180:183], v[32:35]
	v_mfma_f32_16x16x32_bf16 v[44:47], v[140:143], v[188:191], v[44:47]
	v_mfma_f32_16x16x32_bf16 v[48:51], v[172:175], v[188:191], v[48:51]
	v_mfma_f32_16x16x32_bf16 v[80:83], v[140:143], v[196:199], v[80:83]
	v_mfma_f32_16x16x32_bf16 v[120:123], v[172:175], v[196:199], v[120:123]
	v_mfma_f32_16x16x32_bf16 v[36:39], v[140:143], v[204:207], v[36:39]
	v_mfma_f32_16x16x32_bf16 v[40:43], v[172:175], v[204:207], v[40:43]
	v_mfma_f32_16x16x32_bf16 v[28:31], v[144:147], v[184:187], v[28:31]
	v_mfma_f32_16x16x32_bf16 v[32:35], v[176:179], v[184:187], v[32:35]
	v_mfma_f32_16x16x32_bf16 v[44:47], v[144:147], v[192:195], v[44:47]
	v_mfma_f32_16x16x32_bf16 v[48:51], v[176:179], v[192:195], v[48:51]
	v_mfma_f32_16x16x32_bf16 v[80:83], v[144:147], v[200:203], v[80:83]
	v_mfma_f32_16x16x32_bf16 v[120:123], v[176:179], v[200:203], v[120:123]
	v_mfma_f32_16x16x32_bf16 v[36:39], v[144:147], v[208:211], v[36:39]
	v_mfma_f32_16x16x32_bf16 v[40:43], v[176:179], v[208:211], v[40:43]
	s_setprio 0
	s_barrier
	ds_read_b128 v[124:127], v19
	ds_read_b128 v[128:131], v19 offset:1024
	ds_read_b128 v[132:135], v19 offset:2048
	ds_read_b128 v[136:139], v19 offset:3072
	ds_read_b128 v[140:143], v222
	ds_read_b128 v[144:147], v222 offset:1024
	ds_read_b128 v[172:175], v222 offset:2048
	ds_read_b128 v[176:179], v222 offset:3072
	s_add_u32 s36, s40, 0x40000
	s_addc_u32 s37, s41, 0
	s_mov_b32 m0, s47
	ds_read_b128 v[180:183], v18 offset:32768
	ds_read_b128 v[184:187], v18 offset:33792
	ds_read_b128 v[188:191], v18 offset:34816
	ds_read_b128 v[192:195], v18 offset:35840
	ds_read_b128 v[196:199], v18 offset:36864
	ds_read_b128 v[200:203], v18 offset:37888
	ds_read_b128 v[204:207], v18 offset:38912
	ds_read_b128 v[208:211], v18 offset:39936
	global_load_lds_dwordx4 v6, s[36:37]
	s_mov_b32 m0, s48
	s_nop 0
	global_load_lds_dwordx4 v2, s[36:37]
	s_waitcnt vmcnt(8)
	s_waitcnt lgkmcnt(0)
	s_barrier
	s_setprio 1
	s_waitcnt lgkmcnt(0)
	v_mfma_f32_16x16x32_bf16 v[84:87], v[124:127], v[180:183], v[84:87]
	v_mfma_f32_16x16x32_bf16 v[88:91], v[132:135], v[180:183], v[88:91]
	v_mfma_f32_16x16x32_bf16 v[92:95], v[124:127], v[188:191], v[92:95]
	v_mfma_f32_16x16x32_bf16 v[96:99], v[132:135], v[188:191], v[96:99]
	v_mfma_f32_16x16x32_bf16 v[100:103], v[124:127], v[196:199], v[100:103]
	v_mfma_f32_16x16x32_bf16 v[104:107], v[132:135], v[196:199], v[104:107]
	v_mfma_f32_16x16x32_bf16 v[108:111], v[124:127], v[204:207], v[108:111]
	v_mfma_f32_16x16x32_bf16 v[112:115], v[132:135], v[204:207], v[112:115]
	v_mfma_f32_16x16x32_bf16 v[84:87], v[128:131], v[184:187], v[84:87]
	v_mfma_f32_16x16x32_bf16 v[88:91], v[136:139], v[184:187], v[88:91]
	v_mfma_f32_16x16x32_bf16 v[92:95], v[128:131], v[192:195], v[92:95]
	v_mfma_f32_16x16x32_bf16 v[96:99], v[136:139], v[192:195], v[96:99]
	v_mfma_f32_16x16x32_bf16 v[100:103], v[128:131], v[200:203], v[100:103]
	v_mfma_f32_16x16x32_bf16 v[104:107], v[136:139], v[200:203], v[104:107]
	v_mfma_f32_16x16x32_bf16 v[108:111], v[128:131], v[208:211], v[108:111]
	v_mfma_f32_16x16x32_bf16 v[112:115], v[136:139], v[208:211], v[112:115]
	s_setprio 0
	s_setprio 1
	v_mfma_f32_16x16x32_bf16 v[116:119], v[140:143], v[180:183], v[116:119]
	v_mfma_f32_16x16x32_bf16 v[52:55], v[172:175], v[180:183], v[52:55]
	v_mfma_f32_16x16x32_bf16 v[56:59], v[140:143], v[188:191], v[56:59]
	v_mfma_f32_16x16x32_bf16 v[60:63], v[172:175], v[188:191], v[60:63]
	v_mfma_f32_16x16x32_bf16 v[64:67], v[140:143], v[196:199], v[64:67]
	v_mfma_f32_16x16x32_bf16 v[68:71], v[172:175], v[196:199], v[68:71]
	v_mfma_f32_16x16x32_bf16 v[72:75], v[140:143], v[204:207], v[72:75]
	v_mfma_f32_16x16x32_bf16 v[76:79], v[172:175], v[204:207], v[76:79]
	v_mfma_f32_16x16x32_bf16 v[116:119], v[144:147], v[184:187], v[116:119]
	v_mfma_f32_16x16x32_bf16 v[52:55], v[176:179], v[184:187], v[52:55]
	v_mfma_f32_16x16x32_bf16 v[56:59], v[144:147], v[192:195], v[56:59]
	v_mfma_f32_16x16x32_bf16 v[60:63], v[176:179], v[192:195], v[60:63]
	v_mfma_f32_16x16x32_bf16 v[64:67], v[144:147], v[200:203], v[64:67]
	v_mfma_f32_16x16x32_bf16 v[68:71], v[176:179], v[200:203], v[68:71]
	v_mfma_f32_16x16x32_bf16 v[72:75], v[144:147], v[208:211], v[72:75]
	v_mfma_f32_16x16x32_bf16 v[76:79], v[176:179], v[208:211], v[76:79]
	s_setprio 0
	s_barrier
	s_mov_b32 m0, s71
	v_lshl_add_u64 v[212:213], v[212:213], 0, s[4:5]
	s_add_u32 s2, s2, 0x80080
	ds_read_b128 v[180:183], v18 offset:49152
	ds_read_b128 v[184:187], v18 offset:50176
	ds_read_b128 v[188:191], v18 offset:51200
	ds_read_b128 v[192:195], v18 offset:52224
	ds_read_b128 v[196:199], v18 offset:53248
	ds_read_b128 v[200:203], v18 offset:54272
	ds_read_b128 v[204:207], v18 offset:55296
	ds_read_b128 v[208:211], v18 offset:56320
	global_load_lds_dwordx4 v[212:213], off
	v_lshl_add_u64 v[212:213], v[214:215], 0, s[4:5]
	s_mov_b32 m0, s69
	s_addc_u32 s3, s3, 0
	global_load_lds_dwordx4 v[212:213], off
	s_mov_b32 m0, s38
	s_nop 0
	global_load_lds_dwordx4 v4, s[2:3]
	s_mov_b32 m0, s39
	s_nop 0
	global_load_lds_dwordx4 v0, s[2:3]
	v_lshl_add_u64 v[212:213], v[216:217], 0, s[4:5]
	s_mov_b32 m0, s52
	s_nop 0
	global_load_lds_dwordx4 v[212:213], off
	v_lshl_add_u64 v[212:213], v[218:219], 0, s[4:5]
	s_mov_b32 m0, s53
	s_nop 0
	global_load_lds_dwordx4 v[212:213], off
	s_waitcnt vmcnt(8)
	s_waitcnt lgkmcnt(0)
	s_barrier
	s_setprio 1
	s_waitcnt lgkmcnt(0)
	v_mfma_f32_16x16x32_bf16 v[148:151], v[124:127], v[180:183], v[148:151]
	v_mfma_f32_16x16x32_bf16 v[152:155], v[132:135], v[180:183], v[152:155]
	v_mfma_f32_16x16x32_bf16 v[156:159], v[124:127], v[188:191], v[156:159]
	v_mfma_f32_16x16x32_bf16 v[160:163], v[132:135], v[188:191], v[160:163]
	v_mfma_f32_16x16x32_bf16 v[164:167], v[124:127], v[196:199], v[164:167]
	v_mfma_f32_16x16x32_bf16 v[168:171], v[132:135], v[196:199], v[168:171]
	v_mfma_f32_16x16x32_bf16 v[20:23], v[124:127], v[204:207], v[20:23]
	v_mfma_f32_16x16x32_bf16 v[24:27], v[132:135], v[204:207], v[24:27]
	v_mfma_f32_16x16x32_bf16 v[148:151], v[128:131], v[184:187], v[148:151]
	v_mfma_f32_16x16x32_bf16 v[152:155], v[136:139], v[184:187], v[152:155]
	v_mfma_f32_16x16x32_bf16 v[156:159], v[128:131], v[192:195], v[156:159]
	v_mfma_f32_16x16x32_bf16 v[160:163], v[136:139], v[192:195], v[160:163]
	v_mfma_f32_16x16x32_bf16 v[164:167], v[128:131], v[200:203], v[164:167]
	v_mfma_f32_16x16x32_bf16 v[168:171], v[136:139], v[200:203], v[168:171]
	v_mfma_f32_16x16x32_bf16 v[20:23], v[128:131], v[208:211], v[20:23]
	v_mfma_f32_16x16x32_bf16 v[24:27], v[136:139], v[208:211], v[24:27]
	s_setprio 0
	s_setprio 1
	v_mfma_f32_16x16x32_bf16 v[28:31], v[140:143], v[180:183], v[28:31]
	v_mfma_f32_16x16x32_bf16 v[32:35], v[172:175], v[180:183], v[32:35]
	v_mfma_f32_16x16x32_bf16 v[44:47], v[140:143], v[188:191], v[44:47]
	v_mfma_f32_16x16x32_bf16 v[48:51], v[172:175], v[188:191], v[48:51]
	v_mfma_f32_16x16x32_bf16 v[80:83], v[140:143], v[196:199], v[80:83]
	v_mfma_f32_16x16x32_bf16 v[120:123], v[172:175], v[196:199], v[120:123]
	v_mfma_f32_16x16x32_bf16 v[36:39], v[140:143], v[204:207], v[36:39]
	v_mfma_f32_16x16x32_bf16 v[40:43], v[172:175], v[204:207], v[40:43]
	v_mfma_f32_16x16x32_bf16 v[28:31], v[144:147], v[184:187], v[28:31]
	v_mfma_f32_16x16x32_bf16 v[32:35], v[176:179], v[184:187], v[32:35]
	v_mfma_f32_16x16x32_bf16 v[44:47], v[144:147], v[192:195], v[44:47]
	v_mfma_f32_16x16x32_bf16 v[48:51], v[176:179], v[192:195], v[48:51]
	v_mfma_f32_16x16x32_bf16 v[80:83], v[144:147], v[200:203], v[80:83]
	v_mfma_f32_16x16x32_bf16 v[120:123], v[176:179], v[200:203], v[120:123]
	v_mfma_f32_16x16x32_bf16 v[36:39], v[144:147], v[208:211], v[36:39]
	v_mfma_f32_16x16x32_bf16 v[40:43], v[176:179], v[208:211], v[40:43]
	s_setprio 0
	s_barrier
	v_lshl_add_u32 v124, s7, 8, v14
	s_ashr_i32 s7, s6, 31
	s_lshl_b64 s[2:3], s[6:7], 21
	v_ashrrev_i32_e32 v125, 31, v124
	s_add_u32 s2, s49, s2
	v_lshlrev_b64 v[124:125], 10, v[124:125]
	s_addc_u32 s3, s51, s3
	v_lshl_add_u64 v[124:125], s[2:3], 0, v[124:125]
	v_lshl_add_u64 v[124:125], v[124:125], 0, v[12:13]
	s_mov_b64 s[2:3], 0x4000
	global_store_dwordx4 v[124:125], v[84:87], off sc1
	global_store_dwordx4 v[124:125], v[88:91], off offset:64 sc1
	global_store_dwordx4 v[124:125], v[116:119], off offset:512 sc1
	global_store_dwordx4 v[124:125], v[52:55], off offset:576 sc1
	s_add_i32 s56, s56, s76
	s_mov_b32 s6, s63
	v_lshl_add_u64 v[52:53], v[124:125], 0, s[2:3]
	s_movk_i32 s2, 0x4000
	v_add_co_u32_e32 v54, vcc, s2, v124
	s_mov_b64 s[2:3], 0x8000
	s_nop 0
	v_addc_co_u32_e32 v55, vcc, 0, v125, vcc
	global_store_dwordx4 v[54:55], v[92:95], off sc1
	global_store_dwordx4 v[52:53], v[96:99], off offset:64 sc1
	global_store_dwordx4 v[52:53], v[56:59], off offset:512 sc1
	global_store_dwordx4 v[52:53], v[60:63], off offset:576 sc1
	v_lshl_add_u64 v[52:53], v[124:125], 0, s[2:3]
	s_mov_b32 s2, 0x8000
	v_add_co_u32_e32 v54, vcc, s2, v124
	s_mov_b32 s2, 0xc000
	s_nop 0
	v_addc_co_u32_e32 v55, vcc, 0, v125, vcc
	global_store_dwordx4 v[54:55], v[100:103], off sc1
	global_store_dwordx4 v[52:53], v[104:107], off offset:64 sc1
	global_store_dwordx4 v[52:53], v[64:67], off offset:512 sc1
	global_store_dwordx4 v[52:53], v[68:71], off offset:576 sc1
	v_add_co_u32_e32 v54, vcc, s2, v124
	v_lshl_add_u64 v[52:53], v[124:125], 0, s[12:13]
	s_nop 0
	v_addc_co_u32_e32 v55, vcc, 0, v125, vcc
	global_store_dwordx4 v[54:55], v[108:111], off sc1
	global_store_dwordx4 v[52:53], v[112:115], off offset:64 sc1
	global_store_dwordx4 v[52:53], v[72:75], off offset:512 sc1
	global_store_dwordx4 v[52:53], v[76:79], off offset:576 sc1
	v_add_co_u32_e32 v54, vcc, s59, v124
	v_lshl_add_u64 v[52:53], v[124:125], 0, s[14:15]
	s_nop 0
	v_addc_co_u32_e32 v55, vcc, 0, v125, vcc
	global_store_dwordx4 v[54:55], v[148:151], off sc1
	global_store_dwordx4 v[52:53], v[152:155], off offset:64 sc1
	global_store_dwordx4 v[52:53], v[28:31], off offset:512 sc1
	global_store_dwordx4 v[52:53], v[32:35], off offset:576 sc1
	s_mov_b32 s7, s62
	v_add_co_u32_e32 v30, vcc, s60, v124
	v_lshl_add_u64 v[28:29], v[124:125], 0, s[16:17]
	s_nop 0
	v_addc_co_u32_e32 v31, vcc, 0, v125, vcc
	global_store_dwordx4 v[30:31], v[156:159], off sc1
	global_store_dwordx4 v[28:29], v[160:163], off offset:64 sc1
	global_store_dwordx4 v[28:29], v[44:47], off offset:512 sc1
	global_store_dwordx4 v[28:29], v[48:51], off offset:576 sc1
	v_add_co_u32_e32 v30, vcc, s61, v124
	v_lshl_add_u64 v[28:29], v[124:125], 0, s[18:19]
	s_nop 0
	v_addc_co_u32_e32 v31, vcc, 0, v125, vcc
	global_store_dwordx4 v[30:31], v[164:167], off sc1
	global_store_dwordx4 v[28:29], v[168:171], off offset:64 sc1
	global_store_dwordx4 v[28:29], v[80:83], off offset:512 sc1
	global_store_dwordx4 v[28:29], v[120:123], off offset:576 sc1
	v_add_co_u32_e32 v30, vcc, 0x2c000, v124
	s_mov_b64 s[38:39], s[34:35]
	s_nop 0
	v_addc_co_u32_e32 v31, vcc, 0, v125, vcc
	s_andn2_b64 vcc, exec, s[0:1]
	s_mov_b64 s[36:37], s[30:31]
	v_lshl_add_u64 v[28:29], v[124:125], 0, s[20:21]
	global_store_dwordx4 v[30:31], v[20:23], off sc1
	global_store_dwordx4 v[28:29], v[24:27], off offset:64 sc1
	global_store_dwordx4 v[28:29], v[36:39], off offset:512 sc1
	global_store_dwordx4 v[28:29], v[40:43], off offset:576 sc1
	s_cbranch_vccz .LBB0_368

.LBB0_564:
	s_add_u32 s50, s6, 0x1c02000
	s_addc_u32 s51, s7, 0
	s_mov_b64 s[6:7], 0x80
	s_add_i32 m0, s35, 0x18000
	v_lshl_add_u64 v[6:7], v[6:7], 0, s[6:7]
	s_waitcnt vmcnt(2)
	s_barrier
	global_load_lds_dwordx4 v[6:7], off
	v_lshl_add_u64 v[4:5], v[4:5], 0, s[6:7]
	s_add_i32 m0, s35, 0x1a000
	s_add_i32 s52, s35, 0x8000
	s_add_i32 s53, s35, 0xa000
	global_load_lds_dwordx4 v[4:5], off
	v_lshl_add_u64 v[0:1], v[0:1], 0, s[6:7]
	s_mov_b32 m0, s52
	s_add_u32 s10, s36, 0x40080
	global_load_lds_dwordx4 v[0:1], off
	v_lshl_add_u64 v[0:1], v[2:3], 0, s[6:7]
	s_mov_b32 m0, s53
	s_addc_u32 s11, s37, 0
	global_load_lds_dwordx4 v[0:1], off
	s_add_i32 m0, s35, 0x1c000
	s_nop 0
	global_load_lds_dwordx4 v144, s[10:11]
	v_lshl_add_u64 v[0:1], s[10:11], 0, v[146:147]
	s_add_i32 m0, s35, 0x1e000
	s_sext_i32_i8 s58, s8
	global_load_lds_dwordx4 v[0:1], off
	v_and_b32_e32 v0, 15, v10
	v_readlane_b32 s8, v247, 6
	v_and_b32_e32 v3, 48, v10
	v_lshrrev_b32_e32 v1, 6, v10
	v_or_b32_e32 v158, s8, v0
	v_lshlrev_b32_e32 v2, 6, v158
	s_movk_i32 s8, 0x3c0
	v_and_or_b32 v2, v2, s8, v3
	v_readlane_b32 s8, v247, 8
	v_lshl_or_b32 v0, v0, 6, v3
	v_lshlrev_b32_e32 v3, 2, v10
	v_lshl_add_u32 v4, v1, 10, s8
	v_readlane_b32 s8, v247, 10
	v_and_b32_e32 v3, 32, v3
	v_readlane_b32 s10, v247, 9
	v_add_lshl_u32 v1, v1, s8, 10
	v_bitop3_b32 v159, v0, v1, v3 bitop3:0xde
	v_lshrrev_b32_e32 v0, 2, v10
	v_and_b32_e32 v0, 28, v0
	v_add_u32_e32 v160, s10, v0
	v_lshlrev_b32_e32 v0, 14, v12
	v_and_b32_e32 v0, 0xffff8000, v0
	v_lshl_add_u32 v0, v13, 11, v0
	v_and_b32_e32 v1, 1, v12
	v_lshl_or_b32 v0, v1, 6, v0
	v_lshl_add_u32 v148, v14, 1, v0
	v_lshlrev_b32_e32 v0, 14, v8
	v_lshlrev_b32_e32 v5, 2, v158
	v_and_b32_e32 v0, 0xffff8000, v0
	v_and_b32_e32 v5, 32, v5
	s_waitcnt vmcnt(6)
	s_cmpk_lt_u32 s75, 0x100
	v_lshl_add_u32 v0, v9, 11, v0
	v_and_b32_e32 v1, 1, v8
	v_bitop3_b32 v2, v2, v4, v5 bitop3:0xde
	s_cselect_b64 s[8:9], -1, 0
	v_lshl_or_b32 v0, v1, 6, v0
	s_add_i32 s56, 0, 0x10000
	s_add_i32 s57, 0, 0x14000
	s_ashr_i32 s54, s76, 31
	s_mov_b32 s55, s76
	v_mov_b32_e32 v149, v145
	v_lshl_add_u32 v150, v11, 1, v0
	v_mov_b32_e32 v151, v145
	v_mov_b64_e32 v[152:153], 0x100
	v_mov_b64_e32 v[154:155], 0xff
	v_add_u32_e32 v161, s56, v159
	v_add_u32_e32 v162, s57, v159
	v_add_u32_e32 v163, 0, v2
	s_mov_b64 s[12:13], 0x80000
	s_mov_b64 s[14:15], 0x90000
	s_mov_b64 s[16:17], 0xa0000
	s_mov_b64 s[18:19], 0xb0000
	s_barrier
	s_branch .LBB0_567

.LBB0_574:
	ds_read_b128 v[128:131], v161
	ds_read_b128 v[132:135], v161 offset:1024
	ds_read_b128 v[136:139], v161 offset:2048
	ds_read_b128 v[140:143], v161 offset:3072
	ds_read_b128 v[164:167], v162
	ds_read_b128 v[168:171], v162 offset:1024
	ds_read_b128 v[172:175], v162 offset:2048
	ds_read_b128 v[176:179], v162 offset:3072
	s_add_u32 s38, s36, 0xfffc0080
	s_addc_u32 s39, s37, -1
	s_cmp_eq_u32 s63, 12
	s_cselect_b32 s41, s21, s39
	s_cselect_b32 s40, s23, s38
	s_cselect_b32 s39, s59, s62
	s_cselect_b32 s38, s60, s61
	s_add_i32 m0, s35, 0xc000
	ds_read_b128 v[180:183], v163
	ds_read_b128 v[184:187], v163 offset:1024
	ds_read_b128 v[188:191], v163 offset:2048
	ds_read_b128 v[192:195], v163 offset:3072
	ds_read_b128 v[196:199], v163 offset:4096
	ds_read_b128 v[200:203], v163 offset:5120
	ds_read_b128 v[204:207], v163 offset:6144
	ds_read_b128 v[208:211], v163 offset:7168
	global_load_lds_dwordx4 v150, s[36:37]
	s_add_i32 m0, s35, 0xe000
	s_nop 0
	global_load_lds_dwordx4 v148, s[36:37]
	s_waitcnt vmcnt(8)
	s_waitcnt lgkmcnt(0)
	s_barrier
	s_setprio 1
	s_waitcnt lgkmcnt(0)
	v_mfma_f32_16x16x32_bf16 v[124:127], v[128:131], v[180:183], v[124:127]
	v_mfma_f32_16x16x32_bf16 v[120:123], v[136:139], v[180:183], v[120:123]
	v_mfma_f32_16x16x32_bf16 v[112:115], v[128:131], v[188:191], v[112:115]
	v_mfma_f32_16x16x32_bf16 v[108:111], v[136:139], v[188:191], v[108:111]
	v_mfma_f32_16x16x32_bf16 v[96:99], v[128:131], v[196:199], v[96:99]
	v_mfma_f32_16x16x32_bf16 v[92:95], v[136:139], v[196:199], v[92:95]
	v_mfma_f32_16x16x32_bf16 v[80:83], v[128:131], v[204:207], v[80:83]
	v_mfma_f32_16x16x32_bf16 v[76:79], v[136:139], v[204:207], v[76:79]
	v_mfma_f32_16x16x32_bf16 v[124:127], v[132:135], v[184:187], v[124:127]
	v_mfma_f32_16x16x32_bf16 v[120:123], v[140:143], v[184:187], v[120:123]
	v_mfma_f32_16x16x32_bf16 v[112:115], v[132:135], v[192:195], v[112:115]
	v_mfma_f32_16x16x32_bf16 v[108:111], v[140:143], v[192:195], v[108:111]
	v_mfma_f32_16x16x32_bf16 v[96:99], v[132:135], v[200:203], v[96:99]
	v_mfma_f32_16x16x32_bf16 v[92:95], v[140:143], v[200:203], v[92:95]
	v_mfma_f32_16x16x32_bf16 v[80:83], v[132:135], v[208:211], v[80:83]
	v_mfma_f32_16x16x32_bf16 v[76:79], v[140:143], v[208:211], v[76:79]
	s_setprio 0
	s_setprio 1
	v_mfma_f32_16x16x32_bf16 v[116:119], v[164:167], v[180:183], v[116:119]
	v_mfma_f32_16x16x32_bf16 v[104:107], v[172:175], v[180:183], v[104:107]
	v_mfma_f32_16x16x32_bf16 v[100:103], v[164:167], v[188:191], v[100:103]
	v_mfma_f32_16x16x32_bf16 v[88:91], v[172:175], v[188:191], v[88:91]
	v_mfma_f32_16x16x32_bf16 v[84:87], v[164:167], v[196:199], v[84:87]
	v_mfma_f32_16x16x32_bf16 v[72:75], v[172:175], v[196:199], v[72:75]
	v_mfma_f32_16x16x32_bf16 v[68:71], v[164:167], v[204:207], v[68:71]
	v_mfma_f32_16x16x32_bf16 v[64:67], v[172:175], v[204:207], v[64:67]
	v_mfma_f32_16x16x32_bf16 v[116:119], v[168:171], v[184:187], v[116:119]
	v_mfma_f32_16x16x32_bf16 v[104:107], v[176:179], v[184:187], v[104:107]
	v_mfma_f32_16x16x32_bf16 v[100:103], v[168:171], v[192:195], v[100:103]
	v_mfma_f32_16x16x32_bf16 v[88:91], v[176:179], v[192:195], v[88:91]
	v_mfma_f32_16x16x32_bf16 v[84:87], v[168:171], v[200:203], v[84:87]
	v_mfma_f32_16x16x32_bf16 v[72:75], v[176:179], v[200:203], v[72:75]
	v_mfma_f32_16x16x32_bf16 v[68:71], v[168:171], v[208:211], v[68:71]
	v_mfma_f32_16x16x32_bf16 v[64:67], v[176:179], v[208:211], v[64:67]
	s_setprio 0
	s_barrier
	s_add_i32 s64, s56, s70
	v_lshl_add_u64 v[156:157], s[38:39], 0, v[144:145]
	s_mov_b32 m0, s64
	ds_read_b128 v[180:183], v163 offset:16384
	ds_read_b128 v[184:187], v163 offset:17408
	ds_read_b128 v[188:191], v163 offset:18432
	ds_read_b128 v[192:195], v163 offset:19456
	ds_read_b128 v[196:199], v163 offset:20480
	ds_read_b128 v[200:203], v163 offset:21504
	ds_read_b128 v[204:207], v163 offset:22528
	ds_read_b128 v[208:211], v163 offset:23552
	global_load_lds_dwordx4 v[156:157], off
	s_add_i32 m0, s64, 0x2000
	s_add_u32 s64, s38, 0x40000
	v_lshl_add_u64 v[212:213], s[38:39], 0, v[146:147]
	s_addc_u32 s65, s39, 0
	s_add_i32 s66, s57, s70
	global_load_lds_dwordx4 v[212:213], off
	s_mov_b32 m0, s66
	v_lshl_add_u64 v[216:217], s[40:41], 0, v[146:147]
	global_load_lds_dwordx4 v144, s[64:65]
	s_add_i32 m0, s66, 0x2000
	s_nop 0
	global_load_lds_dwordx4 v146, s[64:65]
	v_lshl_add_u64 v[214:215], s[40:41], 0, v[144:145]
	s_mov_b32 m0, s35
	s_nop 0
	global_load_lds_dwordx4 v[214:215], off
	s_mov_b32 m0, s46
	s_nop 0
	global_load_lds_dwordx4 v[216:217], off
	s_waitcnt vmcnt(8)
	s_waitcnt lgkmcnt(0)
	s_barrier
	s_setprio 1
	s_waitcnt lgkmcnt(0)
	v_mfma_f32_16x16x32_bf16 v[60:63], v[128:131], v[180:183], v[60:63]
	v_mfma_f32_16x16x32_bf16 v[56:59], v[136:139], v[180:183], v[56:59]
	v_mfma_f32_16x16x32_bf16 v[48:51], v[128:131], v[188:191], v[48:51]
	v_mfma_f32_16x16x32_bf16 v[44:47], v[136:139], v[188:191], v[44:47]
	v_mfma_f32_16x16x32_bf16 v[32:35], v[128:131], v[196:199], v[32:35]
	v_mfma_f32_16x16x32_bf16 v[28:31], v[136:139], v[196:199], v[28:31]
	v_mfma_f32_16x16x32_bf16 v[16:19], v[128:131], v[204:207], v[16:19]
	v_mfma_f32_16x16x32_bf16 v[12:15], v[136:139], v[204:207], v[12:15]
	v_mfma_f32_16x16x32_bf16 v[60:63], v[132:135], v[184:187], v[60:63]
	v_mfma_f32_16x16x32_bf16 v[56:59], v[140:143], v[184:187], v[56:59]
	v_mfma_f32_16x16x32_bf16 v[48:51], v[132:135], v[192:195], v[48:51]
	v_mfma_f32_16x16x32_bf16 v[44:47], v[140:143], v[192:195], v[44:47]
	v_mfma_f32_16x16x32_bf16 v[32:35], v[132:135], v[200:203], v[32:35]
	v_mfma_f32_16x16x32_bf16 v[28:31], v[140:143], v[200:203], v[28:31]
	v_mfma_f32_16x16x32_bf16 v[16:19], v[132:135], v[208:211], v[16:19]
	v_mfma_f32_16x16x32_bf16 v[12:15], v[140:143], v[208:211], v[12:15]
	s_setprio 0
	s_setprio 1
	v_mfma_f32_16x16x32_bf16 v[52:55], v[164:167], v[180:183], v[52:55]
	v_mfma_f32_16x16x32_bf16 v[40:43], v[172:175], v[180:183], v[40:43]
	v_mfma_f32_16x16x32_bf16 v[36:39], v[164:167], v[188:191], v[36:39]
	v_mfma_f32_16x16x32_bf16 v[24:27], v[172:175], v[188:191], v[24:27]
	v_mfma_f32_16x16x32_bf16 v[20:23], v[164:167], v[196:199], v[20:23]
	v_mfma_f32_16x16x32_bf16 v[8:11], v[172:175], v[196:199], v[8:11]
	v_mfma_f32_16x16x32_bf16 v[4:7], v[164:167], v[204:207], v[4:7]
	v_mfma_f32_16x16x32_bf16 v[0:3], v[172:175], v[204:207], v[0:3]
	v_mfma_f32_16x16x32_bf16 v[52:55], v[168:171], v[184:187], v[52:55]
	v_mfma_f32_16x16x32_bf16 v[40:43], v[176:179], v[184:187], v[40:43]
	v_mfma_f32_16x16x32_bf16 v[36:39], v[168:171], v[192:195], v[36:39]
	v_mfma_f32_16x16x32_bf16 v[24:27], v[176:179], v[192:195], v[24:27]
	v_mfma_f32_16x16x32_bf16 v[20:23], v[168:171], v[200:203], v[20:23]
	v_mfma_f32_16x16x32_bf16 v[8:11], v[176:179], v[200:203], v[8:11]
	v_mfma_f32_16x16x32_bf16 v[4:7], v[168:171], v[208:211], v[4:7]
	v_mfma_f32_16x16x32_bf16 v[0:3], v[176:179], v[208:211], v[0:3]
	s_setprio 0
	s_barrier
	s_add_i32 s64, 0, 0x18000
	s_add_i32 s65, 0, 0x1c000
	v_add_u32_e32 v140, s64, v159
	v_add_u32_e32 v176, s65, v159
	ds_read_b128 v[128:131], v140
	ds_read_b128 v[132:135], v140 offset:1024
	ds_read_b128 v[136:139], v140 offset:2048
	ds_read_b128 v[140:143], v140 offset:3072
	ds_read_b128 v[164:167], v176
	ds_read_b128 v[168:171], v176 offset:1024
	ds_read_b128 v[172:175], v176 offset:2048
	ds_read_b128 v[176:179], v176 offset:3072
	s_add_u32 s40, s40, 0x40000
	s_addc_u32 s41, s41, 0
	s_mov_b32 m0, s47
	ds_read_b128 v[180:183], v163 offset:32768
	ds_read_b128 v[184:187], v163 offset:33792
	ds_read_b128 v[188:191], v163 offset:34816
	ds_read_b128 v[192:195], v163 offset:35840
	ds_read_b128 v[196:199], v163 offset:36864
	ds_read_b128 v[200:203], v163 offset:37888
	ds_read_b128 v[204:207], v163 offset:38912
	ds_read_b128 v[208:211], v163 offset:39936
	global_load_lds_dwordx4 v144, s[40:41]
	s_mov_b32 m0, s48
	s_nop 0
	global_load_lds_dwordx4 v146, s[40:41]
	s_waitcnt vmcnt(8)
	s_waitcnt lgkmcnt(0)
	s_barrier
	s_setprio 1
	s_waitcnt lgkmcnt(0)
	v_mfma_f32_16x16x32_bf16 v[124:127], v[128:131], v[180:183], v[124:127]
	v_mfma_f32_16x16x32_bf16 v[120:123], v[136:139], v[180:183], v[120:123]
	v_mfma_f32_16x16x32_bf16 v[112:115], v[128:131], v[188:191], v[112:115]
	v_mfma_f32_16x16x32_bf16 v[108:111], v[136:139], v[188:191], v[108:111]
	v_mfma_f32_16x16x32_bf16 v[96:99], v[128:131], v[196:199], v[96:99]
	v_mfma_f32_16x16x32_bf16 v[92:95], v[136:139], v[196:199], v[92:95]
	v_mfma_f32_16x16x32_bf16 v[80:83], v[128:131], v[204:207], v[80:83]
	v_mfma_f32_16x16x32_bf16 v[76:79], v[136:139], v[204:207], v[76:79]
	v_mfma_f32_16x16x32_bf16 v[124:127], v[132:135], v[184:187], v[124:127]
	v_mfma_f32_16x16x32_bf16 v[120:123], v[140:143], v[184:187], v[120:123]
	v_mfma_f32_16x16x32_bf16 v[112:115], v[132:135], v[192:195], v[112:115]
	v_mfma_f32_16x16x32_bf16 v[108:111], v[140:143], v[192:195], v[108:111]
	v_mfma_f32_16x16x32_bf16 v[96:99], v[132:135], v[200:203], v[96:99]
	v_mfma_f32_16x16x32_bf16 v[92:95], v[140:143], v[200:203], v[92:95]
	v_mfma_f32_16x16x32_bf16 v[80:83], v[132:135], v[208:211], v[80:83]
	v_mfma_f32_16x16x32_bf16 v[76:79], v[140:143], v[208:211], v[76:79]
	s_setprio 0
	s_setprio 1
	v_mfma_f32_16x16x32_bf16 v[116:119], v[164:167], v[180:183], v[116:119]
	v_mfma_f32_16x16x32_bf16 v[104:107], v[172:175], v[180:183], v[104:107]
	v_mfma_f32_16x16x32_bf16 v[100:103], v[164:167], v[188:191], v[100:103]
	v_mfma_f32_16x16x32_bf16 v[88:91], v[172:175], v[188:191], v[88:91]
	v_mfma_f32_16x16x32_bf16 v[84:87], v[164:167], v[196:199], v[84:87]
	v_mfma_f32_16x16x32_bf16 v[72:75], v[172:175], v[196:199], v[72:75]
	v_mfma_f32_16x16x32_bf16 v[68:71], v[164:167], v[204:207], v[68:71]
	v_mfma_f32_16x16x32_bf16 v[64:67], v[172:175], v[204:207], v[64:67]
	v_mfma_f32_16x16x32_bf16 v[116:119], v[168:171], v[184:187], v[116:119]
	v_mfma_f32_16x16x32_bf16 v[104:107], v[176:179], v[184:187], v[104:107]
	v_mfma_f32_16x16x32_bf16 v[100:103], v[168:171], v[192:195], v[100:103]
	v_mfma_f32_16x16x32_bf16 v[88:91], v[176:179], v[192:195], v[88:91]
	v_mfma_f32_16x16x32_bf16 v[84:87], v[168:171], v[200:203], v[84:87]
	v_mfma_f32_16x16x32_bf16 v[72:75], v[176:179], v[200:203], v[72:75]
	v_mfma_f32_16x16x32_bf16 v[68:71], v[168:171], v[208:211], v[68:71]
	v_mfma_f32_16x16x32_bf16 v[64:67], v[176:179], v[208:211], v[64:67]
	s_setprio 0
	s_barrier
	s_add_i32 s40, s64, s70
	v_lshl_add_u64 v[156:157], v[156:157], 0, s[6:7]
	s_mov_b32 m0, s40
	ds_read_b128 v[180:183], v163 offset:49152
	ds_read_b128 v[184:187], v163 offset:50176
	ds_read_b128 v[188:191], v163 offset:51200
	ds_read_b128 v[192:195], v163 offset:52224
	ds_read_b128 v[196:199], v163 offset:53248
	ds_read_b128 v[200:203], v163 offset:54272
	ds_read_b128 v[204:207], v163 offset:55296
	ds_read_b128 v[208:211], v163 offset:56320
	global_load_lds_dwordx4 v[156:157], off
	s_add_i32 m0, s40, 0x2000
	s_add_u32 s38, s38, 0x40080
	v_lshl_add_u64 v[156:157], v[212:213], 0, s[6:7]
	s_addc_u32 s39, s39, 0
	s_add_i32 s40, s65, s70
	global_load_lds_dwordx4 v[156:157], off
	s_mov_b32 m0, s40
	s_nop 0
	global_load_lds_dwordx4 v144, s[38:39]
	s_add_i32 m0, s40, 0x2000
	s_nop 0
	global_load_lds_dwordx4 v146, s[38:39]
	v_lshl_add_u64 v[156:157], v[214:215], 0, s[6:7]
	s_mov_b32 m0, s52
	s_nop 0
	global_load_lds_dwordx4 v[156:157], off
	v_lshl_add_u64 v[156:157], v[216:217], 0, s[6:7]
	s_mov_b32 m0, s53
	s_nop 0
	global_load_lds_dwordx4 v[156:157], off
	s_waitcnt vmcnt(8)
	s_waitcnt lgkmcnt(0)
	s_barrier
	s_setprio 1
	s_waitcnt lgkmcnt(0)
	v_mfma_f32_16x16x32_bf16 v[60:63], v[128:131], v[180:183], v[60:63]
	v_mfma_f32_16x16x32_bf16 v[56:59], v[136:139], v[180:183], v[56:59]
	v_mfma_f32_16x16x32_bf16 v[48:51], v[128:131], v[188:191], v[48:51]
	v_mfma_f32_16x16x32_bf16 v[44:47], v[136:139], v[188:191], v[44:47]
	v_mfma_f32_16x16x32_bf16 v[32:35], v[128:131], v[196:199], v[32:35]
	v_mfma_f32_16x16x32_bf16 v[28:31], v[136:139], v[196:199], v[28:31]
	v_mfma_f32_16x16x32_bf16 v[16:19], v[128:131], v[204:207], v[16:19]
	v_mfma_f32_16x16x32_bf16 v[12:15], v[136:139], v[204:207], v[12:15]
	v_mfma_f32_16x16x32_bf16 v[60:63], v[132:135], v[184:187], v[60:63]
	v_mfma_f32_16x16x32_bf16 v[56:59], v[140:143], v[184:187], v[56:59]
	v_mfma_f32_16x16x32_bf16 v[48:51], v[132:135], v[192:195], v[48:51]
	v_mfma_f32_16x16x32_bf16 v[44:47], v[140:143], v[192:195], v[44:47]
	v_mfma_f32_16x16x32_bf16 v[32:35], v[132:135], v[200:203], v[32:35]
	v_mfma_f32_16x16x32_bf16 v[28:31], v[140:143], v[200:203], v[28:31]
	v_mfma_f32_16x16x32_bf16 v[16:19], v[132:135], v[208:211], v[16:19]
	v_mfma_f32_16x16x32_bf16 v[12:15], v[140:143], v[208:211], v[12:15]
	s_setprio 0
	s_setprio 1
	v_mfma_f32_16x16x32_bf16 v[52:55], v[164:167], v[180:183], v[52:55]
	v_mfma_f32_16x16x32_bf16 v[40:43], v[172:175], v[180:183], v[40:43]
	v_mfma_f32_16x16x32_bf16 v[36:39], v[164:167], v[188:191], v[36:39]
	v_mfma_f32_16x16x32_bf16 v[24:27], v[172:175], v[188:191], v[24:27]
	v_mfma_f32_16x16x32_bf16 v[20:23], v[164:167], v[196:199], v[20:23]
	v_mfma_f32_16x16x32_bf16 v[8:11], v[172:175], v[196:199], v[8:11]
	v_mfma_f32_16x16x32_bf16 v[4:7], v[164:167], v[204:207], v[4:7]
	v_mfma_f32_16x16x32_bf16 v[0:3], v[172:175], v[204:207], v[0:3]
	v_mfma_f32_16x16x32_bf16 v[52:55], v[168:171], v[184:187], v[52:55]
	v_mfma_f32_16x16x32_bf16 v[40:43], v[176:179], v[184:187], v[40:43]
	v_mfma_f32_16x16x32_bf16 v[36:39], v[168:171], v[192:195], v[36:39]
	v_mfma_f32_16x16x32_bf16 v[24:27], v[176:179], v[192:195], v[24:27]
	v_mfma_f32_16x16x32_bf16 v[20:23], v[168:171], v[200:203], v[20:23]
	v_mfma_f32_16x16x32_bf16 v[8:11], v[176:179], v[200:203], v[8:11]
	v_mfma_f32_16x16x32_bf16 v[4:7], v[168:171], v[208:211], v[4:7]
	v_mfma_f32_16x16x32_bf16 v[0:3], v[176:179], v[208:211], v[0:3]
	s_setprio 0
	s_barrier
	s_add_i32 s63, s63, 2
	s_add_u32 s61, s61, 0x100
	s_addc_u32 s62, s62, 0
	s_add_u32 s36, s36, 0x100
	s_addc_u32 s37, s37, 0
	s_cmp_gt_u32 s63, 13
	s_cbranch_scc0 .LBB0_574
	s_and_b64 vcc, exec, s[8:9]
	s_cbranch_vccz .LBB0_577
	s_barrier

.LBB0_699:
	s_add_u32 s12, s16, 0x4800000
	s_addc_u32 s13, s17, 0
	s_add_u32 s14, s16, 0x2000000
	v_and_b32_e32 v212, 15, v14
	v_readlane_b32 s4, v247, 6
	s_addc_u32 s15, s17, 0
	s_add_u32 s16, s16, 0x2160000
	v_or_b32_e32 v213, s4, v212
	v_lshlrev_b32_e32 v17, 6, v213
	v_and_b32_e32 v18, 48, v14
	s_movk_i32 s4, 0x3c0
	s_mov_b64 s[18:19], 0x80
	s_addc_u32 s17, s17, 0
	v_lshrrev_b32_e32 v16, 6, v14
	v_and_or_b32 v17, v17, s4, v18
	v_readlane_b32 s4, v247, 8
	s_add_i32 m0, s63, 0x18000
	v_lshl_add_u64 v[4:5], v[4:5], 0, s[18:19]
	v_lshl_add_u32 v19, v16, 10, s4
	v_readlane_b32 s4, v247, 10
	s_waitcnt vmcnt(2)
	s_barrier
	global_load_lds_dwordx4 v[4:5], off
	v_lshl_add_u64 v[2:3], v[2:3], 0, s[18:19]
	s_add_i32 m0, s63, 0x1a000
	s_add_i32 s68, s63, 0x8000
	s_add_i32 s69, s63, 0xa000
	v_add_lshl_u32 v16, v16, s4, 10
	global_load_lds_dwordx4 v[2:3], off
	v_lshl_add_u64 v[0:1], v[0:1], 0, s[18:19]
	s_mov_b32 m0, s68
	s_add_u32 s4, s10, 0x40080
	global_load_lds_dwordx4 v[0:1], off
	v_lshl_add_u64 v[0:1], v[6:7], 0, s[18:19]
	s_mov_b32 m0, s69
	s_addc_u32 s5, s11, 0
	global_load_lds_dwordx4 v[0:1], off
	s_add_i32 m0, s63, 0x1c000
	s_nop 0
	global_load_lds_dwordx4 v204, s[4:5]
	v_lshl_add_u64 v[0:1], s[4:5], 0, v[208:209]
	s_add_i32 m0, s63, 0x1e000
	v_readlane_b32 s4, v247, 7
	global_load_lds_dwordx4 v[0:1], off
	s_lshl_b32 s4, s4, 11
	s_add_i32 s8, s4, 0xffffc800
	s_cmpk_lt_u32 s75, 0x100
	v_lshlrev_b32_e32 v0, 10, v212
	s_cselect_b64 s[20:21], -1, 0
	v_add_u32_e32 v1, s8, v0
	v_cmp_gt_u32_e32 vcc, 2, v212
	s_and_b64 s[8:9], s[20:21], exec
	v_lshrrev_b32_e32 v15, 1, v14
	s_cselect_b32 s26, 0, 2
	s_and_b64 s[22:23], s[20:21], vcc
	v_and_b32_e32 v15, 56, v15
	v_readlane_b32 s4, v247, 9
	s_cmpk_gt_u32 s75, 0xff
	s_cselect_b64 s[8:9], -1, 0
	v_add_u32_e32 v214, s4, v15
	v_cmp_lt_u32_e64 s[4:5], 13, v212
	v_cndmask_b32_e64 v2, 0, 1, s[20:21]
	s_and_b64 s[24:25], s[8:9], s[4:5]
	s_ashr_i32 s70, s76, 31
	s_ashr_i32 s72, s80, 31
	v_or_b32_e32 v2, s26, v2
	s_add_u32 s26, s2, 0x2c00
	s_addc_u32 s27, s3, 0
	s_add_u32 s28, s0, 0x2c00
	s_addc_u32 s29, s1, 0
	s_add_u32 s30, s0, 0x5800
	s_addc_u32 s31, s1, 0
	s_add_u32 s34, s0, 0x8400
	s_addc_u32 s35, s1, 0
	s_add_u32 s36, s0, 0xb000
	s_addc_u32 s37, s1, 0
	s_add_u32 s38, s0, 0xdc00
	v_lshlrev_b32_e32 v2, 11, v2
	s_addc_u32 s39, s1, 0
	s_add_i32 s8, 0, 0x20000
	v_lshlrev_b32_e32 v3, 2, v214
	s_add_i32 s9, 0, 0x21000
	v_add_u32_e32 v2, s8, v2
	v_add3_u32 v228, s8, v1, v3
	v_add3_u32 v229, s9, v1, v3
	v_add3_u32 v1, s8, v0, v3
	v_add3_u32 v0, v2, v0, v3
	v_add_u32_e32 v232, 0xffffca00, v0
	v_add_u32_e32 v233, 0xffffc800, v0
	v_add_u32_e32 v236, 0xffffca10, v0
	v_add_u32_e32 v237, 0xffffc810, v0
	v_lshlrev_b32_e32 v0, 14, v11
	v_and_b32_e32 v0, 0xffff8000, v0
	v_add_u32_e32 v230, 0xffffca00, v1
	v_add_u32_e32 v231, 0xffffc800, v1
	v_add_u32_e32 v234, 0xffffca10, v1
	v_add_u32_e32 v235, 0xffffc810, v1
	v_lshl_add_u32 v0, v12, 11, v0
	v_and_b32_e32 v1, 1, v11
	v_lshl_or_b32 v0, v1, 6, v0
	v_lshl_add_u32 v218, v13, 1, v0
	v_lshlrev_b32_e32 v0, 14, v8
	v_lshlrev_b32_e32 v20, 2, v213
	v_lshlrev_b32_e32 v14, 2, v14
	v_and_b32_e32 v0, 0xffff8000, v0
	v_and_b32_e32 v20, 32, v20
	v_lshl_or_b32 v18, v212, 6, v18
	v_and_b32_e32 v14, 32, v14
	s_waitcnt vmcnt(6)
	v_lshl_add_u32 v0, v9, 11, v0
	v_and_b32_e32 v1, 1, v8
	v_bitop3_b32 v17, v17, v19, v20 bitop3:0xde
	v_bitop3_b32 v215, v18, v16, v14 bitop3:0xde
	v_lshl_or_b32 v0, v1, 6, v0
	s_add_i32 s73, 0, 0x10000
	s_add_i32 s74, 0, 0x14000
	v_add_u32_e32 v216, -14, v212
	v_mov_b32_e32 v217, v211
	s_mov_b32 s71, s76
	v_mov_b32_e32 v219, v211
	v_lshl_add_u32 v220, v10, 1, v0
	v_mov_b32_e32 v221, v211
	v_mov_b64_e32 v[222:223], 0x580
	v_mov_b64_e32 v[224:225], 0x57f
	v_add_u32_e32 v238, s73, v215
	v_add_u32_e32 v239, s74, v215
	v_add_u32_e32 v240, 0, v17
	s_movk_i32 s75, 0x2c00
	s_mov_b64 s[40:41], 0x1600
	s_movk_i32 s76, 0x1000
	s_movk_i32 s77, 0x1600
	v_mov_b32_e32 v241, 0x2c00
	s_barrier
	s_branch .LBB0_702

.LBB0_705:
	ds_read_b128 v[48:51], v238
	ds_read_b128 v[52:55], v238 offset:1024
	ds_read_b128 v[56:59], v238 offset:2048
	ds_read_b128 v[60:63], v238 offset:3072
	ds_read_b128 v[64:67], v239
	ds_read_b128 v[68:71], v239 offset:1024
	ds_read_b128 v[72:75], v239 offset:2048
	ds_read_b128 v[76:79], v239 offset:3072
	s_add_u32 s56, s10, 0xfffc0080
	s_addc_u32 s57, s11, -1
	s_cmp_eq_u32 s82, 12
	s_cselect_b32 s59, s43, s57
	s_cselect_b32 s58, s45, s56
	s_cselect_b32 s57, s55, s81
	s_cselect_b32 s56, s79, s80
	s_add_i32 m0, s63, 0xc000
	ds_read_b128 v[144:147], v240
	ds_read_b128 v[148:151], v240 offset:1024
	ds_read_b128 v[152:155], v240 offset:2048
	ds_read_b128 v[156:159], v240 offset:3072
	ds_read_b128 v[160:163], v240 offset:4096
	ds_read_b128 v[164:167], v240 offset:5120
	ds_read_b128 v[168:171], v240 offset:6144
	ds_read_b128 v[172:175], v240 offset:7168
	global_load_lds_dwordx4 v220, s[10:11]
	s_add_i32 m0, s63, 0xe000
	s_nop 0
	global_load_lds_dwordx4 v218, s[10:11]
	s_waitcnt vmcnt(8)
	s_waitcnt lgkmcnt(0)
	s_barrier
	s_setprio 1
	s_waitcnt lgkmcnt(0)
	v_mfma_f32_16x16x32_bf16 v[188:191], v[48:51], v[144:147], v[188:191]
	v_mfma_f32_16x16x32_bf16 v[92:95], v[56:59], v[144:147], v[92:95]
	v_mfma_f32_16x16x32_bf16 v[180:183], v[48:51], v[152:155], v[180:183]
	v_mfma_f32_16x16x32_bf16 v[84:87], v[56:59], v[152:155], v[84:87]
	v_mfma_f32_16x16x32_bf16 v[140:143], v[48:51], v[160:163], v[140:143]
	v_mfma_f32_16x16x32_bf16 v[44:47], v[56:59], v[160:163], v[44:47]
	v_mfma_f32_16x16x32_bf16 v[136:139], v[48:51], v[168:171], v[136:139]
	v_mfma_f32_16x16x32_bf16 v[40:43], v[56:59], v[168:171], v[40:43]
	v_mfma_f32_16x16x32_bf16 v[188:191], v[52:55], v[148:151], v[188:191]
	v_mfma_f32_16x16x32_bf16 v[92:95], v[60:63], v[148:151], v[92:95]
	v_mfma_f32_16x16x32_bf16 v[180:183], v[52:55], v[156:159], v[180:183]
	v_mfma_f32_16x16x32_bf16 v[84:87], v[60:63], v[156:159], v[84:87]
	v_mfma_f32_16x16x32_bf16 v[140:143], v[52:55], v[164:167], v[140:143]
	v_mfma_f32_16x16x32_bf16 v[44:47], v[60:63], v[164:167], v[44:47]
	v_mfma_f32_16x16x32_bf16 v[136:139], v[52:55], v[172:175], v[136:139]
	v_mfma_f32_16x16x32_bf16 v[40:43], v[60:63], v[172:175], v[40:43]
	s_setprio 0
	s_setprio 1
	v_mfma_f32_16x16x32_bf16 v[184:187], v[64:67], v[144:147], v[184:187]
	v_mfma_f32_16x16x32_bf16 v[88:91], v[72:75], v[144:147], v[88:91]
	v_mfma_f32_16x16x32_bf16 v[80:83], v[72:75], v[152:155], v[80:83]
	v_mfma_f32_16x16x32_bf16 v[132:135], v[64:67], v[160:163], v[132:135]
	v_mfma_f32_16x16x32_bf16 v[36:39], v[72:75], v[160:163], v[36:39]
	v_mfma_f32_16x16x32_bf16 v[128:131], v[64:67], v[168:171], v[128:131]
	v_mfma_f32_16x16x32_bf16 v[32:35], v[72:75], v[168:171], v[32:35]
	v_mfma_f32_16x16x32_bf16 v[184:187], v[68:71], v[148:151], v[184:187]
	v_mfma_f32_16x16x32_bf16 v[88:91], v[76:79], v[148:151], v[88:91]
	v_mfma_f32_16x16x32_bf16 v[144:147], v[64:67], v[152:155], v[176:179]
	v_mfma_f32_16x16x32_bf16 v[80:83], v[76:79], v[156:159], v[80:83]
	v_mfma_f32_16x16x32_bf16 v[132:135], v[68:71], v[164:167], v[132:135]
	v_mfma_f32_16x16x32_bf16 v[36:39], v[76:79], v[164:167], v[36:39]
	v_mfma_f32_16x16x32_bf16 v[128:131], v[68:71], v[172:175], v[128:131]
	v_mfma_f32_16x16x32_bf16 v[32:35], v[76:79], v[172:175], v[32:35]
	v_mfma_f32_16x16x32_bf16 v[144:147], v[68:71], v[156:159], v[144:147]
	s_setprio 0
	s_barrier
	s_add_i32 s83, s73, s86
	v_lshl_add_u64 v[200:201], s[56:57], 0, v[204:205]
	s_mov_b32 m0, s83
	ds_read_b128 v[148:151], v240 offset:16384
	ds_read_b128 v[152:155], v240 offset:17408
	ds_read_b128 v[156:159], v240 offset:18432
	ds_read_b128 v[160:163], v240 offset:19456
	ds_read_b128 v[164:167], v240 offset:20480
	ds_read_b128 v[168:171], v240 offset:21504
	ds_read_b128 v[172:175], v240 offset:22528
	ds_read_b128 v[176:179], v240 offset:23552
	global_load_lds_dwordx4 v[200:201], off
	s_add_i32 m0, s83, 0x2000
	s_add_u32 s84, s56, 0x40000
	v_lshl_add_u64 v[226:227], s[56:57], 0, v[208:209]
	s_addc_u32 s85, s57, 0
	s_add_i32 s83, s74, s86
	global_load_lds_dwordx4 v[226:227], off
	s_mov_b32 m0, s83
	v_lshl_add_u64 v[242:243], s[58:59], 0, v[202:203]
	global_load_lds_dwordx4 v204, s[84:85]
	s_add_i32 m0, s83, 0x2000
	v_lshl_add_u64 v[244:245], s[58:59], 0, v[206:207]
	global_load_lds_dwordx4 v208, s[84:85]
	s_mov_b32 m0, s63
	s_nop 0
	global_load_lds_dwordx4 v[242:243], off
	s_mov_b32 m0, s64
	s_nop 0
	global_load_lds_dwordx4 v[244:245], off
	s_waitcnt vmcnt(8)
	s_waitcnt lgkmcnt(0)
	s_barrier
	s_setprio 1
	s_waitcnt lgkmcnt(0)
	v_mfma_f32_16x16x32_bf16 v[124:127], v[48:51], v[148:151], v[124:127]
	v_mfma_f32_16x16x32_bf16 v[28:31], v[56:59], v[148:151], v[28:31]
	v_mfma_f32_16x16x32_bf16 v[116:119], v[48:51], v[156:159], v[116:119]
	v_mfma_f32_16x16x32_bf16 v[20:23], v[56:59], v[156:159], v[20:23]
	v_mfma_f32_16x16x32_bf16 v[108:111], v[48:51], v[164:167], v[108:111]
	v_mfma_f32_16x16x32_bf16 v[12:15], v[56:59], v[164:167], v[12:15]
	v_mfma_f32_16x16x32_bf16 v[8:11], v[56:59], v[172:175], v[8:11]
	v_mfma_f32_16x16x32_bf16 v[124:127], v[52:55], v[152:155], v[124:127]
	v_mfma_f32_16x16x32_bf16 v[28:31], v[60:63], v[152:155], v[28:31]
	v_mfma_f32_16x16x32_bf16 v[116:119], v[52:55], v[160:163], v[116:119]
	v_mfma_f32_16x16x32_bf16 v[20:23], v[60:63], v[160:163], v[20:23]
	v_mfma_f32_16x16x32_bf16 v[108:111], v[52:55], v[168:171], v[108:111]
	v_mfma_f32_16x16x32_bf16 v[12:15], v[60:63], v[168:171], v[12:15]
	v_mfma_f32_16x16x32_bf16 v[48:51], v[48:51], v[172:175], v[104:107]
	v_mfma_f32_16x16x32_bf16 v[8:11], v[60:63], v[176:179], v[8:11]
	v_mfma_f32_16x16x32_bf16 v[48:51], v[52:55], v[176:179], v[48:51]
	s_setprio 0
	s_setprio 1
	v_mfma_f32_16x16x32_bf16 v[24:27], v[72:75], v[148:151], v[24:27]
	v_mfma_f32_16x16x32_bf16 v[16:19], v[72:75], v[156:159], v[16:19]
	v_mfma_f32_16x16x32_bf16 v[4:7], v[72:75], v[164:167], v[4:7]
	v_mfma_f32_16x16x32_bf16 v[0:3], v[72:75], v[172:175], v[0:3]
	v_mfma_f32_16x16x32_bf16 v[52:55], v[64:67], v[148:151], v[120:123]
	v_mfma_f32_16x16x32_bf16 v[24:27], v[76:79], v[152:155], v[24:27]
	v_mfma_f32_16x16x32_bf16 v[56:59], v[64:67], v[156:159], v[112:115]
	v_mfma_f32_16x16x32_bf16 v[16:19], v[76:79], v[160:163], v[16:19]
	v_mfma_f32_16x16x32_bf16 v[60:63], v[64:67], v[164:167], v[100:103]
	v_mfma_f32_16x16x32_bf16 v[4:7], v[76:79], v[168:171], v[4:7]
	v_mfma_f32_16x16x32_bf16 v[64:67], v[64:67], v[172:175], v[96:99]
	v_mfma_f32_16x16x32_bf16 v[0:3], v[76:79], v[176:179], v[0:3]
	v_mfma_f32_16x16x32_bf16 v[52:55], v[68:71], v[152:155], v[52:55]
	v_mfma_f32_16x16x32_bf16 v[56:59], v[68:71], v[160:163], v[56:59]
	v_mfma_f32_16x16x32_bf16 v[60:63], v[68:71], v[168:171], v[60:63]
	v_mfma_f32_16x16x32_bf16 v[64:67], v[68:71], v[176:179], v[64:67]
	s_setprio 0
	s_barrier
	s_add_i32 s83, 0, 0x18000
	s_add_i32 s84, 0, 0x1c000
	v_add_u32_e32 v96, s83, v215
	v_add_u32_e32 v100, s84, v215
	ds_read_b128 v[68:71], v96
	ds_read_b128 v[72:75], v96 offset:1024
	ds_read_b128 v[76:79], v96 offset:2048
	ds_read_b128 v[96:99], v96 offset:3072
	ds_read_b128 v[148:151], v100
	ds_read_b128 v[152:155], v100 offset:1024
	ds_read_b128 v[156:159], v100 offset:2048
	ds_read_b128 v[160:163], v100 offset:3072
	s_add_u32 s58, s58, 0x40000
	s_addc_u32 s59, s59, 0
	s_mov_b32 m0, s65
	ds_read_b128 v[100:103], v240 offset:32768
	ds_read_b128 v[104:107], v240 offset:33792
	ds_read_b128 v[112:115], v240 offset:34816
	ds_read_b128 v[120:123], v240 offset:35840
	ds_read_b128 v[164:167], v240 offset:36864
	ds_read_b128 v[168:171], v240 offset:37888
	ds_read_b128 v[172:175], v240 offset:38912
	ds_read_b128 v[192:195], v240 offset:39936
	global_load_lds_dwordx4 v202, s[58:59]
	s_mov_b32 m0, s66
	s_nop 0
	global_load_lds_dwordx4 v206, s[58:59]
	s_waitcnt vmcnt(8)
	s_waitcnt lgkmcnt(0)
	s_barrier
	s_setprio 1
	s_waitcnt lgkmcnt(0)
	v_mfma_f32_16x16x32_bf16 v[176:179], v[68:71], v[100:103], v[188:191]
	v_mfma_f32_16x16x32_bf16 v[188:191], v[72:75], v[104:107], v[176:179]
	v_mfma_f32_16x16x32_bf16 v[92:95], v[76:79], v[100:103], v[92:95]
	v_mfma_f32_16x16x32_bf16 v[176:179], v[68:71], v[112:115], v[180:183]
	v_mfma_f32_16x16x32_bf16 v[84:87], v[76:79], v[112:115], v[84:87]
	v_mfma_f32_16x16x32_bf16 v[140:143], v[68:71], v[164:167], v[140:143]
	v_mfma_f32_16x16x32_bf16 v[44:47], v[76:79], v[164:167], v[44:47]
	v_mfma_f32_16x16x32_bf16 v[136:139], v[68:71], v[172:175], v[136:139]
	v_mfma_f32_16x16x32_bf16 v[40:43], v[76:79], v[172:175], v[40:43]
	v_mfma_f32_16x16x32_bf16 v[92:95], v[96:99], v[104:107], v[92:95]
	v_mfma_f32_16x16x32_bf16 v[180:183], v[72:75], v[120:123], v[176:179]
	v_mfma_f32_16x16x32_bf16 v[84:87], v[96:99], v[120:123], v[84:87]
	v_mfma_f32_16x16x32_bf16 v[140:143], v[72:75], v[168:171], v[140:143]
	v_mfma_f32_16x16x32_bf16 v[44:47], v[96:99], v[168:171], v[44:47]
	v_mfma_f32_16x16x32_bf16 v[136:139], v[72:75], v[192:195], v[136:139]
	v_mfma_f32_16x16x32_bf16 v[40:43], v[96:99], v[192:195], v[40:43]
	s_setprio 0
	s_setprio 1
	v_mfma_f32_16x16x32_bf16 v[176:179], v[148:151], v[100:103], v[184:187]
	v_mfma_f32_16x16x32_bf16 v[88:91], v[156:159], v[100:103], v[88:91]
	v_mfma_f32_16x16x32_bf16 v[100:103], v[148:151], v[112:115], v[144:147]
	v_mfma_f32_16x16x32_bf16 v[184:187], v[152:155], v[104:107], v[176:179]
	v_mfma_f32_16x16x32_bf16 v[176:179], v[152:155], v[120:123], v[100:103]
	v_mfma_f32_16x16x32_bf16 v[100:103], v[148:151], v[164:167], v[132:135]
	v_mfma_f32_16x16x32_bf16 v[80:83], v[156:159], v[112:115], v[80:83]
	v_mfma_f32_16x16x32_bf16 v[132:135], v[152:155], v[168:171], v[100:103]
	v_mfma_f32_16x16x32_bf16 v[36:39], v[156:159], v[164:167], v[36:39]
	v_mfma_f32_16x16x32_bf16 v[100:103], v[148:151], v[172:175], v[128:131]
	v_mfma_f32_16x16x32_bf16 v[32:35], v[156:159], v[172:175], v[32:35]
	v_mfma_f32_16x16x32_bf16 v[88:91], v[160:163], v[104:107], v[88:91]
	v_mfma_f32_16x16x32_bf16 v[80:83], v[160:163], v[120:123], v[80:83]
	v_mfma_f32_16x16x32_bf16 v[36:39], v[160:163], v[168:171], v[36:39]
	v_mfma_f32_16x16x32_bf16 v[128:131], v[152:155], v[192:195], v[100:103]
	v_mfma_f32_16x16x32_bf16 v[32:35], v[160:163], v[192:195], v[32:35]
	s_setprio 0
	s_barrier
	s_add_i32 s58, s83, s86
	v_lshl_add_u64 v[104:105], v[200:201], 0, s[18:19]
	s_mov_b32 m0, s58
	ds_read_b128 v[100:103], v240 offset:49152
	ds_read_b128 v[112:115], v240 offset:50176
	ds_read_b128 v[144:147], v240 offset:51200
	ds_read_b128 v[164:167], v240 offset:52224
	ds_read_b128 v[168:171], v240 offset:53248
	ds_read_b128 v[172:175], v240 offset:54272
	ds_read_b128 v[192:195], v240 offset:55296
	ds_read_b128 v[196:199], v240 offset:56320
	global_load_lds_dwordx4 v[104:105], off
	s_add_i32 m0, s58, 0x2000
	s_add_u32 s56, s56, 0x40080
	v_lshl_add_u64 v[104:105], v[226:227], 0, s[18:19]
	s_addc_u32 s57, s57, 0
	s_add_i32 s58, s84, s86
	global_load_lds_dwordx4 v[104:105], off
	s_mov_b32 m0, s58
	s_nop 0
	global_load_lds_dwordx4 v204, s[56:57]
	s_add_i32 m0, s58, 0x2000
	s_nop 0
	global_load_lds_dwordx4 v208, s[56:57]
	v_lshl_add_u64 v[104:105], v[242:243], 0, s[18:19]
	s_mov_b32 m0, s68
	s_nop 0
	global_load_lds_dwordx4 v[104:105], off
	v_lshl_add_u64 v[104:105], v[244:245], 0, s[18:19]
	s_mov_b32 m0, s69
	s_nop 0
	global_load_lds_dwordx4 v[104:105], off
	s_waitcnt vmcnt(8)
	s_waitcnt lgkmcnt(0)
	s_barrier
	s_setprio 1
	s_waitcnt lgkmcnt(0)
	v_mfma_f32_16x16x32_bf16 v[104:107], v[68:71], v[100:103], v[124:127]
	v_mfma_f32_16x16x32_bf16 v[124:127], v[72:75], v[112:115], v[104:107]
	v_mfma_f32_16x16x32_bf16 v[104:107], v[68:71], v[144:147], v[116:119]
	v_mfma_f32_16x16x32_bf16 v[28:31], v[76:79], v[100:103], v[28:31]
	v_mfma_f32_16x16x32_bf16 v[116:119], v[72:75], v[164:167], v[104:107]
	v_mfma_f32_16x16x32_bf16 v[20:23], v[76:79], v[144:147], v[20:23]
	v_mfma_f32_16x16x32_bf16 v[104:107], v[68:71], v[168:171], v[108:111]
	v_mfma_f32_16x16x32_bf16 v[12:15], v[76:79], v[168:171], v[12:15]
	v_mfma_f32_16x16x32_bf16 v[48:51], v[68:71], v[192:195], v[48:51]
	v_mfma_f32_16x16x32_bf16 v[8:11], v[76:79], v[192:195], v[8:11]
	v_mfma_f32_16x16x32_bf16 v[28:31], v[96:99], v[112:115], v[28:31]
	v_mfma_f32_16x16x32_bf16 v[20:23], v[96:99], v[164:167], v[20:23]
	v_mfma_f32_16x16x32_bf16 v[108:111], v[72:75], v[172:175], v[104:107]
	v_mfma_f32_16x16x32_bf16 v[12:15], v[96:99], v[172:175], v[12:15]
	v_mfma_f32_16x16x32_bf16 v[104:107], v[72:75], v[196:199], v[48:51]
	v_mfma_f32_16x16x32_bf16 v[8:11], v[96:99], v[196:199], v[8:11]
	s_setprio 0
	s_setprio 1
	v_mfma_f32_16x16x32_bf16 v[48:51], v[148:151], v[100:103], v[52:55]
	v_mfma_f32_16x16x32_bf16 v[120:123], v[152:155], v[112:115], v[48:51]
	v_mfma_f32_16x16x32_bf16 v[24:27], v[156:159], v[100:103], v[24:27]
	v_mfma_f32_16x16x32_bf16 v[48:51], v[148:151], v[144:147], v[56:59]
	v_mfma_f32_16x16x32_bf16 v[24:27], v[160:163], v[112:115], v[24:27]
	v_mfma_f32_16x16x32_bf16 v[112:115], v[152:155], v[164:167], v[48:51]
	v_mfma_f32_16x16x32_bf16 v[48:51], v[148:151], v[168:171], v[60:63]
	v_mfma_f32_16x16x32_bf16 v[16:19], v[156:159], v[144:147], v[16:19]
	v_mfma_f32_16x16x32_bf16 v[100:103], v[152:155], v[172:175], v[48:51]
	v_mfma_f32_16x16x32_bf16 v[4:7], v[156:159], v[168:171], v[4:7]
	v_mfma_f32_16x16x32_bf16 v[48:51], v[148:151], v[192:195], v[64:67]
	v_mfma_f32_16x16x32_bf16 v[0:3], v[156:159], v[192:195], v[0:3]
	v_mfma_f32_16x16x32_bf16 v[16:19], v[160:163], v[164:167], v[16:19]
	v_mfma_f32_16x16x32_bf16 v[4:7], v[160:163], v[172:175], v[4:7]
	v_mfma_f32_16x16x32_bf16 v[96:99], v[152:155], v[196:199], v[48:51]
	v_mfma_f32_16x16x32_bf16 v[0:3], v[160:163], v[196:199], v[0:3]
	s_setprio 0
	s_barrier
	s_add_i32 s82, s82, 2
	s_add_u32 s80, s80, 0x100
	s_addc_u32 s81, s81, 0
	s_add_u32 s10, s10, 0x100
	s_addc_u32 s11, s11, 0
	s_cmp_gt_u32 s82, 13
	s_cbranch_scc0 .LBB0_705
	s_and_b64 vcc, exec, s[20:21]
	s_cbranch_vccz .LBB0_708
	s_barrier

.LBB0_805:
	s_add_u32 s45, s30, 0x1c05000
	s_mov_b64 s[8:9], 0x80
	s_addc_u32 s46, s31, 0
	s_add_i32 m0, s40, 0x18000
	v_lshl_add_u64 v[6:7], v[6:7], 0, s[8:9]
	s_waitcnt vmcnt(2)
	s_barrier
	global_load_lds_dwordx4 v[6:7], off
	v_lshl_add_u64 v[4:5], v[4:5], 0, s[8:9]
	s_add_i32 m0, s40, 0x1a000
	s_add_i32 s47, s40, 0x8000
	s_add_i32 s48, s40, 0xa000
	global_load_lds_dwordx4 v[4:5], off
	v_lshl_add_u64 v[0:1], v[0:1], 0, s[8:9]
	s_mov_b32 m0, s47
	s_add_u32 s10, s28, 0xb0080
	global_load_lds_dwordx4 v[0:1], off
	v_lshl_add_u64 v[0:1], v[2:3], 0, s[8:9]
	s_mov_b32 m0, s48
	s_addc_u32 s11, s29, 0
	global_load_lds_dwordx4 v[0:1], off
	s_add_i32 m0, s40, 0x1c000
	s_nop 0
	global_load_lds_dwordx4 v144, s[10:11]
	v_lshl_add_u64 v[0:1], s[10:11], 0, v[146:147]
	s_add_i32 m0, s40, 0x1e000
	s_sext_i32_i8 s58, s1
	global_load_lds_dwordx4 v[0:1], off
	v_and_b32_e32 v0, 15, v9
	v_readlane_b32 s1, v247, 6
	v_and_b32_e32 v3, 48, v9
	v_lshrrev_b32_e32 v1, 6, v9
	v_or_b32_e32 v162, s1, v0
	v_lshlrev_b32_e32 v2, 6, v162
	s_movk_i32 s1, 0x3c0
	v_and_or_b32 v2, v2, s1, v3
	v_readlane_b32 s1, v247, 8
	v_lshl_or_b32 v0, v0, 6, v3
	v_lshlrev_b32_e32 v3, 2, v9
	v_lshl_add_u32 v4, v1, 10, s1
	v_readlane_b32 s1, v247, 10
	v_and_b32_e32 v3, 32, v3
	s_mov_b64 s[12:13], 0xb0080
	v_add_lshl_u32 v1, v1, s1, 10
	v_bitop3_b32 v163, v0, v1, v3 bitop3:0xde
	v_lshrrev_b32_e32 v0, 2, v9
	v_and_b32_e32 v0, 28, v0
	v_readlane_b32 s1, v247, 9
	v_lshrrev_b32_e32 v1, 1, v13
	v_lshlrev_b32_e32 v5, 2, v162
	v_add_u32_e32 v164, s1, v0
	v_mul_lo_u32 v0, v15, s0
	s_mov_b32 s1, 0xb000
	v_mad_u64_u32 v[0:1], s[14:15], v1, s1, v[0:1]
	v_or_b32_e32 v0, v0, v14
	v_add_lshl_u32 v0, v0, v16, 1
	v_mov_b32_e32 v1, v145
	v_lshl_add_u64 v[148:149], v[0:1], 0, s[12:13]
	v_lshrrev_b32_e32 v1, 1, v8
	v_mul_lo_u32 v0, v10, s0
	v_mad_u64_u32 v[0:1], s[0:1], v1, s1, v[0:1]
	v_and_b32_e32 v5, 32, v5
	s_waitcnt vmcnt(6)
	s_cmpk_lt_u32 s75, 0x100
	v_or_b32_e32 v0, v0, v11
	v_bitop3_b32 v2, v2, v4, v5 bitop3:0xde
	s_cselect_b64 s[10:11], -1, 0
	v_add_lshl_u32 v0, v0, v12, 1
	v_mov_b32_e32 v1, v145
	s_add_i32 s49, 0, 0x10000
	s_add_i32 s50, 0, 0x14000
	v_lshl_add_u64 v[150:151], v[0:1], 0, s[12:13]
	v_mov_b64_e32 v[152:153], 0x100
	v_mov_b64_e32 v[154:155], 0xff
	v_add_u32_e32 v165, s49, v163
	v_add_u32_e32 v166, s50, v163
	v_add_u32_e32 v167, 0, v2
	s_mov_b64 s[12:13], 0x80000
	s_mov_b32 s51, 0x80000
	s_mov_b64 s[14:15], 0x90000
	s_mov_b32 s52, 0x90000
	s_mov_b64 s[16:17], 0xa0000
	s_mov_b32 s53, 0xa0000
	s_mov_b32 s54, 0xb0000
	s_barrier
	s_branch .LBB0_808

.LBB0_815:
	ds_read_b128 v[64:67], v165
	ds_read_b128 v[108:111], v165 offset:1024
	ds_read_b128 v[116:119], v165 offset:2048
	ds_read_b128 v[128:131], v165 offset:3072
	ds_read_b128 v[156:159], v166
	ds_read_b128 v[168:171], v166 offset:1024
	ds_read_b128 v[172:175], v166 offset:2048
	ds_read_b128 v[176:179], v166 offset:3072
	s_add_u32 s28, s26, 0x100
	s_addc_u32 s29, s27, 0
	s_cmp_eq_u32 s65, 40
	s_cselect_b32 s35, s59, s29
	s_cselect_b32 s34, s60, s28
	s_cselect_b32 s31, s61, s64
	s_cselect_b32 s30, s62, s63
	v_lshl_add_u64 v[160:161], s[26:27], 0, v[150:151]
	s_add_i32 m0, s40, 0xc000
	ds_read_b128 v[180:183], v167
	ds_read_b128 v[184:187], v167 offset:1024
	ds_read_b128 v[188:191], v167 offset:2048
	ds_read_b128 v[192:195], v167 offset:3072
	ds_read_b128 v[196:199], v167 offset:4096
	ds_read_b128 v[200:203], v167 offset:5120
	ds_read_b128 v[204:207], v167 offset:6144
	ds_read_b128 v[208:211], v167 offset:7168
	global_load_lds_dwordx4 v[160:161], off
	v_lshl_add_u64 v[160:161], s[26:27], 0, v[148:149]
	s_add_i32 m0, s40, 0xe000
	s_nop 0
	global_load_lds_dwordx4 v[160:161], off
	s_waitcnt vmcnt(8)
	s_waitcnt lgkmcnt(0)
	s_barrier
	s_setprio 1
	s_waitcnt lgkmcnt(0)
	v_mfma_f32_16x16x32_bf16 v[140:143], v[64:67], v[180:183], v[140:143]
	v_mfma_f32_16x16x32_bf16 v[136:139], v[116:119], v[180:183], v[136:139]
	v_mfma_f32_16x16x32_bf16 v[120:123], v[64:67], v[188:191], v[120:123]
	v_mfma_f32_16x16x32_bf16 v[112:115], v[116:119], v[188:191], v[112:115]
	v_mfma_f32_16x16x32_bf16 v[96:99], v[64:67], v[196:199], v[96:99]
	v_mfma_f32_16x16x32_bf16 v[92:95], v[116:119], v[196:199], v[92:95]
	v_mfma_f32_16x16x32_bf16 v[80:83], v[64:67], v[204:207], v[80:83]
	v_mfma_f32_16x16x32_bf16 v[76:79], v[116:119], v[204:207], v[76:79]
	v_mfma_f32_16x16x32_bf16 v[140:143], v[108:111], v[184:187], v[140:143]
	v_mfma_f32_16x16x32_bf16 v[136:139], v[128:131], v[184:187], v[136:139]
	v_mfma_f32_16x16x32_bf16 v[120:123], v[108:111], v[192:195], v[120:123]
	v_mfma_f32_16x16x32_bf16 v[112:115], v[128:131], v[192:195], v[112:115]
	v_mfma_f32_16x16x32_bf16 v[96:99], v[108:111], v[200:203], v[96:99]
	v_mfma_f32_16x16x32_bf16 v[92:95], v[128:131], v[200:203], v[92:95]
	v_mfma_f32_16x16x32_bf16 v[80:83], v[108:111], v[208:211], v[80:83]
	v_mfma_f32_16x16x32_bf16 v[76:79], v[128:131], v[208:211], v[76:79]
	s_setprio 0
	s_setprio 1
	v_mfma_f32_16x16x32_bf16 v[132:135], v[156:159], v[180:183], v[132:135]
	v_mfma_f32_16x16x32_bf16 v[124:127], v[172:175], v[180:183], v[124:127]
	v_mfma_f32_16x16x32_bf16 v[104:107], v[156:159], v[188:191], v[104:107]
	v_mfma_f32_16x16x32_bf16 v[100:103], v[172:175], v[188:191], v[100:103]
	v_mfma_f32_16x16x32_bf16 v[88:91], v[156:159], v[196:199], v[88:91]
	v_mfma_f32_16x16x32_bf16 v[84:87], v[172:175], v[196:199], v[84:87]
	v_mfma_f32_16x16x32_bf16 v[72:75], v[156:159], v[204:207], v[72:75]
	v_mfma_f32_16x16x32_bf16 v[68:71], v[172:175], v[204:207], v[68:71]
	v_mfma_f32_16x16x32_bf16 v[132:135], v[168:171], v[184:187], v[132:135]
	v_mfma_f32_16x16x32_bf16 v[124:127], v[176:179], v[184:187], v[124:127]
	v_mfma_f32_16x16x32_bf16 v[104:107], v[168:171], v[192:195], v[104:107]
	v_mfma_f32_16x16x32_bf16 v[100:103], v[176:179], v[192:195], v[100:103]
	v_mfma_f32_16x16x32_bf16 v[88:91], v[168:171], v[200:203], v[88:91]
	v_mfma_f32_16x16x32_bf16 v[84:87], v[176:179], v[200:203], v[84:87]
	v_mfma_f32_16x16x32_bf16 v[72:75], v[168:171], v[208:211], v[72:75]
	v_mfma_f32_16x16x32_bf16 v[68:71], v[176:179], v[208:211], v[68:71]
	s_setprio 0
	s_barrier
	s_add_i32 s26, s49, s68
	v_lshl_add_u64 v[160:161], s[30:31], 0, v[144:145]
	s_mov_b32 m0, s26
	ds_read_b128 v[180:183], v167 offset:16384
	ds_read_b128 v[184:187], v167 offset:17408
	ds_read_b128 v[188:191], v167 offset:18432
	ds_read_b128 v[192:195], v167 offset:19456
	ds_read_b128 v[196:199], v167 offset:20480
	ds_read_b128 v[200:203], v167 offset:21504
	ds_read_b128 v[204:207], v167 offset:22528
	ds_read_b128 v[208:211], v167 offset:23552
	global_load_lds_dwordx4 v[160:161], off
	s_add_i32 m0, s26, 0x2000
	s_add_u32 s26, s30, 0xb0000
	v_lshl_add_u64 v[212:213], s[30:31], 0, v[146:147]
	s_addc_u32 s27, s31, 0
	s_add_i32 s66, s50, s68
	global_load_lds_dwordx4 v[212:213], off
	s_mov_b32 m0, s66
	v_lshl_add_u64 v[216:217], s[34:35], 0, v[146:147]
	global_load_lds_dwordx4 v144, s[26:27]
	s_add_i32 m0, s66, 0x2000
	s_nop 0
	global_load_lds_dwordx4 v146, s[26:27]
	v_lshl_add_u64 v[214:215], s[34:35], 0, v[144:145]
	s_mov_b32 m0, s40
	s_nop 0
	global_load_lds_dwordx4 v[214:215], off
	s_mov_b32 m0, s41
	s_nop 0
	global_load_lds_dwordx4 v[216:217], off
	s_waitcnt vmcnt(8)
	s_waitcnt lgkmcnt(0)
	s_barrier
	s_setprio 1
	s_waitcnt lgkmcnt(0)
	v_mfma_f32_16x16x32_bf16 v[60:63], v[64:67], v[180:183], v[60:63]
	v_mfma_f32_16x16x32_bf16 v[56:59], v[116:119], v[180:183], v[56:59]
	v_mfma_f32_16x16x32_bf16 v[44:47], v[64:67], v[188:191], v[44:47]
	v_mfma_f32_16x16x32_bf16 v[40:43], v[116:119], v[188:191], v[40:43]
	v_mfma_f32_16x16x32_bf16 v[28:31], v[64:67], v[196:199], v[28:31]
	v_mfma_f32_16x16x32_bf16 v[24:27], v[116:119], v[196:199], v[24:27]
	v_mfma_f32_16x16x32_bf16 v[12:15], v[64:67], v[204:207], v[12:15]
	v_mfma_f32_16x16x32_bf16 v[8:11], v[116:119], v[204:207], v[8:11]
	v_mfma_f32_16x16x32_bf16 v[60:63], v[108:111], v[184:187], v[60:63]
	v_mfma_f32_16x16x32_bf16 v[56:59], v[128:131], v[184:187], v[56:59]
	v_mfma_f32_16x16x32_bf16 v[44:47], v[108:111], v[192:195], v[44:47]
	v_mfma_f32_16x16x32_bf16 v[40:43], v[128:131], v[192:195], v[40:43]
	v_mfma_f32_16x16x32_bf16 v[28:31], v[108:111], v[200:203], v[28:31]
	v_mfma_f32_16x16x32_bf16 v[24:27], v[128:131], v[200:203], v[24:27]
	v_mfma_f32_16x16x32_bf16 v[12:15], v[108:111], v[208:211], v[12:15]
	v_mfma_f32_16x16x32_bf16 v[8:11], v[128:131], v[208:211], v[8:11]
	s_setprio 0
	s_setprio 1
	v_mfma_f32_16x16x32_bf16 v[52:55], v[156:159], v[180:183], v[52:55]
	v_mfma_f32_16x16x32_bf16 v[48:51], v[172:175], v[180:183], v[48:51]
	v_mfma_f32_16x16x32_bf16 v[36:39], v[156:159], v[188:191], v[36:39]
	v_mfma_f32_16x16x32_bf16 v[32:35], v[172:175], v[188:191], v[32:35]
	v_mfma_f32_16x16x32_bf16 v[20:23], v[156:159], v[196:199], v[20:23]
	v_mfma_f32_16x16x32_bf16 v[16:19], v[172:175], v[196:199], v[16:19]
	v_mfma_f32_16x16x32_bf16 v[4:7], v[156:159], v[204:207], v[4:7]
	v_mfma_f32_16x16x32_bf16 v[0:3], v[172:175], v[204:207], v[0:3]
	v_mfma_f32_16x16x32_bf16 v[52:55], v[168:171], v[184:187], v[52:55]
	v_mfma_f32_16x16x32_bf16 v[48:51], v[176:179], v[184:187], v[48:51]
	v_mfma_f32_16x16x32_bf16 v[36:39], v[168:171], v[192:195], v[36:39]
	v_mfma_f32_16x16x32_bf16 v[32:35], v[176:179], v[192:195], v[32:35]
	v_mfma_f32_16x16x32_bf16 v[20:23], v[168:171], v[200:203], v[20:23]
	v_mfma_f32_16x16x32_bf16 v[16:19], v[176:179], v[200:203], v[16:19]
	v_mfma_f32_16x16x32_bf16 v[4:7], v[168:171], v[208:211], v[4:7]
	v_mfma_f32_16x16x32_bf16 v[0:3], v[176:179], v[208:211], v[0:3]
	s_setprio 0
	s_barrier
	s_add_i32 s66, 0, 0x18000
	s_add_i32 s67, 0, 0x1c000
	v_add_u32_e32 v128, s66, v163
	v_add_u32_e32 v176, s67, v163
	ds_read_b128 v[64:67], v128
	ds_read_b128 v[108:111], v128 offset:1024
	ds_read_b128 v[116:119], v128 offset:2048
	ds_read_b128 v[128:131], v128 offset:3072
	ds_read_b128 v[156:159], v176
	ds_read_b128 v[168:171], v176 offset:1024
	ds_read_b128 v[172:175], v176 offset:2048
	ds_read_b128 v[176:179], v176 offset:3072
	s_add_u32 s26, s34, 0xb0000
	s_addc_u32 s27, s35, 0
	s_mov_b32 m0, s42
	ds_read_b128 v[180:183], v167 offset:32768
	ds_read_b128 v[184:187], v167 offset:33792
	ds_read_b128 v[188:191], v167 offset:34816
	ds_read_b128 v[192:195], v167 offset:35840
	ds_read_b128 v[196:199], v167 offset:36864
	ds_read_b128 v[200:203], v167 offset:37888
	ds_read_b128 v[204:207], v167 offset:38912
	ds_read_b128 v[208:211], v167 offset:39936
	global_load_lds_dwordx4 v144, s[26:27]
	s_mov_b32 m0, s43
	s_nop 0
	global_load_lds_dwordx4 v146, s[26:27]
	s_waitcnt vmcnt(8)
	s_waitcnt lgkmcnt(0)
	s_barrier
	s_setprio 1
	s_waitcnt lgkmcnt(0)
	v_mfma_f32_16x16x32_bf16 v[140:143], v[64:67], v[180:183], v[140:143]
	v_mfma_f32_16x16x32_bf16 v[136:139], v[116:119], v[180:183], v[136:139]
	v_mfma_f32_16x16x32_bf16 v[120:123], v[64:67], v[188:191], v[120:123]
	v_mfma_f32_16x16x32_bf16 v[112:115], v[116:119], v[188:191], v[112:115]
	v_mfma_f32_16x16x32_bf16 v[96:99], v[64:67], v[196:199], v[96:99]
	v_mfma_f32_16x16x32_bf16 v[92:95], v[116:119], v[196:199], v[92:95]
	v_mfma_f32_16x16x32_bf16 v[80:83], v[64:67], v[204:207], v[80:83]
	v_mfma_f32_16x16x32_bf16 v[76:79], v[116:119], v[204:207], v[76:79]
	v_mfma_f32_16x16x32_bf16 v[140:143], v[108:111], v[184:187], v[140:143]
	v_mfma_f32_16x16x32_bf16 v[136:139], v[128:131], v[184:187], v[136:139]
	v_mfma_f32_16x16x32_bf16 v[120:123], v[108:111], v[192:195], v[120:123]
	v_mfma_f32_16x16x32_bf16 v[112:115], v[128:131], v[192:195], v[112:115]
	v_mfma_f32_16x16x32_bf16 v[96:99], v[108:111], v[200:203], v[96:99]
	v_mfma_f32_16x16x32_bf16 v[92:95], v[128:131], v[200:203], v[92:95]
	v_mfma_f32_16x16x32_bf16 v[80:83], v[108:111], v[208:211], v[80:83]
	v_mfma_f32_16x16x32_bf16 v[76:79], v[128:131], v[208:211], v[76:79]
	s_setprio 0
	s_setprio 1
	v_mfma_f32_16x16x32_bf16 v[132:135], v[156:159], v[180:183], v[132:135]
	v_mfma_f32_16x16x32_bf16 v[124:127], v[172:175], v[180:183], v[124:127]
	v_mfma_f32_16x16x32_bf16 v[104:107], v[156:159], v[188:191], v[104:107]
	v_mfma_f32_16x16x32_bf16 v[100:103], v[172:175], v[188:191], v[100:103]
	v_mfma_f32_16x16x32_bf16 v[88:91], v[156:159], v[196:199], v[88:91]
	v_mfma_f32_16x16x32_bf16 v[84:87], v[172:175], v[196:199], v[84:87]
	v_mfma_f32_16x16x32_bf16 v[72:75], v[156:159], v[204:207], v[72:75]
	v_mfma_f32_16x16x32_bf16 v[68:71], v[172:175], v[204:207], v[68:71]
	v_mfma_f32_16x16x32_bf16 v[132:135], v[168:171], v[184:187], v[132:135]
	v_mfma_f32_16x16x32_bf16 v[124:127], v[176:179], v[184:187], v[124:127]
	v_mfma_f32_16x16x32_bf16 v[104:107], v[168:171], v[192:195], v[104:107]
	v_mfma_f32_16x16x32_bf16 v[100:103], v[176:179], v[192:195], v[100:103]
	v_mfma_f32_16x16x32_bf16 v[88:91], v[168:171], v[200:203], v[88:91]
	v_mfma_f32_16x16x32_bf16 v[84:87], v[176:179], v[200:203], v[84:87]
	v_mfma_f32_16x16x32_bf16 v[72:75], v[168:171], v[208:211], v[72:75]
	v_mfma_f32_16x16x32_bf16 v[68:71], v[176:179], v[208:211], v[68:71]
	s_setprio 0
	s_barrier
	s_add_i32 s26, s66, s68
	v_lshl_add_u64 v[160:161], v[160:161], 0, s[8:9]
	s_mov_b32 m0, s26
	ds_read_b128 v[180:183], v167 offset:49152
	ds_read_b128 v[184:187], v167 offset:50176
	ds_read_b128 v[188:191], v167 offset:51200
	ds_read_b128 v[192:195], v167 offset:52224
	ds_read_b128 v[196:199], v167 offset:53248
	ds_read_b128 v[200:203], v167 offset:54272
	ds_read_b128 v[204:207], v167 offset:55296
	ds_read_b128 v[208:211], v167 offset:56320
	global_load_lds_dwordx4 v[160:161], off
	s_add_i32 m0, s26, 0x2000
	s_add_u32 s26, s30, 0xb0080
	v_lshl_add_u64 v[160:161], v[212:213], 0, s[8:9]
	s_addc_u32 s27, s31, 0
	s_add_i32 s30, s67, s68
	global_load_lds_dwordx4 v[160:161], off
	s_mov_b32 m0, s30
	s_nop 0
	global_load_lds_dwordx4 v144, s[26:27]
	s_add_i32 m0, s30, 0x2000
	s_nop 0
	global_load_lds_dwordx4 v146, s[26:27]
	v_lshl_add_u64 v[160:161], v[214:215], 0, s[8:9]
	s_mov_b32 m0, s47
	s_nop 0
	global_load_lds_dwordx4 v[160:161], off
	v_lshl_add_u64 v[160:161], v[216:217], 0, s[8:9]
	s_mov_b32 m0, s48
	s_nop 0
	global_load_lds_dwordx4 v[160:161], off
	s_waitcnt vmcnt(8)
	s_waitcnt lgkmcnt(0)
	s_barrier
	s_setprio 1
	s_waitcnt lgkmcnt(0)
	v_mfma_f32_16x16x32_bf16 v[60:63], v[64:67], v[180:183], v[60:63]
	v_mfma_f32_16x16x32_bf16 v[56:59], v[116:119], v[180:183], v[56:59]
	v_mfma_f32_16x16x32_bf16 v[44:47], v[64:67], v[188:191], v[44:47]
	v_mfma_f32_16x16x32_bf16 v[40:43], v[116:119], v[188:191], v[40:43]
	v_mfma_f32_16x16x32_bf16 v[28:31], v[64:67], v[196:199], v[28:31]
	v_mfma_f32_16x16x32_bf16 v[24:27], v[116:119], v[196:199], v[24:27]
	v_mfma_f32_16x16x32_bf16 v[12:15], v[64:67], v[204:207], v[12:15]
	v_mfma_f32_16x16x32_bf16 v[8:11], v[116:119], v[204:207], v[8:11]
	v_mfma_f32_16x16x32_bf16 v[60:63], v[108:111], v[184:187], v[60:63]
	v_mfma_f32_16x16x32_bf16 v[56:59], v[128:131], v[184:187], v[56:59]
	v_mfma_f32_16x16x32_bf16 v[44:47], v[108:111], v[192:195], v[44:47]
	v_mfma_f32_16x16x32_bf16 v[40:43], v[128:131], v[192:195], v[40:43]
	v_mfma_f32_16x16x32_bf16 v[28:31], v[108:111], v[200:203], v[28:31]
	v_mfma_f32_16x16x32_bf16 v[24:27], v[128:131], v[200:203], v[24:27]
	v_mfma_f32_16x16x32_bf16 v[12:15], v[108:111], v[208:211], v[12:15]
	v_mfma_f32_16x16x32_bf16 v[8:11], v[128:131], v[208:211], v[8:11]
	s_setprio 0
	s_setprio 1
	v_mfma_f32_16x16x32_bf16 v[52:55], v[156:159], v[180:183], v[52:55]
	v_mfma_f32_16x16x32_bf16 v[48:51], v[172:175], v[180:183], v[48:51]
	v_mfma_f32_16x16x32_bf16 v[36:39], v[156:159], v[188:191], v[36:39]
	v_mfma_f32_16x16x32_bf16 v[32:35], v[172:175], v[188:191], v[32:35]
	v_mfma_f32_16x16x32_bf16 v[20:23], v[156:159], v[196:199], v[20:23]
	v_mfma_f32_16x16x32_bf16 v[16:19], v[172:175], v[196:199], v[16:19]
	v_mfma_f32_16x16x32_bf16 v[4:7], v[156:159], v[204:207], v[4:7]
	v_mfma_f32_16x16x32_bf16 v[0:3], v[172:175], v[204:207], v[0:3]
	v_mfma_f32_16x16x32_bf16 v[52:55], v[168:171], v[184:187], v[52:55]
	v_mfma_f32_16x16x32_bf16 v[48:51], v[176:179], v[184:187], v[48:51]
	v_mfma_f32_16x16x32_bf16 v[36:39], v[168:171], v[192:195], v[36:39]
	v_mfma_f32_16x16x32_bf16 v[32:35], v[176:179], v[192:195], v[32:35]
	v_mfma_f32_16x16x32_bf16 v[20:23], v[168:171], v[200:203], v[20:23]
	v_mfma_f32_16x16x32_bf16 v[16:19], v[176:179], v[200:203], v[16:19]
	v_mfma_f32_16x16x32_bf16 v[4:7], v[168:171], v[208:211], v[4:7]
	v_mfma_f32_16x16x32_bf16 v[0:3], v[176:179], v[208:211], v[0:3]
	s_setprio 0
	s_barrier
	s_add_i32 s65, s65, 2
	s_add_u32 s63, s63, 0x100
	s_addc_u32 s64, s64, 0
	s_cmp_gt_u32 s65, 41
	s_mov_b64 s[26:27], s[28:29]
	s_cbranch_scc0 .LBB0_815
	s_and_b64 vcc, exec, s[10:11]
	s_cbranch_vccz .LBB0_818
	s_barrier
